# one static s_setprio 1 for waves 4..7 at kernel start, per-segment priority toggles in the GEMM loops removed
# speedup vs baseline: 1.0068x; 1.0068x over previous
.LBB0_63:
	v_readfirstlane_b32 s8, v178
	s_cmpk_lt_u32 s8, 0x100
	s_cbranch_scc1 .Lprio_skip
	s_setprio 1

.LBB0_135:
	s_add_i32 s96, s68, 2
	s_add_u32 s69, s28, 0xfff80080
	s_addc_u32 s70, s29, -1
	s_add_i32 s97, 0, 0x10000
	v_add_u32_e32 v154, s97, v143
	ds_read_b128 v[138:141], v154
	ds_read_b128 v[146:149], v154 offset:1024
	ds_read_b128 v[150:153], v154 offset:2048
	ds_read_b128 v[154:157], v154 offset:3072
	s_cmp_eq_u32 s93, s68
	s_cselect_b32 s68, s92, s94
	s_cselect_b32 s71, s3, s70
	s_cselect_b32 s70, s91, s69
	s_cselect_b32 s69, s5, s95
	v_lshl_add_u64 v[166:167], s[28:29], 0, v[134:135]
	s_add_i32 m0, s7, 0xc000
	ds_read_b128 v[158:161], v145
	ds_read_b128 v[162:165], v145 offset:1024
	ds_read_b128 v[194:197], v145 offset:2048
	ds_read_b128 v[198:201], v145 offset:3072
	ds_read_b128 v[202:205], v145 offset:4096
	ds_read_b128 v[206:209], v145 offset:5120
	ds_read_b128 v[210:213], v145 offset:6144
	ds_read_b128 v[214:217], v145 offset:7168
	global_load_lds_dwordx4 v[166:167], off
	v_lshl_add_u64 v[166:167], s[28:29], 0, v[136:137]
	s_add_i32 m0, s7, 0xe000
	s_nop 0
	global_load_lds_dwordx4 v[166:167], off
	s_waitcnt lgkmcnt(8)
	s_barrier
	s_waitcnt lgkmcnt(0)
	s_nop 0
	s_waitcnt lgkmcnt(0)
	v_mfma_f32_16x16x32_bf16 v[124:127], v[138:141], v[158:161], v[124:127]
	v_mfma_f32_16x16x32_bf16 v[120:123], v[150:153], v[158:161], v[120:123]
	v_mfma_f32_16x16x32_bf16 v[116:119], v[138:141], v[194:197], v[116:119]
	v_mfma_f32_16x16x32_bf16 v[108:111], v[150:153], v[194:197], v[108:111]
	v_mfma_f32_16x16x32_bf16 v[100:103], v[138:141], v[202:205], v[100:103]
	v_mfma_f32_16x16x32_bf16 v[92:95], v[150:153], v[202:205], v[92:95]
	v_mfma_f32_16x16x32_bf16 v[84:87], v[138:141], v[210:213], v[84:87]
	v_mfma_f32_16x16x32_bf16 v[76:79], v[150:153], v[210:213], v[76:79]
	v_mfma_f32_16x16x32_bf16 v[124:127], v[146:149], v[162:165], v[124:127]
	v_mfma_f32_16x16x32_bf16 v[120:123], v[154:157], v[162:165], v[120:123]
	v_mfma_f32_16x16x32_bf16 v[116:119], v[146:149], v[198:201], v[116:119]
	v_mfma_f32_16x16x32_bf16 v[108:111], v[154:157], v[198:201], v[108:111]
	v_mfma_f32_16x16x32_bf16 v[100:103], v[146:149], v[206:209], v[100:103]
	v_mfma_f32_16x16x32_bf16 v[92:95], v[154:157], v[206:209], v[92:95]
	v_mfma_f32_16x16x32_bf16 v[84:87], v[146:149], v[214:217], v[84:87]
	v_mfma_f32_16x16x32_bf16 v[76:79], v[154:157], v[214:217], v[76:79]
	s_nop 0
	s_barrier
	s_add_i32 s58, 0, 0x14000
	v_add_u32_e32 v166, s58, v143
	s_add_i32 s97, s97, s78
	ds_read_b128 v[218:221], v166
	ds_read_b128 v[222:225], v166 offset:1024
	ds_read_b128 v[226:229], v166 offset:2048
	ds_read_b128 v[230:233], v166 offset:3072
	v_lshl_add_u64 v[166:167], s[68:69], 0, v[168:169]
	s_mov_b32 m0, s97
	v_lshl_add_u64 v[176:177], s[68:69], 0, v[132:133]
	global_load_lds_dwordx4 v[166:167], off
	s_add_i32 m0, s97, 0x2000
	s_nop 0
	global_load_lds_dwordx4 v[176:177], off
	s_barrier
	s_waitcnt lgkmcnt(0)
	s_nop 0
	s_waitcnt lgkmcnt(0)
	v_mfma_f32_16x16x32_bf16 v[112:115], v[218:221], v[158:161], v[112:115]
	v_mfma_f32_16x16x32_bf16 v[104:107], v[226:229], v[158:161], v[104:107]
	v_mfma_f32_16x16x32_bf16 v[96:99], v[218:221], v[194:197], v[96:99]
	v_mfma_f32_16x16x32_bf16 v[88:91], v[226:229], v[194:197], v[88:91]
	v_mfma_f32_16x16x32_bf16 v[80:83], v[218:221], v[202:205], v[80:83]
	v_mfma_f32_16x16x32_bf16 v[72:75], v[226:229], v[202:205], v[72:75]
	v_mfma_f32_16x16x32_bf16 v[68:71], v[218:221], v[210:213], v[68:71]
	v_mfma_f32_16x16x32_bf16 v[64:67], v[226:229], v[210:213], v[64:67]
	v_mfma_f32_16x16x32_bf16 v[112:115], v[222:225], v[162:165], v[112:115]
	v_mfma_f32_16x16x32_bf16 v[104:107], v[230:233], v[162:165], v[104:107]
	v_mfma_f32_16x16x32_bf16 v[96:99], v[222:225], v[198:201], v[96:99]
	v_mfma_f32_16x16x32_bf16 v[88:91], v[230:233], v[198:201], v[88:91]
	v_mfma_f32_16x16x32_bf16 v[80:83], v[222:225], v[206:209], v[80:83]
	v_mfma_f32_16x16x32_bf16 v[72:75], v[230:233], v[206:209], v[72:75]
	v_mfma_f32_16x16x32_bf16 v[68:71], v[222:225], v[214:217], v[68:71]
	v_mfma_f32_16x16x32_bf16 v[64:67], v[230:233], v[214:217], v[64:67]
	s_nop 0
	s_mov_b32 m0, s7
	v_lshl_add_u64 v[234:235], s[70:71], 0, v[128:129]
	s_barrier
	ds_read_b128 v[158:161], v145 offset:16384
	ds_read_b128 v[162:165], v145 offset:17408
	ds_read_b128 v[194:197], v145 offset:18432
	ds_read_b128 v[198:201], v145 offset:19456
	ds_read_b128 v[202:205], v145 offset:20480
	ds_read_b128 v[206:209], v145 offset:21504
	ds_read_b128 v[210:213], v145 offset:22528
	ds_read_b128 v[214:217], v145 offset:23552
	global_load_lds_dwordx4 v[234:235], off
	v_lshl_add_u64 v[236:237], s[70:71], 0, v[130:131]
	s_mov_b32 m0, s79
	s_nop 0
	global_load_lds_dwordx4 v[236:237], off
	s_barrier
	s_waitcnt lgkmcnt(0)
	s_nop 0
	s_waitcnt lgkmcnt(0)
	v_mfma_f32_16x16x32_bf16 v[60:63], v[138:141], v[158:161], v[60:63]
	v_mfma_f32_16x16x32_bf16 v[56:59], v[150:153], v[158:161], v[56:59]
	v_mfma_f32_16x16x32_bf16 v[52:55], v[138:141], v[194:197], v[52:55]
	v_mfma_f32_16x16x32_bf16 v[44:47], v[150:153], v[194:197], v[44:47]
	v_mfma_f32_16x16x32_bf16 v[36:39], v[138:141], v[202:205], v[36:39]
	v_mfma_f32_16x16x32_bf16 v[28:31], v[150:153], v[202:205], v[28:31]
	v_mfma_f32_16x16x32_bf16 v[20:23], v[138:141], v[210:213], v[20:23]
	v_mfma_f32_16x16x32_bf16 v[12:15], v[150:153], v[210:213], v[12:15]
	v_mfma_f32_16x16x32_bf16 v[60:63], v[146:149], v[162:165], v[60:63]
	v_mfma_f32_16x16x32_bf16 v[56:59], v[154:157], v[162:165], v[56:59]
	v_mfma_f32_16x16x32_bf16 v[52:55], v[146:149], v[198:201], v[52:55]
	v_mfma_f32_16x16x32_bf16 v[44:47], v[154:157], v[198:201], v[44:47]
	v_mfma_f32_16x16x32_bf16 v[36:39], v[146:149], v[206:209], v[36:39]
	v_mfma_f32_16x16x32_bf16 v[28:31], v[154:157], v[206:209], v[28:31]
	v_mfma_f32_16x16x32_bf16 v[20:23], v[146:149], v[214:217], v[20:23]
	v_mfma_f32_16x16x32_bf16 v[12:15], v[154:157], v[214:217], v[12:15]
	s_nop 0
	s_barrier
	s_add_u32 vcc_lo, s68, 0x80000
	s_addc_u32 vcc_hi, s69, 0
	s_add_i32 s58, s58, s78
	v_lshl_add_u64 v[138:139], vcc, 0, v[168:169]
	s_mov_b32 m0, s58
	s_nop 0
	global_load_lds_dwordx4 v[138:139], off
	v_lshl_add_u64 v[138:139], vcc, 0, v[132:133]
	s_add_i32 m0, s58, 0x2000
	s_nop 0
	global_load_lds_dwordx4 v[138:139], off
	s_waitcnt vmcnt(6)
	s_barrier
	s_nop 0
	v_mfma_f32_16x16x32_bf16 v[48:51], v[218:221], v[158:161], v[48:51]
	v_mfma_f32_16x16x32_bf16 v[40:43], v[226:229], v[158:161], v[40:43]
	v_mfma_f32_16x16x32_bf16 v[32:35], v[218:221], v[194:197], v[32:35]
	v_mfma_f32_16x16x32_bf16 v[24:27], v[226:229], v[194:197], v[24:27]
	v_mfma_f32_16x16x32_bf16 v[16:19], v[218:221], v[202:205], v[16:19]
	v_mfma_f32_16x16x32_bf16 v[8:11], v[226:229], v[202:205], v[8:11]
	v_mfma_f32_16x16x32_bf16 v[4:7], v[218:221], v[210:213], v[4:7]
	v_mfma_f32_16x16x32_bf16 v[0:3], v[226:229], v[210:213], v[0:3]
	v_mfma_f32_16x16x32_bf16 v[48:51], v[222:225], v[162:165], v[48:51]
	v_mfma_f32_16x16x32_bf16 v[40:43], v[230:233], v[162:165], v[40:43]
	v_mfma_f32_16x16x32_bf16 v[32:35], v[222:225], v[198:201], v[32:35]
	v_mfma_f32_16x16x32_bf16 v[24:27], v[230:233], v[198:201], v[24:27]
	v_mfma_f32_16x16x32_bf16 v[16:19], v[222:225], v[206:209], v[16:19]
	v_mfma_f32_16x16x32_bf16 v[8:11], v[230:233], v[206:209], v[8:11]
	v_mfma_f32_16x16x32_bf16 v[4:7], v[222:225], v[214:217], v[4:7]
	v_mfma_f32_16x16x32_bf16 v[0:3], v[230:233], v[214:217], v[0:3]
	s_nop 0
	s_add_i32 s58, 0, 0x18000
	v_add_u32_e32 v154, s58, v143
	s_barrier
	ds_read_b128 v[138:141], v154
	ds_read_b128 v[146:149], v154 offset:1024
	ds_read_b128 v[150:153], v154 offset:2048
	ds_read_b128 v[154:157], v154 offset:3072
	s_add_u32 s70, s70, 0x80000
	s_addc_u32 s71, s71, 0
	s_mov_b32 m0, s82
	v_lshl_add_u64 v[218:219], s[70:71], 0, v[128:129]
	ds_read_b128 v[158:161], v145 offset:32768
	ds_read_b128 v[162:165], v145 offset:33792
	ds_read_b128 v[194:197], v145 offset:34816
	ds_read_b128 v[198:201], v145 offset:35840
	ds_read_b128 v[202:205], v145 offset:36864
	ds_read_b128 v[206:209], v145 offset:37888
	ds_read_b128 v[210:213], v145 offset:38912
	ds_read_b128 v[214:217], v145 offset:39936
	global_load_lds_dwordx4 v[218:219], off
	v_lshl_add_u64 v[218:219], s[70:71], 0, v[130:131]
	s_mov_b32 m0, s83
	s_nop 0
	global_load_lds_dwordx4 v[218:219], off
	s_waitcnt lgkmcnt(8)
	s_barrier
	s_waitcnt lgkmcnt(0)
	s_nop 0
	s_waitcnt lgkmcnt(0)
	v_mfma_f32_16x16x32_bf16 v[124:127], v[138:141], v[158:161], v[124:127]
	v_mfma_f32_16x16x32_bf16 v[120:123], v[150:153], v[158:161], v[120:123]
	v_mfma_f32_16x16x32_bf16 v[116:119], v[138:141], v[194:197], v[116:119]
	v_mfma_f32_16x16x32_bf16 v[108:111], v[150:153], v[194:197], v[108:111]
	v_mfma_f32_16x16x32_bf16 v[100:103], v[138:141], v[202:205], v[100:103]
	v_mfma_f32_16x16x32_bf16 v[92:95], v[150:153], v[202:205], v[92:95]
	v_mfma_f32_16x16x32_bf16 v[84:87], v[138:141], v[210:213], v[84:87]
	v_mfma_f32_16x16x32_bf16 v[76:79], v[150:153], v[210:213], v[76:79]
	v_mfma_f32_16x16x32_bf16 v[124:127], v[146:149], v[162:165], v[124:127]
	v_mfma_f32_16x16x32_bf16 v[120:123], v[154:157], v[162:165], v[120:123]
	v_mfma_f32_16x16x32_bf16 v[116:119], v[146:149], v[198:201], v[116:119]
	v_mfma_f32_16x16x32_bf16 v[108:111], v[154:157], v[198:201], v[108:111]
	v_mfma_f32_16x16x32_bf16 v[100:103], v[146:149], v[206:209], v[100:103]
	v_mfma_f32_16x16x32_bf16 v[92:95], v[154:157], v[206:209], v[92:95]
	v_mfma_f32_16x16x32_bf16 v[84:87], v[146:149], v[214:217], v[84:87]
	v_mfma_f32_16x16x32_bf16 v[76:79], v[154:157], v[214:217], v[76:79]
	s_nop 0
	s_barrier
	s_add_i32 s70, 0, 0x1c000
	s_add_i32 s58, s58, s78
	v_add_u32_e32 v193, s70, v143
	v_lshl_add_u64 v[166:167], v[166:167], 0, s[0:1]
	s_mov_b32 m0, s58
	ds_read_b128 v[218:221], v193
	ds_read_b128 v[222:225], v193 offset:1024
	ds_read_b128 v[226:229], v193 offset:2048
	ds_read_b128 v[230:233], v193 offset:3072
	global_load_lds_dwordx4 v[166:167], off
	v_lshl_add_u64 v[166:167], v[176:177], 0, s[0:1]
	s_add_i32 m0, s58, 0x2000
	s_nop 0
	global_load_lds_dwordx4 v[166:167], off
	s_barrier
	s_waitcnt lgkmcnt(0)
	s_nop 0
	s_waitcnt lgkmcnt(0)
	v_mfma_f32_16x16x32_bf16 v[112:115], v[218:221], v[158:161], v[112:115]
	v_mfma_f32_16x16x32_bf16 v[104:107], v[226:229], v[158:161], v[104:107]
	v_mfma_f32_16x16x32_bf16 v[96:99], v[218:221], v[194:197], v[96:99]
	v_mfma_f32_16x16x32_bf16 v[88:91], v[226:229], v[194:197], v[88:91]
	v_mfma_f32_16x16x32_bf16 v[80:83], v[218:221], v[202:205], v[80:83]
	v_mfma_f32_16x16x32_bf16 v[72:75], v[226:229], v[202:205], v[72:75]
	v_mfma_f32_16x16x32_bf16 v[68:71], v[218:221], v[210:213], v[68:71]
	v_mfma_f32_16x16x32_bf16 v[64:67], v[226:229], v[210:213], v[64:67]
	v_mfma_f32_16x16x32_bf16 v[112:115], v[222:225], v[162:165], v[112:115]
	v_mfma_f32_16x16x32_bf16 v[104:107], v[230:233], v[162:165], v[104:107]
	v_mfma_f32_16x16x32_bf16 v[96:99], v[222:225], v[198:201], v[96:99]
	v_mfma_f32_16x16x32_bf16 v[88:91], v[230:233], v[198:201], v[88:91]
	v_mfma_f32_16x16x32_bf16 v[80:83], v[222:225], v[206:209], v[80:83]
	v_mfma_f32_16x16x32_bf16 v[72:75], v[230:233], v[206:209], v[72:75]
	v_mfma_f32_16x16x32_bf16 v[68:71], v[222:225], v[214:217], v[68:71]
	v_mfma_f32_16x16x32_bf16 v[64:67], v[230:233], v[214:217], v[64:67]
	s_nop 0
	s_mov_b32 m0, s85
	v_lshl_add_u64 v[166:167], v[234:235], 0, s[0:1]
	s_barrier
	ds_read_b128 v[158:161], v145 offset:49152
	ds_read_b128 v[162:165], v145 offset:50176
	ds_read_b128 v[194:197], v145 offset:51200
	ds_read_b128 v[198:201], v145 offset:52224
	ds_read_b128 v[202:205], v145 offset:53248
	ds_read_b128 v[206:209], v145 offset:54272
	ds_read_b128 v[210:213], v145 offset:55296
	ds_read_b128 v[214:217], v145 offset:56320
	global_load_lds_dwordx4 v[166:167], off
	v_lshl_add_u64 v[166:167], v[236:237], 0, s[0:1]
	s_mov_b32 m0, s86
	s_nop 0
	global_load_lds_dwordx4 v[166:167], off
	s_barrier
	s_waitcnt lgkmcnt(0)
	s_nop 0
	s_waitcnt lgkmcnt(0)
	v_mfma_f32_16x16x32_bf16 v[60:63], v[138:141], v[158:161], v[60:63]
	v_mfma_f32_16x16x32_bf16 v[56:59], v[150:153], v[158:161], v[56:59]
	v_mfma_f32_16x16x32_bf16 v[52:55], v[138:141], v[194:197], v[52:55]
	v_mfma_f32_16x16x32_bf16 v[44:47], v[150:153], v[194:197], v[44:47]
	v_mfma_f32_16x16x32_bf16 v[36:39], v[138:141], v[202:205], v[36:39]
	v_mfma_f32_16x16x32_bf16 v[28:31], v[150:153], v[202:205], v[28:31]
	v_mfma_f32_16x16x32_bf16 v[20:23], v[138:141], v[210:213], v[20:23]
	v_mfma_f32_16x16x32_bf16 v[12:15], v[150:153], v[210:213], v[12:15]
	v_mfma_f32_16x16x32_bf16 v[60:63], v[146:149], v[162:165], v[60:63]
	v_mfma_f32_16x16x32_bf16 v[56:59], v[154:157], v[162:165], v[56:59]
	v_mfma_f32_16x16x32_bf16 v[52:55], v[146:149], v[198:201], v[52:55]
	v_mfma_f32_16x16x32_bf16 v[44:47], v[154:157], v[198:201], v[44:47]
	v_mfma_f32_16x16x32_bf16 v[36:39], v[146:149], v[206:209], v[36:39]
	v_mfma_f32_16x16x32_bf16 v[28:31], v[154:157], v[206:209], v[28:31]
	v_mfma_f32_16x16x32_bf16 v[20:23], v[146:149], v[214:217], v[20:23]
	v_mfma_f32_16x16x32_bf16 v[12:15], v[154:157], v[214:217], v[12:15]
	s_nop 0
	s_barrier
	s_add_u32 s68, s68, 0x80080
	s_addc_u32 s69, s69, 0
	s_add_i32 s58, s70, s78
	v_lshl_add_u64 v[138:139], s[68:69], 0, v[168:169]
	s_mov_b32 m0, s58
	s_nop 0
	global_load_lds_dwordx4 v[138:139], off
	v_lshl_add_u64 v[138:139], s[68:69], 0, v[132:133]
	s_add_i32 m0, s58, 0x2000
	s_nop 0
	global_load_lds_dwordx4 v[138:139], off
	s_waitcnt vmcnt(6)
	s_barrier
	s_nop 0
	v_mfma_f32_16x16x32_bf16 v[48:51], v[218:221], v[158:161], v[48:51]
	v_mfma_f32_16x16x32_bf16 v[40:43], v[226:229], v[158:161], v[40:43]
	v_mfma_f32_16x16x32_bf16 v[32:35], v[218:221], v[194:197], v[32:35]
	v_mfma_f32_16x16x32_bf16 v[24:27], v[226:229], v[194:197], v[24:27]
	v_mfma_f32_16x16x32_bf16 v[16:19], v[218:221], v[202:205], v[16:19]
	v_mfma_f32_16x16x32_bf16 v[8:11], v[226:229], v[202:205], v[8:11]
	v_mfma_f32_16x16x32_bf16 v[4:7], v[218:221], v[210:213], v[4:7]
	v_mfma_f32_16x16x32_bf16 v[0:3], v[226:229], v[210:213], v[0:3]
	v_mfma_f32_16x16x32_bf16 v[48:51], v[222:225], v[162:165], v[48:51]
	v_mfma_f32_16x16x32_bf16 v[40:43], v[230:233], v[162:165], v[40:43]
	v_mfma_f32_16x16x32_bf16 v[32:35], v[222:225], v[198:201], v[32:35]
	v_mfma_f32_16x16x32_bf16 v[24:27], v[230:233], v[198:201], v[24:27]
	v_mfma_f32_16x16x32_bf16 v[16:19], v[222:225], v[206:209], v[16:19]
	v_mfma_f32_16x16x32_bf16 v[8:11], v[230:233], v[206:209], v[8:11]
	v_mfma_f32_16x16x32_bf16 v[4:7], v[222:225], v[214:217], v[4:7]
	v_mfma_f32_16x16x32_bf16 v[0:3], v[230:233], v[214:217], v[0:3]
	s_nop 0
	s_add_u32 s28, s28, 0x100
	s_addc_u32 s29, s29, 0
	s_add_u32 s94, s94, 0x100
	s_addc_u32 s95, s95, 0
	s_cmp_ge_u32 s96, s90
	s_mov_b32 s68, s96
	s_barrier
	s_cbranch_scc0 .LBB0_135
	v_lshl_or_b32 v140, s89, 8, v144
	v_lshl_add_u32 v148, s6, 8, v142
	v_ashrrev_i32_e32 v141, 31, v140
	v_mov_b64_e32 v[138:139], s[80:81]
	v_mad_i64_i32 v[146:147], s[28:29], v148, s54, v[138:139]
	v_lshlrev_b64 v[140:141], 1, v[140:141]
	v_lshl_add_u64 v[146:147], v[146:147], 0, v[140:141]
	v_cvt_pk_bf16_f32 v124, v124, v125
	v_cvt_pk_bf16_f32 v125, v126, v127
	v_cvt_pk_bf16_f32 v126, v120, v121
	v_cvt_pk_bf16_f32 v127, v122, v123
	global_store_dwordx4 v[146:147], v[124:127], off
	v_cvt_pk_bf16_f32 v112, v112, v113
	v_cvt_pk_bf16_f32 v113, v114, v115
	v_cvt_pk_bf16_f32 v114, v104, v105
	v_or_b32_e32 v104, 16, v148
	v_mad_i64_i32 v[104:105], s[28:29], v104, s54, v[138:139]
	v_cvt_pk_bf16_f32 v115, v106, v107
	global_store_dwordx4 v[146:147], v[112:115], off offset:256
	v_readlane_b32 s94, v239, 44
	s_and_b64 vcc, exec, s[12:13]
	v_lshl_add_u64 v[112:113], v[104:105], 0, v[140:141]
	v_cvt_pk_bf16_f32 v104, v116, v117
	v_cvt_pk_bf16_f32 v105, v118, v119
	v_cvt_pk_bf16_f32 v106, v108, v109
	v_cvt_pk_bf16_f32 v107, v110, v111
	global_store_dwordx4 v[112:113], v[104:107], off
	v_cvt_pk_bf16_f32 v96, v96, v97
	v_cvt_pk_bf16_f32 v97, v98, v99
	v_cvt_pk_bf16_f32 v98, v88, v89
	v_or_b32_e32 v88, 32, v148
	v_mad_i64_i32 v[88:89], s[28:29], v88, s54, v[138:139]
	v_cvt_pk_bf16_f32 v99, v90, v91
	global_store_dwordx4 v[112:113], v[96:99], off offset:256
	s_mov_b32 s89, s4
	s_mov_b32 s6, s2
	v_lshl_add_u64 v[96:97], v[88:89], 0, v[140:141]
	v_cvt_pk_bf16_f32 v88, v100, v101
	v_cvt_pk_bf16_f32 v89, v102, v103
	v_cvt_pk_bf16_f32 v90, v92, v93
	v_cvt_pk_bf16_f32 v91, v94, v95
	global_store_dwordx4 v[96:97], v[88:91], off
	v_cvt_pk_bf16_f32 v80, v80, v81
	v_cvt_pk_bf16_f32 v81, v82, v83
	v_cvt_pk_bf16_f32 v82, v72, v73
	v_or_b32_e32 v72, 48, v148
	v_mad_i64_i32 v[72:73], s[28:29], v72, s54, v[138:139]
	v_cvt_pk_bf16_f32 v83, v74, v75
	global_store_dwordx4 v[96:97], v[80:83], off offset:256
	s_mov_b32 s90, s88
	s_mov_b64 s[68:69], s[14:15]
	v_lshl_add_u64 v[80:81], v[72:73], 0, v[140:141]
	v_cvt_pk_bf16_f32 v72, v84, v85
	v_cvt_pk_bf16_f32 v73, v86, v87
	v_cvt_pk_bf16_f32 v74, v76, v77
	v_cvt_pk_bf16_f32 v75, v78, v79
	global_store_dwordx4 v[80:81], v[72:75], off
	v_cvt_pk_bf16_f32 v68, v68, v69
	v_cvt_pk_bf16_f32 v69, v70, v71
	v_cvt_pk_bf16_f32 v70, v64, v65
	v_add_u32_e32 v64, 0x80, v148
	v_mad_i64_i32 v[64:65], s[28:29], v64, s54, v[138:139]
	v_lshl_add_u64 v[64:65], v[64:65], 0, v[140:141]
	v_cvt_pk_bf16_f32 v71, v66, v67
	global_store_dwordx4 v[80:81], v[68:71], off offset:256
	v_cvt_pk_bf16_f32 v60, v60, v61
	v_cvt_pk_bf16_f32 v61, v62, v63
	v_cvt_pk_bf16_f32 v62, v56, v57
	v_cvt_pk_bf16_f32 v63, v58, v59
	global_store_dwordx4 v[64:65], v[60:63], off
	v_cvt_pk_bf16_f32 v48, v48, v49
	v_cvt_pk_bf16_f32 v49, v50, v51
	v_cvt_pk_bf16_f32 v50, v40, v41
	v_add_u32_e32 v40, 0x90, v148
	v_mad_i64_i32 v[40:41], s[28:29], v40, s54, v[138:139]
	v_cvt_pk_bf16_f32 v51, v42, v43
	global_store_dwordx4 v[64:65], v[48:51], off offset:256
	v_readlane_b32 s95, v239, 45
	s_nop 0
	v_lshl_add_u64 v[48:49], v[40:41], 0, v[140:141]
	v_cvt_pk_bf16_f32 v40, v52, v53
	v_cvt_pk_bf16_f32 v41, v54, v55
	v_cvt_pk_bf16_f32 v42, v44, v45
	v_cvt_pk_bf16_f32 v43, v46, v47
	global_store_dwordx4 v[48:49], v[40:43], off
	v_cvt_pk_bf16_f32 v32, v32, v33
	v_cvt_pk_bf16_f32 v33, v34, v35
	v_cvt_pk_bf16_f32 v34, v24, v25
	v_add_u32_e32 v24, 0xa0, v148
	v_mad_i64_i32 v[24:25], s[28:29], v24, s54, v[138:139]
	v_cvt_pk_bf16_f32 v35, v26, v27
	global_store_dwordx4 v[48:49], v[32:35], off offset:256
	s_nop 1
	v_lshl_add_u64 v[32:33], v[24:25], 0, v[140:141]
	v_cvt_pk_bf16_f32 v24, v36, v37
	v_cvt_pk_bf16_f32 v25, v38, v39
	v_cvt_pk_bf16_f32 v26, v28, v29
	v_cvt_pk_bf16_f32 v27, v30, v31
	global_store_dwordx4 v[32:33], v[24:27], off
	v_cvt_pk_bf16_f32 v16, v16, v17
	v_cvt_pk_bf16_f32 v17, v18, v19
	v_cvt_pk_bf16_f32 v18, v8, v9
	v_add_u32_e32 v8, 0xb0, v148
	v_mad_i64_i32 v[8:9], s[28:29], v8, s54, v[138:139]
	v_cvt_pk_bf16_f32 v19, v10, v11
	global_store_dwordx4 v[32:33], v[16:19], off offset:256
	s_mov_b64 s[28:29], s[8:9]
	s_nop 0
	v_lshl_add_u64 v[16:17], v[8:9], 0, v[140:141]
	v_cvt_pk_bf16_f32 v8, v20, v21
	v_cvt_pk_bf16_f32 v9, v22, v23
	v_cvt_pk_bf16_f32 v10, v12, v13
	v_cvt_pk_bf16_f32 v11, v14, v15
	global_store_dwordx4 v[16:17], v[8:11], off
	v_cvt_pk_bf16_f32 v4, v4, v5
	v_cvt_pk_bf16_f32 v5, v6, v7
	v_cvt_pk_bf16_f32 v6, v0, v1
	v_cvt_pk_bf16_f32 v7, v2, v3
	global_store_dwordx4 v[16:17], v[4:7], off offset:256
	s_cbranch_vccz .LBB0_125
	s_waitcnt vmcnt(0)
	s_cmpk_gt_u32 s36, 0xff
	s_cbranch_scc1 .LBB0_139
	s_barrier

.LBB0_1004:
	s_add_i32 s97, s68, 2
	s_add_u32 s69, s28, 0xfff80080
	s_addc_u32 s70, s29, -1
	s_add_i32 vcc_lo, 0, 0x10000
	v_add_u32_e32 v138, vcc_lo, v141
	ds_read_b128 v[144:147], v138
	ds_read_b128 v[148:151], v138 offset:1024
	ds_read_b128 v[152:155], v138 offset:2048
	ds_read_b128 v[156:159], v138 offset:3072
	s_cmp_eq_u32 s94, s68
	s_cselect_b32 s68, s93, s95
	s_cselect_b32 s71, s5, s70
	s_cselect_b32 s70, s92, s69
	s_cselect_b32 s69, s7, s96
	v_lshl_add_u64 v[138:139], s[28:29], 0, v[134:135]
	s_add_i32 m0, s3, 0xc000
	ds_read_b128 v[160:163], v143
	ds_read_b128 v[164:167], v143 offset:1024
	ds_read_b128 v[194:197], v143 offset:2048
	ds_read_b128 v[198:201], v143 offset:3072
	ds_read_b128 v[202:205], v143 offset:4096
	ds_read_b128 v[206:209], v143 offset:5120
	ds_read_b128 v[210:213], v143 offset:6144
	ds_read_b128 v[214:217], v143 offset:7168
	global_load_lds_dwordx4 v[138:139], off
	v_lshl_add_u64 v[138:139], s[28:29], 0, v[136:137]
	s_add_i32 m0, s3, 0xe000
	s_nop 0
	global_load_lds_dwordx4 v[138:139], off
	s_waitcnt lgkmcnt(8)
	s_barrier
	s_waitcnt lgkmcnt(0)
	s_nop 0
	s_waitcnt lgkmcnt(0)
	v_mfma_f32_16x16x32_bf16 v[124:127], v[144:147], v[160:163], v[124:127]
	v_mfma_f32_16x16x32_bf16 v[120:123], v[152:155], v[160:163], v[120:123]
	v_mfma_f32_16x16x32_bf16 v[116:119], v[144:147], v[194:197], v[116:119]
	v_mfma_f32_16x16x32_bf16 v[108:111], v[152:155], v[194:197], v[108:111]
	v_mfma_f32_16x16x32_bf16 v[100:103], v[144:147], v[202:205], v[100:103]
	v_mfma_f32_16x16x32_bf16 v[92:95], v[152:155], v[202:205], v[92:95]
	v_mfma_f32_16x16x32_bf16 v[80:83], v[144:147], v[210:213], v[80:83]
	v_mfma_f32_16x16x32_bf16 v[72:75], v[152:155], v[210:213], v[72:75]
	v_mfma_f32_16x16x32_bf16 v[124:127], v[148:151], v[164:167], v[124:127]
	v_mfma_f32_16x16x32_bf16 v[120:123], v[156:159], v[164:167], v[120:123]
	v_mfma_f32_16x16x32_bf16 v[116:119], v[148:151], v[198:201], v[116:119]
	v_mfma_f32_16x16x32_bf16 v[108:111], v[156:159], v[198:201], v[108:111]
	v_mfma_f32_16x16x32_bf16 v[100:103], v[148:151], v[206:209], v[100:103]
	v_mfma_f32_16x16x32_bf16 v[92:95], v[156:159], v[206:209], v[92:95]
	v_mfma_f32_16x16x32_bf16 v[80:83], v[148:151], v[214:217], v[80:83]
	v_mfma_f32_16x16x32_bf16 v[72:75], v[156:159], v[214:217], v[72:75]
	s_nop 0
	s_barrier
	s_add_i32 s73, 0, 0x14000
	v_add_u32_e32 v138, s73, v141
	s_add_i32 vcc_lo, vcc_lo, s78
	ds_read_b128 v[218:221], v138
	ds_read_b128 v[222:225], v138 offset:1024
	ds_read_b128 v[226:229], v138 offset:2048
	ds_read_b128 v[230:233], v138 offset:3072
	v_lshl_add_u64 v[138:139], s[68:69], 0, v[168:169]
	s_mov_b32 m0, vcc_lo
	v_lshl_add_u64 v[176:177], s[68:69], 0, v[128:129]
	global_load_lds_dwordx4 v[138:139], off
	s_add_i32 m0, vcc_lo, 0x2000
	s_nop 0
	global_load_lds_dwordx4 v[176:177], off
	s_barrier
	s_waitcnt lgkmcnt(0)
	s_nop 0
	s_waitcnt lgkmcnt(0)
	v_mfma_f32_16x16x32_bf16 v[112:115], v[218:221], v[160:163], v[112:115]
	v_mfma_f32_16x16x32_bf16 v[104:107], v[226:229], v[160:163], v[104:107]
	v_mfma_f32_16x16x32_bf16 v[96:99], v[218:221], v[194:197], v[96:99]
	v_mfma_f32_16x16x32_bf16 v[88:91], v[226:229], v[194:197], v[88:91]
	v_mfma_f32_16x16x32_bf16 v[84:87], v[218:221], v[202:205], v[84:87]
	v_mfma_f32_16x16x32_bf16 v[76:79], v[226:229], v[202:205], v[76:79]
	v_mfma_f32_16x16x32_bf16 v[68:71], v[218:221], v[210:213], v[68:71]
	v_mfma_f32_16x16x32_bf16 v[64:67], v[226:229], v[210:213], v[64:67]
	v_mfma_f32_16x16x32_bf16 v[112:115], v[222:225], v[164:167], v[112:115]
	v_mfma_f32_16x16x32_bf16 v[104:107], v[230:233], v[164:167], v[104:107]
	v_mfma_f32_16x16x32_bf16 v[96:99], v[222:225], v[198:201], v[96:99]
	v_mfma_f32_16x16x32_bf16 v[88:91], v[230:233], v[198:201], v[88:91]
	v_mfma_f32_16x16x32_bf16 v[84:87], v[222:225], v[206:209], v[84:87]
	v_mfma_f32_16x16x32_bf16 v[76:79], v[230:233], v[206:209], v[76:79]
	v_mfma_f32_16x16x32_bf16 v[68:71], v[222:225], v[214:217], v[68:71]
	v_mfma_f32_16x16x32_bf16 v[64:67], v[230:233], v[214:217], v[64:67]
	s_nop 0
	s_mov_b32 m0, s3
	v_lshl_add_u64 v[234:235], s[70:71], 0, v[132:133]
	s_barrier
	ds_read_b128 v[160:163], v143 offset:16384
	ds_read_b128 v[164:167], v143 offset:17408
	ds_read_b128 v[194:197], v143 offset:18432
	ds_read_b128 v[198:201], v143 offset:19456
	ds_read_b128 v[202:205], v143 offset:20480
	ds_read_b128 v[206:209], v143 offset:21504
	ds_read_b128 v[210:213], v143 offset:22528
	ds_read_b128 v[214:217], v143 offset:23552
	global_load_lds_dwordx4 v[234:235], off
	v_lshl_add_u64 v[236:237], s[70:71], 0, v[130:131]
	s_mov_b32 m0, s82
	s_nop 0
	global_load_lds_dwordx4 v[236:237], off
	s_barrier
	s_waitcnt lgkmcnt(0)
	s_nop 0
	s_waitcnt lgkmcnt(0)
	v_mfma_f32_16x16x32_bf16 v[60:63], v[144:147], v[160:163], v[60:63]
	v_mfma_f32_16x16x32_bf16 v[56:59], v[152:155], v[160:163], v[56:59]
	v_mfma_f32_16x16x32_bf16 v[52:55], v[144:147], v[194:197], v[52:55]
	v_mfma_f32_16x16x32_bf16 v[44:47], v[152:155], v[194:197], v[44:47]
	v_mfma_f32_16x16x32_bf16 v[36:39], v[144:147], v[202:205], v[36:39]
	v_mfma_f32_16x16x32_bf16 v[28:31], v[152:155], v[202:205], v[28:31]
	v_mfma_f32_16x16x32_bf16 v[20:23], v[144:147], v[210:213], v[20:23]
	v_mfma_f32_16x16x32_bf16 v[12:15], v[152:155], v[210:213], v[12:15]
	v_mfma_f32_16x16x32_bf16 v[60:63], v[148:151], v[164:167], v[60:63]
	v_mfma_f32_16x16x32_bf16 v[56:59], v[156:159], v[164:167], v[56:59]
	v_mfma_f32_16x16x32_bf16 v[52:55], v[148:151], v[198:201], v[52:55]
	v_mfma_f32_16x16x32_bf16 v[44:47], v[156:159], v[198:201], v[44:47]
	v_mfma_f32_16x16x32_bf16 v[36:39], v[148:151], v[206:209], v[36:39]
	v_mfma_f32_16x16x32_bf16 v[28:31], v[156:159], v[206:209], v[28:31]
	v_mfma_f32_16x16x32_bf16 v[20:23], v[148:151], v[214:217], v[20:23]
	v_mfma_f32_16x16x32_bf16 v[12:15], v[156:159], v[214:217], v[12:15]
	s_nop 0
	s_barrier
	s_add_u32 vcc_lo, s68, 0x80000
	s_addc_u32 vcc_hi, s69, 0
	s_add_i32 s73, s73, s78
	v_lshl_add_u64 v[144:145], vcc, 0, v[168:169]
	s_mov_b32 m0, s73
	s_nop 0
	global_load_lds_dwordx4 v[144:145], off
	v_lshl_add_u64 v[144:145], vcc, 0, v[128:129]
	s_add_i32 m0, s73, 0x2000
	s_nop 0
	global_load_lds_dwordx4 v[144:145], off
	s_waitcnt vmcnt(6)
	s_barrier
	s_nop 0
	v_mfma_f32_16x16x32_bf16 v[48:51], v[218:221], v[160:163], v[48:51]
	v_mfma_f32_16x16x32_bf16 v[40:43], v[226:229], v[160:163], v[40:43]
	v_mfma_f32_16x16x32_bf16 v[32:35], v[218:221], v[194:197], v[32:35]
	v_mfma_f32_16x16x32_bf16 v[24:27], v[226:229], v[194:197], v[24:27]
	v_mfma_f32_16x16x32_bf16 v[16:19], v[218:221], v[202:205], v[16:19]
	v_mfma_f32_16x16x32_bf16 v[8:11], v[226:229], v[202:205], v[8:11]
	v_mfma_f32_16x16x32_bf16 v[4:7], v[218:221], v[210:213], v[4:7]
	v_mfma_f32_16x16x32_bf16 v[0:3], v[226:229], v[210:213], v[0:3]
	v_mfma_f32_16x16x32_bf16 v[48:51], v[222:225], v[164:167], v[48:51]
	v_mfma_f32_16x16x32_bf16 v[40:43], v[230:233], v[164:167], v[40:43]
	v_mfma_f32_16x16x32_bf16 v[32:35], v[222:225], v[198:201], v[32:35]
	v_mfma_f32_16x16x32_bf16 v[24:27], v[230:233], v[198:201], v[24:27]
	v_mfma_f32_16x16x32_bf16 v[16:19], v[222:225], v[206:209], v[16:19]
	v_mfma_f32_16x16x32_bf16 v[8:11], v[230:233], v[206:209], v[8:11]
	v_mfma_f32_16x16x32_bf16 v[4:7], v[222:225], v[214:217], v[4:7]
	v_mfma_f32_16x16x32_bf16 v[0:3], v[230:233], v[214:217], v[0:3]
	s_nop 0
	s_add_i32 s73, 0, 0x18000
	v_add_u32_e32 v156, s73, v141
	s_barrier
	ds_read_b128 v[144:147], v156
	ds_read_b128 v[148:151], v156 offset:1024
	ds_read_b128 v[152:155], v156 offset:2048
	ds_read_b128 v[156:159], v156 offset:3072
	s_add_u32 s70, s70, 0x80000
	s_addc_u32 s71, s71, 0
	s_mov_b32 m0, s83
	v_lshl_add_u64 v[218:219], s[70:71], 0, v[132:133]
	ds_read_b128 v[160:163], v143 offset:32768
	ds_read_b128 v[164:167], v143 offset:33792
	ds_read_b128 v[194:197], v143 offset:34816
	ds_read_b128 v[198:201], v143 offset:35840
	ds_read_b128 v[202:205], v143 offset:36864
	ds_read_b128 v[206:209], v143 offset:37888
	ds_read_b128 v[210:213], v143 offset:38912
	ds_read_b128 v[214:217], v143 offset:39936
	global_load_lds_dwordx4 v[218:219], off
	v_lshl_add_u64 v[218:219], s[70:71], 0, v[130:131]
	s_mov_b32 m0, s84
	s_nop 0
	global_load_lds_dwordx4 v[218:219], off
	s_waitcnt lgkmcnt(8)
	s_barrier
	s_waitcnt lgkmcnt(0)
	s_nop 0
	s_waitcnt lgkmcnt(0)
	v_mfma_f32_16x16x32_bf16 v[124:127], v[144:147], v[160:163], v[124:127]
	v_mfma_f32_16x16x32_bf16 v[120:123], v[152:155], v[160:163], v[120:123]
	v_mfma_f32_16x16x32_bf16 v[116:119], v[144:147], v[194:197], v[116:119]
	v_mfma_f32_16x16x32_bf16 v[108:111], v[152:155], v[194:197], v[108:111]
	v_mfma_f32_16x16x32_bf16 v[100:103], v[144:147], v[202:205], v[100:103]
	v_mfma_f32_16x16x32_bf16 v[92:95], v[152:155], v[202:205], v[92:95]
	v_mfma_f32_16x16x32_bf16 v[80:83], v[144:147], v[210:213], v[80:83]
	v_mfma_f32_16x16x32_bf16 v[72:75], v[152:155], v[210:213], v[72:75]
	v_mfma_f32_16x16x32_bf16 v[124:127], v[148:151], v[164:167], v[124:127]
	v_mfma_f32_16x16x32_bf16 v[120:123], v[156:159], v[164:167], v[120:123]
	v_mfma_f32_16x16x32_bf16 v[116:119], v[148:151], v[198:201], v[116:119]
	v_mfma_f32_16x16x32_bf16 v[108:111], v[156:159], v[198:201], v[108:111]
	v_mfma_f32_16x16x32_bf16 v[100:103], v[148:151], v[206:209], v[100:103]
	v_mfma_f32_16x16x32_bf16 v[92:95], v[156:159], v[206:209], v[92:95]
	v_mfma_f32_16x16x32_bf16 v[80:83], v[148:151], v[214:217], v[80:83]
	v_mfma_f32_16x16x32_bf16 v[72:75], v[156:159], v[214:217], v[72:75]
	s_nop 0
	s_barrier
	s_add_i32 s70, 0, 0x1c000
	s_add_i32 s71, s73, s78
	v_add_u32_e32 v193, s70, v141
	v_lshl_add_u64 v[138:139], v[138:139], 0, s[0:1]
	s_mov_b32 m0, s71
	ds_read_b128 v[218:221], v193
	ds_read_b128 v[222:225], v193 offset:1024
	ds_read_b128 v[226:229], v193 offset:2048
	ds_read_b128 v[230:233], v193 offset:3072
	global_load_lds_dwordx4 v[138:139], off
	v_lshl_add_u64 v[138:139], v[176:177], 0, s[0:1]
	s_add_i32 m0, s71, 0x2000
	s_nop 0
	global_load_lds_dwordx4 v[138:139], off
	s_barrier
	s_waitcnt lgkmcnt(0)
	s_nop 0
	s_waitcnt lgkmcnt(0)
	v_mfma_f32_16x16x32_bf16 v[112:115], v[218:221], v[160:163], v[112:115]
	v_mfma_f32_16x16x32_bf16 v[104:107], v[226:229], v[160:163], v[104:107]
	v_mfma_f32_16x16x32_bf16 v[96:99], v[218:221], v[194:197], v[96:99]
	v_mfma_f32_16x16x32_bf16 v[88:91], v[226:229], v[194:197], v[88:91]
	v_mfma_f32_16x16x32_bf16 v[84:87], v[218:221], v[202:205], v[84:87]
	v_mfma_f32_16x16x32_bf16 v[76:79], v[226:229], v[202:205], v[76:79]
	v_mfma_f32_16x16x32_bf16 v[68:71], v[218:221], v[210:213], v[68:71]
	v_mfma_f32_16x16x32_bf16 v[64:67], v[226:229], v[210:213], v[64:67]
	v_mfma_f32_16x16x32_bf16 v[112:115], v[222:225], v[164:167], v[112:115]
	v_mfma_f32_16x16x32_bf16 v[104:107], v[230:233], v[164:167], v[104:107]
	v_mfma_f32_16x16x32_bf16 v[96:99], v[222:225], v[198:201], v[96:99]
	v_mfma_f32_16x16x32_bf16 v[88:91], v[230:233], v[198:201], v[88:91]
	v_mfma_f32_16x16x32_bf16 v[84:87], v[222:225], v[206:209], v[84:87]
	v_mfma_f32_16x16x32_bf16 v[76:79], v[230:233], v[206:209], v[76:79]
	v_mfma_f32_16x16x32_bf16 v[68:71], v[222:225], v[214:217], v[68:71]
	v_mfma_f32_16x16x32_bf16 v[64:67], v[230:233], v[214:217], v[64:67]
	s_nop 0
	s_mov_b32 m0, s86
	v_lshl_add_u64 v[138:139], v[234:235], 0, s[0:1]
	s_barrier
	ds_read_b128 v[160:163], v143 offset:49152
	ds_read_b128 v[164:167], v143 offset:50176
	ds_read_b128 v[194:197], v143 offset:51200
	ds_read_b128 v[198:201], v143 offset:52224
	ds_read_b128 v[202:205], v143 offset:53248
	ds_read_b128 v[206:209], v143 offset:54272
	ds_read_b128 v[210:213], v143 offset:55296
	ds_read_b128 v[214:217], v143 offset:56320
	global_load_lds_dwordx4 v[138:139], off
	v_lshl_add_u64 v[138:139], v[236:237], 0, s[0:1]
	s_mov_b32 m0, s87
	s_nop 0
	global_load_lds_dwordx4 v[138:139], off
	s_barrier
	s_waitcnt lgkmcnt(0)
	s_nop 0
	s_waitcnt lgkmcnt(0)
	v_mfma_f32_16x16x32_bf16 v[60:63], v[144:147], v[160:163], v[60:63]
	v_mfma_f32_16x16x32_bf16 v[56:59], v[152:155], v[160:163], v[56:59]
	v_mfma_f32_16x16x32_bf16 v[52:55], v[144:147], v[194:197], v[52:55]
	v_mfma_f32_16x16x32_bf16 v[44:47], v[152:155], v[194:197], v[44:47]
	v_mfma_f32_16x16x32_bf16 v[36:39], v[144:147], v[202:205], v[36:39]
	v_mfma_f32_16x16x32_bf16 v[28:31], v[152:155], v[202:205], v[28:31]
	v_mfma_f32_16x16x32_bf16 v[20:23], v[144:147], v[210:213], v[20:23]
	v_mfma_f32_16x16x32_bf16 v[12:15], v[152:155], v[210:213], v[12:15]
	v_mfma_f32_16x16x32_bf16 v[60:63], v[148:151], v[164:167], v[60:63]
	v_mfma_f32_16x16x32_bf16 v[56:59], v[156:159], v[164:167], v[56:59]
	v_mfma_f32_16x16x32_bf16 v[52:55], v[148:151], v[198:201], v[52:55]
	v_mfma_f32_16x16x32_bf16 v[44:47], v[156:159], v[198:201], v[44:47]
	v_mfma_f32_16x16x32_bf16 v[36:39], v[148:151], v[206:209], v[36:39]
	v_mfma_f32_16x16x32_bf16 v[28:31], v[156:159], v[206:209], v[28:31]
	v_mfma_f32_16x16x32_bf16 v[20:23], v[148:151], v[214:217], v[20:23]
	v_mfma_f32_16x16x32_bf16 v[12:15], v[156:159], v[214:217], v[12:15]
	s_nop 0
	s_barrier
	s_add_u32 s68, s68, 0x80080
	s_addc_u32 s69, s69, 0
	s_add_i32 s70, s70, s78
	v_lshl_add_u64 v[138:139], s[68:69], 0, v[168:169]
	s_mov_b32 m0, s70
	s_nop 0
	global_load_lds_dwordx4 v[138:139], off
	v_lshl_add_u64 v[138:139], s[68:69], 0, v[128:129]
	s_add_i32 m0, s70, 0x2000
	s_nop 0
	global_load_lds_dwordx4 v[138:139], off
	s_waitcnt vmcnt(6)
	s_barrier
	s_nop 0
	v_mfma_f32_16x16x32_bf16 v[48:51], v[218:221], v[160:163], v[48:51]
	v_mfma_f32_16x16x32_bf16 v[40:43], v[226:229], v[160:163], v[40:43]
	v_mfma_f32_16x16x32_bf16 v[32:35], v[218:221], v[194:197], v[32:35]
	v_mfma_f32_16x16x32_bf16 v[24:27], v[226:229], v[194:197], v[24:27]
	v_mfma_f32_16x16x32_bf16 v[16:19], v[218:221], v[202:205], v[16:19]
	v_mfma_f32_16x16x32_bf16 v[8:11], v[226:229], v[202:205], v[8:11]
	v_mfma_f32_16x16x32_bf16 v[4:7], v[218:221], v[210:213], v[4:7]
	v_mfma_f32_16x16x32_bf16 v[0:3], v[226:229], v[210:213], v[0:3]
	v_mfma_f32_16x16x32_bf16 v[48:51], v[222:225], v[164:167], v[48:51]
	v_mfma_f32_16x16x32_bf16 v[40:43], v[230:233], v[164:167], v[40:43]
	v_mfma_f32_16x16x32_bf16 v[32:35], v[222:225], v[198:201], v[32:35]
	v_mfma_f32_16x16x32_bf16 v[24:27], v[230:233], v[198:201], v[24:27]
	v_mfma_f32_16x16x32_bf16 v[16:19], v[222:225], v[206:209], v[16:19]
	v_mfma_f32_16x16x32_bf16 v[8:11], v[230:233], v[206:209], v[8:11]
	v_mfma_f32_16x16x32_bf16 v[4:7], v[222:225], v[214:217], v[4:7]
	v_mfma_f32_16x16x32_bf16 v[0:3], v[230:233], v[214:217], v[0:3]
	s_nop 0
	s_add_u32 s28, s28, 0x100
	s_addc_u32 s29, s29, 0
	s_add_u32 s95, s95, 0x100
	s_addc_u32 s96, s96, 0
	s_cmp_ge_u32 s97, s91
	s_mov_b32 s68, s97
	s_barrier
	s_cbranch_scc0 .LBB0_1004
	v_lshl_add_u32 v144, s2, 8, v140
	v_lshl_or_b32 v138, s90, 8, v142
	v_ashrrev_i32_e32 v145, 31, v144
	v_readlane_b32 s28, v240, 62
	v_ashrrev_i32_e32 v139, 31, v138
	v_lshlrev_b64 v[146:147], 12, v[144:145]
	v_readlane_b32 s29, v240, 63
	v_lshlrev_b64 v[148:149], 1, v[138:139]
	v_cvt_pk_bf16_f32 v124, v124, v125
	v_cvt_pk_bf16_f32 v125, v126, v127
	v_cvt_pk_bf16_f32 v126, v120, v121
	v_cvt_pk_bf16_f32 v127, v122, v123
	s_nop 0
	v_lshl_add_u64 v[146:147], s[28:29], 0, v[146:147]
	v_lshl_add_u64 v[138:139], v[146:147], 0, v[148:149]
	global_store_dwordx4 v[138:139], v[124:127], off
	v_cvt_pk_bf16_f32 v112, v112, v113
	v_cvt_pk_bf16_f32 v113, v114, v115
	v_cvt_pk_bf16_f32 v114, v104, v105
	v_or_b32_e32 v104, 16, v144
	v_ashrrev_i32_e32 v105, 31, v104
	v_lshlrev_b64 v[104:105], 12, v[104:105]
	v_lshl_add_u64 v[104:105], s[28:29], 0, v[104:105]
	v_cvt_pk_bf16_f32 v115, v106, v107
	global_store_dwordx4 v[138:139], v[112:115], off offset:256
	s_mov_b32 s2, 0x80000
	v_readlane_b32 s92, v239, 42
	v_lshl_add_u64 v[112:113], v[104:105], 0, v[148:149]
	v_cvt_pk_bf16_f32 v104, v116, v117
	v_cvt_pk_bf16_f32 v105, v118, v119
	v_cvt_pk_bf16_f32 v106, v108, v109
	v_cvt_pk_bf16_f32 v107, v110, v111
	global_store_dwordx4 v[112:113], v[104:107], off
	v_cvt_pk_bf16_f32 v96, v96, v97
	v_cvt_pk_bf16_f32 v97, v98, v99
	v_cvt_pk_bf16_f32 v98, v88, v89
	v_or_b32_e32 v88, 32, v144
	v_ashrrev_i32_e32 v89, 31, v88
	v_lshlrev_b64 v[88:89], 12, v[88:89]
	v_lshl_add_u64 v[88:89], s[28:29], 0, v[88:89]
	v_cvt_pk_bf16_f32 v99, v90, v91
	global_store_dwordx4 v[112:113], v[96:99], off offset:256
	v_readlane_b32 s94, v239, 44
	s_mov_b32 s90, s6
	v_lshl_add_u64 v[96:97], v[88:89], 0, v[148:149]
	v_cvt_pk_bf16_f32 v88, v100, v101
	v_cvt_pk_bf16_f32 v89, v102, v103
	v_cvt_pk_bf16_f32 v90, v92, v93
	v_cvt_pk_bf16_f32 v91, v94, v95
	global_store_dwordx4 v[96:97], v[88:91], off
	v_cvt_pk_bf16_f32 v84, v84, v85
	v_cvt_pk_bf16_f32 v85, v86, v87
	v_cvt_pk_bf16_f32 v86, v76, v77
	v_or_b32_e32 v76, 48, v144
	v_ashrrev_i32_e32 v77, 31, v76
	v_lshlrev_b64 v[76:77], 12, v[76:77]
	v_lshl_add_u64 v[76:77], s[28:29], 0, v[76:77]
	v_cvt_pk_bf16_f32 v87, v78, v79
	global_store_dwordx4 v[96:97], v[84:87], off offset:256
	s_mov_b64 s[28:29], 0x80000
	s_mov_b32 s91, s89
	v_lshl_add_u64 v[84:85], v[76:77], 0, v[148:149]
	v_cvt_pk_bf16_f32 v76, v80, v81
	v_cvt_pk_bf16_f32 v77, v82, v83
	v_cvt_pk_bf16_f32 v78, v72, v73
	v_cvt_pk_bf16_f32 v79, v74, v75
	global_store_dwordx4 v[84:85], v[76:79], off
	v_cvt_pk_bf16_f32 v68, v68, v69
	v_cvt_pk_bf16_f32 v69, v70, v71
	v_cvt_pk_bf16_f32 v70, v64, v65
	v_cvt_pk_bf16_f32 v71, v66, v67
	global_store_dwordx4 v[84:85], v[68:71], off offset:256
	v_cvt_pk_bf16_f32 v60, v60, v61
	v_cvt_pk_bf16_f32 v61, v62, v63
	v_cvt_pk_bf16_f32 v62, v56, v57
	v_add_co_u32_e32 v56, vcc, s2, v138
	v_lshl_add_u64 v[64:65], v[138:139], 0, s[28:29]
	s_nop 0
	v_addc_co_u32_e32 v57, vcc, 0, v139, vcc
	s_mov_b32 s2, 0x90000
	v_cvt_pk_bf16_f32 v63, v58, v59
	global_store_dwordx4 v[56:57], v[60:63], off
	v_cvt_pk_bf16_f32 v48, v48, v49
	v_cvt_pk_bf16_f32 v49, v50, v51
	v_cvt_pk_bf16_f32 v50, v40, v41
	v_cvt_pk_bf16_f32 v51, v42, v43
	global_store_dwordx4 v[64:65], v[48:51], off offset:256
	s_mov_b64 s[28:29], 0x90000
	v_cvt_pk_bf16_f32 v40, v52, v53
	v_cvt_pk_bf16_f32 v41, v54, v55
	v_cvt_pk_bf16_f32 v42, v44, v45
	v_add_co_u32_e32 v44, vcc, s2, v138
	v_lshl_add_u64 v[48:49], v[138:139], 0, s[28:29]
	s_nop 0
	v_addc_co_u32_e32 v45, vcc, 0, v139, vcc
	s_mov_b32 s2, 0xa0000
	v_cvt_pk_bf16_f32 v43, v46, v47
	global_store_dwordx4 v[44:45], v[40:43], off
	v_cvt_pk_bf16_f32 v32, v32, v33
	v_cvt_pk_bf16_f32 v33, v34, v35
	v_cvt_pk_bf16_f32 v34, v24, v25
	v_cvt_pk_bf16_f32 v35, v26, v27
	global_store_dwordx4 v[48:49], v[32:35], off offset:256
	s_mov_b64 s[28:29], 0xa0000
	v_cvt_pk_bf16_f32 v24, v36, v37
	v_cvt_pk_bf16_f32 v25, v38, v39
	v_cvt_pk_bf16_f32 v26, v28, v29
	v_add_co_u32_e32 v28, vcc, s2, v138
	v_lshl_add_u64 v[32:33], v[138:139], 0, s[28:29]
	s_nop 0
	v_addc_co_u32_e32 v29, vcc, 0, v139, vcc
	s_mov_b32 s2, 0xb0000
	v_cvt_pk_bf16_f32 v27, v30, v31
	global_store_dwordx4 v[28:29], v[24:27], off
	v_cvt_pk_bf16_f32 v16, v16, v17
	v_cvt_pk_bf16_f32 v17, v18, v19
	v_cvt_pk_bf16_f32 v18, v8, v9
	v_cvt_pk_bf16_f32 v19, v10, v11
	global_store_dwordx4 v[32:33], v[16:19], off offset:256
	v_cvt_pk_bf16_f32 v8, v20, v21
	v_cvt_pk_bf16_f32 v9, v22, v23
	v_cvt_pk_bf16_f32 v10, v12, v13
	v_add_co_u32_e32 v12, vcc, s2, v138
	s_mov_b64 s[28:29], 0xb0000
	s_nop 0
	v_addc_co_u32_e32 v13, vcc, 0, v139, vcc
	v_lshl_add_u64 v[16:17], v[138:139], 0, s[28:29]
	s_and_b64 vcc, exec, s[12:13]
	s_mov_b32 s2, s4
	s_mov_b64 s[68:69], s[14:15]
	s_mov_b64 s[28:29], s[8:9]
	v_readlane_b32 s93, v239, 43
	v_readlane_b32 s95, v239, 45
	s_mov_b32 s97, 0xac00
	v_cvt_pk_bf16_f32 v11, v14, v15
	global_store_dwordx4 v[12:13], v[8:11], off
	v_cvt_pk_bf16_f32 v4, v4, v5
	v_cvt_pk_bf16_f32 v5, v6, v7
	v_cvt_pk_bf16_f32 v6, v0, v1
	v_cvt_pk_bf16_f32 v7, v2, v3
	global_store_dwordx4 v[16:17], v[4:7], off offset:256
	s_cbranch_vccz .LBB0_998
	s_waitcnt vmcnt(0)
	s_cmpk_gt_u32 s36, 0xff
	s_cbranch_scc1 .LBB0_1008
	s_barrier

.LBB0_1023:
	s_add_i32 vcc_lo, s72, 2
	s_add_u32 s2, s28, 0xfff80080
	s_addc_u32 s3, s29, -1
	s_add_i32 vcc_hi, 0, 0x10000
	v_add_u32_e32 v146, vcc_hi, v149
	ds_read_b128 v[128:131], v146
	ds_read_b128 v[142:145], v146 offset:1024
	ds_read_b128 v[152:155], v146 offset:2048
	ds_read_b128 v[156:159], v146 offset:3072
	s_cmp_eq_u32 s95, s72
	s_cselect_b32 s71, s7, s3
	s_cselect_b32 s70, s92, s2
	s_cselect_b32 s69, s93, s97
	s_cselect_b32 s68, s94, s96
	v_lshl_add_u64 v[146:147], s[28:29], 0, v[138:139]
	s_add_i32 m0, s78, 0xc000
	ds_read_b128 v[160:163], v151
	ds_read_b128 v[164:167], v151 offset:1024
	ds_read_b128 v[194:197], v151 offset:2048
	ds_read_b128 v[198:201], v151 offset:3072
	ds_read_b128 v[202:205], v151 offset:4096
	ds_read_b128 v[206:209], v151 offset:5120
	ds_read_b128 v[210:213], v151 offset:6144
	ds_read_b128 v[214:217], v151 offset:7168
	global_load_lds_dwordx4 v[146:147], off
	v_lshl_add_u64 v[146:147], s[28:29], 0, v[140:141]
	s_add_i32 m0, s78, 0xe000
	s_nop 0
	global_load_lds_dwordx4 v[146:147], off
	s_waitcnt lgkmcnt(8)
	s_barrier
	s_waitcnt lgkmcnt(0)
	s_nop 0
	s_waitcnt lgkmcnt(0)
	v_mfma_f32_16x16x32_bf16 v[124:127], v[128:131], v[160:163], v[124:127]
	v_mfma_f32_16x16x32_bf16 v[120:123], v[152:155], v[160:163], v[120:123]
	v_mfma_f32_16x16x32_bf16 v[116:119], v[128:131], v[194:197], v[116:119]
	v_mfma_f32_16x16x32_bf16 v[108:111], v[152:155], v[194:197], v[108:111]
	v_mfma_f32_16x16x32_bf16 v[100:103], v[128:131], v[202:205], v[100:103]
	v_mfma_f32_16x16x32_bf16 v[92:95], v[152:155], v[202:205], v[92:95]
	v_mfma_f32_16x16x32_bf16 v[84:87], v[128:131], v[210:213], v[84:87]
	v_mfma_f32_16x16x32_bf16 v[76:79], v[152:155], v[210:213], v[76:79]
	v_mfma_f32_16x16x32_bf16 v[124:127], v[142:145], v[164:167], v[124:127]
	v_mfma_f32_16x16x32_bf16 v[120:123], v[156:159], v[164:167], v[120:123]
	v_mfma_f32_16x16x32_bf16 v[116:119], v[142:145], v[198:201], v[116:119]
	v_mfma_f32_16x16x32_bf16 v[108:111], v[156:159], v[198:201], v[108:111]
	v_mfma_f32_16x16x32_bf16 v[100:103], v[142:145], v[206:209], v[100:103]
	v_mfma_f32_16x16x32_bf16 v[92:95], v[156:159], v[206:209], v[92:95]
	v_mfma_f32_16x16x32_bf16 v[84:87], v[142:145], v[214:217], v[84:87]
	v_mfma_f32_16x16x32_bf16 v[76:79], v[156:159], v[214:217], v[76:79]
	s_nop 0
	s_barrier
	s_add_i32 s72, 0, 0x14000
	v_add_u32_e32 v146, s72, v149
	s_add_i32 s2, vcc_hi, s73
	ds_read_b128 v[218:221], v146
	ds_read_b128 v[222:225], v146 offset:1024
	ds_read_b128 v[226:229], v146 offset:2048
	ds_read_b128 v[230:233], v146 offset:3072
	v_lshl_add_u64 v[146:147], s[68:69], 0, v[168:169]
	s_mov_b32 m0, s2
	v_lshl_add_u64 v[176:177], s[68:69], 0, v[136:137]
	global_load_lds_dwordx4 v[146:147], off
	s_add_i32 m0, s2, 0x2000
	s_nop 0
	global_load_lds_dwordx4 v[176:177], off
	s_barrier
	s_waitcnt lgkmcnt(0)
	s_nop 0
	s_waitcnt lgkmcnt(0)
	v_mfma_f32_16x16x32_bf16 v[112:115], v[218:221], v[160:163], v[112:115]
	v_mfma_f32_16x16x32_bf16 v[104:107], v[226:229], v[160:163], v[104:107]
	v_mfma_f32_16x16x32_bf16 v[96:99], v[218:221], v[194:197], v[96:99]
	v_mfma_f32_16x16x32_bf16 v[88:91], v[226:229], v[194:197], v[88:91]
	v_mfma_f32_16x16x32_bf16 v[80:83], v[218:221], v[202:205], v[80:83]
	v_mfma_f32_16x16x32_bf16 v[72:75], v[226:229], v[202:205], v[72:75]
	v_mfma_f32_16x16x32_bf16 v[68:71], v[218:221], v[210:213], v[68:71]
	v_mfma_f32_16x16x32_bf16 v[64:67], v[226:229], v[210:213], v[64:67]
	v_mfma_f32_16x16x32_bf16 v[112:115], v[222:225], v[164:167], v[112:115]
	v_mfma_f32_16x16x32_bf16 v[104:107], v[230:233], v[164:167], v[104:107]
	v_mfma_f32_16x16x32_bf16 v[96:99], v[222:225], v[198:201], v[96:99]
	v_mfma_f32_16x16x32_bf16 v[88:91], v[230:233], v[198:201], v[88:91]
	v_mfma_f32_16x16x32_bf16 v[80:83], v[222:225], v[206:209], v[80:83]
	v_mfma_f32_16x16x32_bf16 v[72:75], v[230:233], v[206:209], v[72:75]
	v_mfma_f32_16x16x32_bf16 v[68:71], v[222:225], v[214:217], v[68:71]
	v_mfma_f32_16x16x32_bf16 v[64:67], v[230:233], v[214:217], v[64:67]
	s_nop 0
	s_mov_b32 m0, s78
	v_lshl_add_u64 v[234:235], s[70:71], 0, v[132:133]
	s_barrier
	ds_read_b128 v[160:163], v151 offset:16384
	ds_read_b128 v[164:167], v151 offset:17408
	ds_read_b128 v[194:197], v151 offset:18432
	ds_read_b128 v[198:201], v151 offset:19456
	ds_read_b128 v[202:205], v151 offset:20480
	ds_read_b128 v[206:209], v151 offset:21504
	ds_read_b128 v[210:213], v151 offset:22528
	ds_read_b128 v[214:217], v151 offset:23552
	global_load_lds_dwordx4 v[234:235], off
	v_lshl_add_u64 v[236:237], s[70:71], 0, v[134:135]
	s_mov_b32 m0, s79
	s_nop 0
	global_load_lds_dwordx4 v[236:237], off
	s_barrier
	s_waitcnt lgkmcnt(0)
	s_nop 0
	s_waitcnt lgkmcnt(0)
	v_mfma_f32_16x16x32_bf16 v[60:63], v[128:131], v[160:163], v[60:63]
	v_mfma_f32_16x16x32_bf16 v[56:59], v[152:155], v[160:163], v[56:59]
	v_mfma_f32_16x16x32_bf16 v[52:55], v[128:131], v[194:197], v[52:55]
	v_mfma_f32_16x16x32_bf16 v[44:47], v[152:155], v[194:197], v[44:47]
	v_mfma_f32_16x16x32_bf16 v[36:39], v[128:131], v[202:205], v[36:39]
	v_mfma_f32_16x16x32_bf16 v[28:31], v[152:155], v[202:205], v[28:31]
	v_mfma_f32_16x16x32_bf16 v[20:23], v[128:131], v[210:213], v[20:23]
	v_mfma_f32_16x16x32_bf16 v[12:15], v[152:155], v[210:213], v[12:15]
	v_mfma_f32_16x16x32_bf16 v[60:63], v[142:145], v[164:167], v[60:63]
	v_mfma_f32_16x16x32_bf16 v[56:59], v[156:159], v[164:167], v[56:59]
	v_mfma_f32_16x16x32_bf16 v[52:55], v[142:145], v[198:201], v[52:55]
	v_mfma_f32_16x16x32_bf16 v[44:47], v[156:159], v[198:201], v[44:47]
	v_mfma_f32_16x16x32_bf16 v[36:39], v[142:145], v[206:209], v[36:39]
	v_mfma_f32_16x16x32_bf16 v[28:31], v[156:159], v[206:209], v[28:31]
	v_mfma_f32_16x16x32_bf16 v[20:23], v[142:145], v[214:217], v[20:23]
	v_mfma_f32_16x16x32_bf16 v[12:15], v[156:159], v[214:217], v[12:15]
	s_nop 0
	s_barrier
	s_add_u32 s2, s68, 0x80000
	s_addc_u32 s3, s69, 0
	s_add_i32 s72, s72, s73
	v_lshl_add_u64 v[128:129], s[2:3], 0, v[168:169]
	s_mov_b32 m0, s72
	s_nop 0
	global_load_lds_dwordx4 v[128:129], off
	v_lshl_add_u64 v[128:129], s[2:3], 0, v[136:137]
	s_add_i32 m0, s72, 0x2000
	s_nop 0
	global_load_lds_dwordx4 v[128:129], off
	s_waitcnt vmcnt(6)
	s_barrier
	s_nop 0
	v_mfma_f32_16x16x32_bf16 v[48:51], v[218:221], v[160:163], v[48:51]
	v_mfma_f32_16x16x32_bf16 v[40:43], v[226:229], v[160:163], v[40:43]
	v_mfma_f32_16x16x32_bf16 v[32:35], v[218:221], v[194:197], v[32:35]
	v_mfma_f32_16x16x32_bf16 v[24:27], v[226:229], v[194:197], v[24:27]
	v_mfma_f32_16x16x32_bf16 v[16:19], v[218:221], v[202:205], v[16:19]
	v_mfma_f32_16x16x32_bf16 v[8:11], v[226:229], v[202:205], v[8:11]
	v_mfma_f32_16x16x32_bf16 v[4:7], v[218:221], v[210:213], v[4:7]
	v_mfma_f32_16x16x32_bf16 v[0:3], v[226:229], v[210:213], v[0:3]
	v_mfma_f32_16x16x32_bf16 v[48:51], v[222:225], v[164:167], v[48:51]
	v_mfma_f32_16x16x32_bf16 v[40:43], v[230:233], v[164:167], v[40:43]
	v_mfma_f32_16x16x32_bf16 v[32:35], v[222:225], v[198:201], v[32:35]
	v_mfma_f32_16x16x32_bf16 v[24:27], v[230:233], v[198:201], v[24:27]
	v_mfma_f32_16x16x32_bf16 v[16:19], v[222:225], v[206:209], v[16:19]
	v_mfma_f32_16x16x32_bf16 v[8:11], v[230:233], v[206:209], v[8:11]
	v_mfma_f32_16x16x32_bf16 v[4:7], v[222:225], v[214:217], v[4:7]
	v_mfma_f32_16x16x32_bf16 v[0:3], v[230:233], v[214:217], v[0:3]
	s_nop 0
	s_add_i32 s72, 0, 0x18000
	v_add_u32_e32 v156, s72, v149
	s_barrier
	ds_read_b128 v[128:131], v156
	ds_read_b128 v[142:145], v156 offset:1024
	ds_read_b128 v[152:155], v156 offset:2048
	ds_read_b128 v[156:159], v156 offset:3072
	s_add_u32 s2, s70, 0x80000
	s_addc_u32 s3, s71, 0
	s_mov_b32 m0, s82
	v_lshl_add_u64 v[218:219], s[2:3], 0, v[132:133]
	ds_read_b128 v[160:163], v151 offset:32768
	ds_read_b128 v[164:167], v151 offset:33792
	ds_read_b128 v[194:197], v151 offset:34816
	ds_read_b128 v[198:201], v151 offset:35840
	ds_read_b128 v[202:205], v151 offset:36864
	ds_read_b128 v[206:209], v151 offset:37888
	ds_read_b128 v[210:213], v151 offset:38912
	ds_read_b128 v[214:217], v151 offset:39936
	global_load_lds_dwordx4 v[218:219], off
	v_lshl_add_u64 v[218:219], s[2:3], 0, v[134:135]
	s_mov_b32 m0, s83
	s_nop 0
	global_load_lds_dwordx4 v[218:219], off
	s_waitcnt lgkmcnt(8)
	s_barrier
	s_waitcnt lgkmcnt(0)
	s_nop 0
	s_waitcnt lgkmcnt(0)
	v_mfma_f32_16x16x32_bf16 v[124:127], v[128:131], v[160:163], v[124:127]
	v_mfma_f32_16x16x32_bf16 v[120:123], v[152:155], v[160:163], v[120:123]
	v_mfma_f32_16x16x32_bf16 v[116:119], v[128:131], v[194:197], v[116:119]
	v_mfma_f32_16x16x32_bf16 v[108:111], v[152:155], v[194:197], v[108:111]
	v_mfma_f32_16x16x32_bf16 v[100:103], v[128:131], v[202:205], v[100:103]
	v_mfma_f32_16x16x32_bf16 v[92:95], v[152:155], v[202:205], v[92:95]
	v_mfma_f32_16x16x32_bf16 v[84:87], v[128:131], v[210:213], v[84:87]
	v_mfma_f32_16x16x32_bf16 v[76:79], v[152:155], v[210:213], v[76:79]
	v_mfma_f32_16x16x32_bf16 v[124:127], v[142:145], v[164:167], v[124:127]
	v_mfma_f32_16x16x32_bf16 v[120:123], v[156:159], v[164:167], v[120:123]
	v_mfma_f32_16x16x32_bf16 v[116:119], v[142:145], v[198:201], v[116:119]
	v_mfma_f32_16x16x32_bf16 v[108:111], v[156:159], v[198:201], v[108:111]
	v_mfma_f32_16x16x32_bf16 v[100:103], v[142:145], v[206:209], v[100:103]
	v_mfma_f32_16x16x32_bf16 v[92:95], v[156:159], v[206:209], v[92:95]
	v_mfma_f32_16x16x32_bf16 v[84:87], v[142:145], v[214:217], v[84:87]
	v_mfma_f32_16x16x32_bf16 v[76:79], v[156:159], v[214:217], v[76:79]
	s_nop 0
	s_barrier
	s_add_i32 s70, 0, 0x1c000
	s_add_i32 s2, s72, s73
	v_add_u32_e32 v193, s70, v149
	v_lshl_add_u64 v[146:147], v[146:147], 0, s[0:1]
	s_mov_b32 m0, s2
	ds_read_b128 v[218:221], v193
	ds_read_b128 v[222:225], v193 offset:1024
	ds_read_b128 v[226:229], v193 offset:2048
	ds_read_b128 v[230:233], v193 offset:3072
	global_load_lds_dwordx4 v[146:147], off
	v_lshl_add_u64 v[146:147], v[176:177], 0, s[0:1]
	s_add_i32 m0, s2, 0x2000
	s_nop 0
	global_load_lds_dwordx4 v[146:147], off
	s_barrier
	s_waitcnt lgkmcnt(0)
	s_nop 0
	s_waitcnt lgkmcnt(0)
	v_mfma_f32_16x16x32_bf16 v[112:115], v[218:221], v[160:163], v[112:115]
	v_mfma_f32_16x16x32_bf16 v[104:107], v[226:229], v[160:163], v[104:107]
	v_mfma_f32_16x16x32_bf16 v[96:99], v[218:221], v[194:197], v[96:99]
	v_mfma_f32_16x16x32_bf16 v[88:91], v[226:229], v[194:197], v[88:91]
	v_mfma_f32_16x16x32_bf16 v[80:83], v[218:221], v[202:205], v[80:83]
	v_mfma_f32_16x16x32_bf16 v[72:75], v[226:229], v[202:205], v[72:75]
	v_mfma_f32_16x16x32_bf16 v[68:71], v[218:221], v[210:213], v[68:71]
	v_mfma_f32_16x16x32_bf16 v[64:67], v[226:229], v[210:213], v[64:67]
	v_mfma_f32_16x16x32_bf16 v[112:115], v[222:225], v[164:167], v[112:115]
	v_mfma_f32_16x16x32_bf16 v[104:107], v[230:233], v[164:167], v[104:107]
	v_mfma_f32_16x16x32_bf16 v[96:99], v[222:225], v[198:201], v[96:99]
	v_mfma_f32_16x16x32_bf16 v[88:91], v[230:233], v[198:201], v[88:91]
	v_mfma_f32_16x16x32_bf16 v[80:83], v[222:225], v[206:209], v[80:83]
	v_mfma_f32_16x16x32_bf16 v[72:75], v[230:233], v[206:209], v[72:75]
	v_mfma_f32_16x16x32_bf16 v[68:71], v[222:225], v[214:217], v[68:71]
	v_mfma_f32_16x16x32_bf16 v[64:67], v[230:233], v[214:217], v[64:67]
	s_nop 0
	s_mov_b32 m0, s84
	v_lshl_add_u64 v[146:147], v[234:235], 0, s[0:1]
	s_barrier
	ds_read_b128 v[160:163], v151 offset:49152
	ds_read_b128 v[164:167], v151 offset:50176
	ds_read_b128 v[194:197], v151 offset:51200
	ds_read_b128 v[198:201], v151 offset:52224
	ds_read_b128 v[202:205], v151 offset:53248
	ds_read_b128 v[206:209], v151 offset:54272
	ds_read_b128 v[210:213], v151 offset:55296
	ds_read_b128 v[214:217], v151 offset:56320
	global_load_lds_dwordx4 v[146:147], off
	v_lshl_add_u64 v[146:147], v[236:237], 0, s[0:1]
	s_mov_b32 m0, s85
	s_nop 0
	global_load_lds_dwordx4 v[146:147], off
	s_barrier
	s_waitcnt lgkmcnt(0)
	s_nop 0
	s_waitcnt lgkmcnt(0)
	v_mfma_f32_16x16x32_bf16 v[60:63], v[128:131], v[160:163], v[60:63]
	v_mfma_f32_16x16x32_bf16 v[56:59], v[152:155], v[160:163], v[56:59]
	v_mfma_f32_16x16x32_bf16 v[52:55], v[128:131], v[194:197], v[52:55]
	v_mfma_f32_16x16x32_bf16 v[44:47], v[152:155], v[194:197], v[44:47]
	v_mfma_f32_16x16x32_bf16 v[36:39], v[128:131], v[202:205], v[36:39]
	v_mfma_f32_16x16x32_bf16 v[28:31], v[152:155], v[202:205], v[28:31]
	v_mfma_f32_16x16x32_bf16 v[20:23], v[128:131], v[210:213], v[20:23]
	v_mfma_f32_16x16x32_bf16 v[12:15], v[152:155], v[210:213], v[12:15]
	v_mfma_f32_16x16x32_bf16 v[60:63], v[142:145], v[164:167], v[60:63]
	v_mfma_f32_16x16x32_bf16 v[56:59], v[156:159], v[164:167], v[56:59]
	v_mfma_f32_16x16x32_bf16 v[52:55], v[142:145], v[198:201], v[52:55]
	v_mfma_f32_16x16x32_bf16 v[44:47], v[156:159], v[198:201], v[44:47]
	v_mfma_f32_16x16x32_bf16 v[36:39], v[142:145], v[206:209], v[36:39]
	v_mfma_f32_16x16x32_bf16 v[28:31], v[156:159], v[206:209], v[28:31]
	v_mfma_f32_16x16x32_bf16 v[20:23], v[142:145], v[214:217], v[20:23]
	v_mfma_f32_16x16x32_bf16 v[12:15], v[156:159], v[214:217], v[12:15]
	s_nop 0
	s_barrier
	s_add_u32 s2, s68, 0x80080
	s_addc_u32 s3, s69, 0
	s_add_i32 s68, s70, s73
	v_lshl_add_u64 v[128:129], s[2:3], 0, v[168:169]
	s_mov_b32 m0, s68
	s_nop 0
	global_load_lds_dwordx4 v[128:129], off
	v_lshl_add_u64 v[128:129], s[2:3], 0, v[136:137]
	s_add_i32 m0, s68, 0x2000
	s_nop 0
	global_load_lds_dwordx4 v[128:129], off
	s_waitcnt vmcnt(6)
	s_barrier
	s_nop 0
	v_mfma_f32_16x16x32_bf16 v[48:51], v[218:221], v[160:163], v[48:51]
	v_mfma_f32_16x16x32_bf16 v[40:43], v[226:229], v[160:163], v[40:43]
	v_mfma_f32_16x16x32_bf16 v[32:35], v[218:221], v[194:197], v[32:35]
	v_mfma_f32_16x16x32_bf16 v[24:27], v[226:229], v[194:197], v[24:27]
	v_mfma_f32_16x16x32_bf16 v[16:19], v[218:221], v[202:205], v[16:19]
	v_mfma_f32_16x16x32_bf16 v[8:11], v[226:229], v[202:205], v[8:11]
	v_mfma_f32_16x16x32_bf16 v[4:7], v[218:221], v[210:213], v[4:7]
	v_mfma_f32_16x16x32_bf16 v[0:3], v[226:229], v[210:213], v[0:3]
	v_mfma_f32_16x16x32_bf16 v[48:51], v[222:225], v[164:167], v[48:51]
	v_mfma_f32_16x16x32_bf16 v[40:43], v[230:233], v[164:167], v[40:43]
	v_mfma_f32_16x16x32_bf16 v[32:35], v[222:225], v[198:201], v[32:35]
	v_mfma_f32_16x16x32_bf16 v[24:27], v[230:233], v[198:201], v[24:27]
	v_mfma_f32_16x16x32_bf16 v[16:19], v[222:225], v[206:209], v[16:19]
	v_mfma_f32_16x16x32_bf16 v[8:11], v[230:233], v[206:209], v[8:11]
	v_mfma_f32_16x16x32_bf16 v[4:7], v[222:225], v[214:217], v[4:7]
	v_mfma_f32_16x16x32_bf16 v[0:3], v[230:233], v[214:217], v[0:3]
	s_nop 0
	s_add_u32 s28, s28, 0x100
	s_addc_u32 s29, s29, 0
	s_add_u32 s96, s96, 0x100
	s_addc_u32 s97, s97, 0
	s_cmp_ge_u32 vcc_lo, s91
	s_mov_b32 s72, vcc_lo
	s_barrier
	s_cbranch_scc0 .LBB0_1023
	v_lshl_add_u32 v144, s14, 8, v148
	v_lshl_or_b32 v142, s15, 8, v150
	s_mov_b64 s[14:15], -1
	s_cmp_gt_i32 s30, -1
	v_ashrrev_i32_e32 v143, 31, v142
	v_ashrrev_i32_e32 v145, 31, v144
	s_cbranch_scc1 .LBB0_1026
	v_readlane_b32 s2, v240, 62
	v_lshlrev_b64 v[128:129], 12, v[144:145]
	v_readlane_b32 s3, v240, 63
	v_or_b32_e32 v146, 16, v144
	v_lshlrev_b64 v[130:131], 1, v[142:143]
	v_lshl_add_u64 v[128:129], s[2:3], 0, v[128:129]
	v_ashrrev_i32_e32 v147, 31, v146
	v_lshl_add_u64 v[128:129], v[128:129], 0, v[130:131]
	v_cvt_pk_bf16_f32 v152, v124, v125
	v_cvt_pk_bf16_f32 v153, v126, v127
	v_cvt_pk_bf16_f32 v154, v120, v121
	v_cvt_pk_bf16_f32 v155, v122, v123
	v_lshlrev_b64 v[146:147], 12, v[146:147]
	global_store_dwordx4 v[128:129], v[152:155], off
	v_lshl_add_u64 v[146:147], s[2:3], 0, v[146:147]
	v_lshl_add_u64 v[146:147], v[146:147], 0, v[130:131]
	v_cvt_pk_bf16_f32 v152, v112, v113
	v_cvt_pk_bf16_f32 v153, v114, v115
	v_cvt_pk_bf16_f32 v154, v104, v105
	v_cvt_pk_bf16_f32 v155, v106, v107
	global_store_dwordx4 v[128:129], v[152:155], off offset:256
	s_mov_b64 s[14:15], 0
	s_nop 0
	v_cvt_pk_bf16_f32 v152, v116, v117
	v_cvt_pk_bf16_f32 v153, v118, v119
	v_cvt_pk_bf16_f32 v154, v108, v109
	v_cvt_pk_bf16_f32 v155, v110, v111
	global_store_dwordx4 v[146:147], v[152:155], off
	s_nop 1
	v_cvt_pk_bf16_f32 v152, v96, v97
	v_cvt_pk_bf16_f32 v153, v98, v99
	v_cvt_pk_bf16_f32 v154, v88, v89
	v_cvt_pk_bf16_f32 v155, v90, v91
	global_store_dwordx4 v[146:147], v[152:155], off offset:256
	v_or_b32_e32 v146, 32, v144
	v_ashrrev_i32_e32 v147, 31, v146
	v_lshlrev_b64 v[146:147], 12, v[146:147]
	v_lshl_add_u64 v[146:147], s[2:3], 0, v[146:147]
	v_lshl_add_u64 v[146:147], v[146:147], 0, v[130:131]
	v_cvt_pk_bf16_f32 v152, v100, v101
	v_cvt_pk_bf16_f32 v153, v102, v103
	v_cvt_pk_bf16_f32 v154, v92, v93
	v_cvt_pk_bf16_f32 v155, v94, v95
	global_store_dwordx4 v[146:147], v[152:155], off
	s_nop 1
	v_cvt_pk_bf16_f32 v152, v80, v81
	v_cvt_pk_bf16_f32 v153, v82, v83
	v_cvt_pk_bf16_f32 v154, v72, v73
	v_cvt_pk_bf16_f32 v155, v74, v75
	global_store_dwordx4 v[146:147], v[152:155], off offset:256
	v_or_b32_e32 v146, 48, v144
	v_ashrrev_i32_e32 v147, 31, v146
	v_lshlrev_b64 v[146:147], 12, v[146:147]
	v_lshl_add_u64 v[146:147], s[2:3], 0, v[146:147]
	v_lshl_add_u64 v[130:131], v[146:147], 0, v[130:131]
	v_cvt_pk_bf16_f32 v152, v84, v85
	v_cvt_pk_bf16_f32 v153, v86, v87
	v_cvt_pk_bf16_f32 v154, v76, v77
	v_cvt_pk_bf16_f32 v155, v78, v79
	s_mov_b64 s[2:3], 0x80000
	global_store_dwordx4 v[130:131], v[152:155], off
	s_nop 1
	v_cvt_pk_bf16_f32 v152, v68, v69
	v_cvt_pk_bf16_f32 v153, v70, v71
	v_cvt_pk_bf16_f32 v154, v64, v65
	v_cvt_pk_bf16_f32 v155, v66, v67
	global_store_dwordx4 v[130:131], v[152:155], off offset:256
	v_lshl_add_u64 v[130:131], v[128:129], 0, s[2:3]
	s_mov_b32 s2, 0x80000
	v_add_co_u32_e32 v146, vcc, s2, v128
	v_cvt_pk_bf16_f32 v152, v60, v61
	v_cvt_pk_bf16_f32 v153, v62, v63
	v_cvt_pk_bf16_f32 v154, v56, v57
	v_cvt_pk_bf16_f32 v155, v58, v59
	s_nop 1
	v_addc_co_u32_e32 v147, vcc, 0, v129, vcc
	s_mov_b64 s[2:3], 0x90000
	global_store_dwordx4 v[146:147], v[152:155], off
	s_nop 1
	v_cvt_pk_bf16_f32 v152, v48, v49
	v_cvt_pk_bf16_f32 v153, v50, v51
	v_cvt_pk_bf16_f32 v154, v40, v41
	v_cvt_pk_bf16_f32 v155, v42, v43
	global_store_dwordx4 v[130:131], v[152:155], off offset:256
	v_lshl_add_u64 v[130:131], v[128:129], 0, s[2:3]
	s_mov_b32 s2, 0x90000
	v_add_co_u32_e32 v146, vcc, s2, v128
	v_cvt_pk_bf16_f32 v152, v52, v53
	v_cvt_pk_bf16_f32 v153, v54, v55
	v_cvt_pk_bf16_f32 v154, v44, v45
	v_cvt_pk_bf16_f32 v155, v46, v47
	s_nop 1
	v_addc_co_u32_e32 v147, vcc, 0, v129, vcc
	s_mov_b64 s[2:3], 0xa0000
	global_store_dwordx4 v[146:147], v[152:155], off
	s_nop 1
	v_cvt_pk_bf16_f32 v152, v32, v33
	v_cvt_pk_bf16_f32 v153, v34, v35
	v_cvt_pk_bf16_f32 v154, v24, v25
	v_cvt_pk_bf16_f32 v155, v26, v27
	global_store_dwordx4 v[130:131], v[152:155], off offset:256
	v_lshl_add_u64 v[130:131], v[128:129], 0, s[2:3]
	s_mov_b32 s2, 0xa0000
	v_add_co_u32_e32 v146, vcc, s2, v128
	s_mov_b64 s[2:3], 0xb0000
	s_nop 0
	v_addc_co_u32_e32 v147, vcc, 0, v129, vcc
	v_cvt_pk_bf16_f32 v152, v36, v37
	v_cvt_pk_bf16_f32 v153, v38, v39
	v_cvt_pk_bf16_f32 v154, v28, v29
	v_cvt_pk_bf16_f32 v155, v30, v31
	global_store_dwordx4 v[146:147], v[152:155], off
	v_lshl_add_u64 v[146:147], v[128:129], 0, s[2:3]
	s_mov_b32 s2, 0xb0000
	v_add_co_u32_e32 v128, vcc, s2, v128
	v_cvt_pk_bf16_f32 v152, v16, v17
	v_cvt_pk_bf16_f32 v153, v18, v19
	v_cvt_pk_bf16_f32 v154, v8, v9
	v_cvt_pk_bf16_f32 v155, v10, v11
	s_nop 1
	v_addc_co_u32_e32 v129, vcc, 0, v129, vcc
	global_store_dwordx4 v[130:131], v[152:155], off offset:256
	s_nop 1
	v_cvt_pk_bf16_f32 v152, v20, v21
	v_cvt_pk_bf16_f32 v153, v22, v23
	v_cvt_pk_bf16_f32 v154, v12, v13
	v_cvt_pk_bf16_f32 v155, v14, v15
	global_store_dwordx4 v[128:129], v[152:155], off
	v_cvt_pk_bf16_f32 v128, v4, v5
	v_cvt_pk_bf16_f32 v129, v6, v7
	v_cvt_pk_bf16_f32 v130, v0, v1
	v_cvt_pk_bf16_f32 v131, v2, v3

.LBB0_1189:
	s_add_i32 vcc_lo, s68, 2
	s_add_u32 s69, s28, 0xfff80080
	s_addc_u32 s70, s29, -1
	s_add_i32 s78, 0, 0x10000
	v_add_u32_e32 v154, s78, v143
	ds_read_b128 v[138:141], v154
	ds_read_b128 v[146:149], v154 offset:1024
	ds_read_b128 v[150:153], v154 offset:2048
	ds_read_b128 v[154:157], v154 offset:3072
	s_cmp_eq_u32 s95, s68
	s_cselect_b32 s68, s94, s96
	s_cselect_b32 s71, s5, s70
	s_cselect_b32 s70, s93, s69
	s_cselect_b32 s69, s7, s97
	v_lshl_add_u64 v[166:167], s[28:29], 0, v[134:135]
	s_add_i32 m0, s3, 0xc000
	ds_read_b128 v[158:161], v145
	ds_read_b128 v[162:165], v145 offset:1024
	ds_read_b128 v[194:197], v145 offset:2048
	ds_read_b128 v[198:201], v145 offset:3072
	ds_read_b128 v[202:205], v145 offset:4096
	ds_read_b128 v[206:209], v145 offset:5120
	ds_read_b128 v[210:213], v145 offset:6144
	ds_read_b128 v[214:217], v145 offset:7168
	global_load_lds_dwordx4 v[166:167], off
	v_lshl_add_u64 v[166:167], s[28:29], 0, v[136:137]
	s_add_i32 m0, s3, 0xe000
	s_nop 0
	global_load_lds_dwordx4 v[166:167], off
	s_waitcnt lgkmcnt(8)
	s_barrier
	s_waitcnt lgkmcnt(0)
	s_nop 0
	s_waitcnt lgkmcnt(0)
	v_mfma_f32_16x16x32_bf16 v[124:127], v[138:141], v[158:161], v[124:127]
	v_mfma_f32_16x16x32_bf16 v[120:123], v[150:153], v[158:161], v[120:123]
	v_mfma_f32_16x16x32_bf16 v[116:119], v[138:141], v[194:197], v[116:119]
	v_mfma_f32_16x16x32_bf16 v[108:111], v[150:153], v[194:197], v[108:111]
	v_mfma_f32_16x16x32_bf16 v[100:103], v[138:141], v[202:205], v[100:103]
	v_mfma_f32_16x16x32_bf16 v[92:95], v[150:153], v[202:205], v[92:95]
	v_mfma_f32_16x16x32_bf16 v[84:87], v[138:141], v[210:213], v[84:87]
	v_mfma_f32_16x16x32_bf16 v[76:79], v[150:153], v[210:213], v[76:79]
	v_mfma_f32_16x16x32_bf16 v[124:127], v[146:149], v[162:165], v[124:127]
	v_mfma_f32_16x16x32_bf16 v[120:123], v[154:157], v[162:165], v[120:123]
	v_mfma_f32_16x16x32_bf16 v[116:119], v[146:149], v[198:201], v[116:119]
	v_mfma_f32_16x16x32_bf16 v[108:111], v[154:157], v[198:201], v[108:111]
	v_mfma_f32_16x16x32_bf16 v[100:103], v[146:149], v[206:209], v[100:103]
	v_mfma_f32_16x16x32_bf16 v[92:95], v[154:157], v[206:209], v[92:95]
	v_mfma_f32_16x16x32_bf16 v[84:87], v[146:149], v[214:217], v[84:87]
	v_mfma_f32_16x16x32_bf16 v[76:79], v[154:157], v[214:217], v[76:79]
	s_nop 0
	s_barrier
	s_add_i32 vcc_hi, 0, 0x14000
	v_add_u32_e32 v166, vcc_hi, v143
	s_add_i32 s78, s78, s83
	ds_read_b128 v[218:221], v166
	ds_read_b128 v[222:225], v166 offset:1024
	ds_read_b128 v[226:229], v166 offset:2048
	ds_read_b128 v[230:233], v166 offset:3072
	v_lshl_add_u64 v[166:167], s[68:69], 0, v[168:169]
	s_mov_b32 m0, s78
	v_lshl_add_u64 v[176:177], s[68:69], 0, v[132:133]
	global_load_lds_dwordx4 v[166:167], off
	s_add_i32 m0, s78, 0x2000
	s_nop 0
	global_load_lds_dwordx4 v[176:177], off
	s_barrier
	s_waitcnt lgkmcnt(0)
	s_nop 0
	s_waitcnt lgkmcnt(0)
	v_mfma_f32_16x16x32_bf16 v[112:115], v[218:221], v[158:161], v[112:115]
	v_mfma_f32_16x16x32_bf16 v[104:107], v[226:229], v[158:161], v[104:107]
	v_mfma_f32_16x16x32_bf16 v[96:99], v[218:221], v[194:197], v[96:99]
	v_mfma_f32_16x16x32_bf16 v[88:91], v[226:229], v[194:197], v[88:91]
	v_mfma_f32_16x16x32_bf16 v[80:83], v[218:221], v[202:205], v[80:83]
	v_mfma_f32_16x16x32_bf16 v[72:75], v[226:229], v[202:205], v[72:75]
	v_mfma_f32_16x16x32_bf16 v[68:71], v[218:221], v[210:213], v[68:71]
	v_mfma_f32_16x16x32_bf16 v[64:67], v[226:229], v[210:213], v[64:67]
	v_mfma_f32_16x16x32_bf16 v[112:115], v[222:225], v[162:165], v[112:115]
	v_mfma_f32_16x16x32_bf16 v[104:107], v[230:233], v[162:165], v[104:107]
	v_mfma_f32_16x16x32_bf16 v[96:99], v[222:225], v[198:201], v[96:99]
	v_mfma_f32_16x16x32_bf16 v[88:91], v[230:233], v[198:201], v[88:91]
	v_mfma_f32_16x16x32_bf16 v[80:83], v[222:225], v[206:209], v[80:83]
	v_mfma_f32_16x16x32_bf16 v[72:75], v[230:233], v[206:209], v[72:75]
	v_mfma_f32_16x16x32_bf16 v[68:71], v[222:225], v[214:217], v[68:71]
	v_mfma_f32_16x16x32_bf16 v[64:67], v[230:233], v[214:217], v[64:67]
	s_nop 0
	s_mov_b32 m0, s3
	v_lshl_add_u64 v[234:235], s[70:71], 0, v[128:129]
	s_barrier
	ds_read_b128 v[158:161], v145 offset:16384
	ds_read_b128 v[162:165], v145 offset:17408
	ds_read_b128 v[194:197], v145 offset:18432
	ds_read_b128 v[198:201], v145 offset:19456
	ds_read_b128 v[202:205], v145 offset:20480
	ds_read_b128 v[206:209], v145 offset:21504
	ds_read_b128 v[210:213], v145 offset:22528
	ds_read_b128 v[214:217], v145 offset:23552
	global_load_lds_dwordx4 v[234:235], off
	v_lshl_add_u64 v[236:237], s[70:71], 0, v[130:131]
	s_mov_b32 m0, s84
	s_nop 0
	global_load_lds_dwordx4 v[236:237], off
	s_barrier
	s_waitcnt lgkmcnt(0)
	s_nop 0
	s_waitcnt lgkmcnt(0)
	v_mfma_f32_16x16x32_bf16 v[60:63], v[138:141], v[158:161], v[60:63]
	v_mfma_f32_16x16x32_bf16 v[56:59], v[150:153], v[158:161], v[56:59]
	v_mfma_f32_16x16x32_bf16 v[52:55], v[138:141], v[194:197], v[52:55]
	v_mfma_f32_16x16x32_bf16 v[44:47], v[150:153], v[194:197], v[44:47]
	v_mfma_f32_16x16x32_bf16 v[36:39], v[138:141], v[202:205], v[36:39]
	v_mfma_f32_16x16x32_bf16 v[28:31], v[150:153], v[202:205], v[28:31]
	v_mfma_f32_16x16x32_bf16 v[20:23], v[138:141], v[210:213], v[20:23]
	v_mfma_f32_16x16x32_bf16 v[12:15], v[150:153], v[210:213], v[12:15]
	v_mfma_f32_16x16x32_bf16 v[60:63], v[146:149], v[162:165], v[60:63]
	v_mfma_f32_16x16x32_bf16 v[56:59], v[154:157], v[162:165], v[56:59]
	v_mfma_f32_16x16x32_bf16 v[52:55], v[146:149], v[198:201], v[52:55]
	v_mfma_f32_16x16x32_bf16 v[44:47], v[154:157], v[198:201], v[44:47]
	v_mfma_f32_16x16x32_bf16 v[36:39], v[146:149], v[206:209], v[36:39]
	v_mfma_f32_16x16x32_bf16 v[28:31], v[154:157], v[206:209], v[28:31]
	v_mfma_f32_16x16x32_bf16 v[20:23], v[146:149], v[214:217], v[20:23]
	v_mfma_f32_16x16x32_bf16 v[12:15], v[154:157], v[214:217], v[12:15]
	s_nop 0
	s_barrier
	s_add_u32 s78, s68, 0x80000
	s_addc_u32 s79, s69, 0
	s_add_i32 vcc_hi, vcc_hi, s83
	v_lshl_add_u64 v[138:139], s[78:79], 0, v[168:169]
	s_mov_b32 m0, vcc_hi
	s_nop 0
	global_load_lds_dwordx4 v[138:139], off
	v_lshl_add_u64 v[138:139], s[78:79], 0, v[132:133]
	s_add_i32 m0, vcc_hi, 0x2000
	s_nop 0
	global_load_lds_dwordx4 v[138:139], off
	s_waitcnt vmcnt(6)
	s_barrier
	s_nop 0
	v_mfma_f32_16x16x32_bf16 v[48:51], v[218:221], v[158:161], v[48:51]
	v_mfma_f32_16x16x32_bf16 v[40:43], v[226:229], v[158:161], v[40:43]
	v_mfma_f32_16x16x32_bf16 v[32:35], v[218:221], v[194:197], v[32:35]
	v_mfma_f32_16x16x32_bf16 v[24:27], v[226:229], v[194:197], v[24:27]
	v_mfma_f32_16x16x32_bf16 v[16:19], v[218:221], v[202:205], v[16:19]
	v_mfma_f32_16x16x32_bf16 v[8:11], v[226:229], v[202:205], v[8:11]
	v_mfma_f32_16x16x32_bf16 v[4:7], v[218:221], v[210:213], v[4:7]
	v_mfma_f32_16x16x32_bf16 v[0:3], v[226:229], v[210:213], v[0:3]
	v_mfma_f32_16x16x32_bf16 v[48:51], v[222:225], v[162:165], v[48:51]
	v_mfma_f32_16x16x32_bf16 v[40:43], v[230:233], v[162:165], v[40:43]
	v_mfma_f32_16x16x32_bf16 v[32:35], v[222:225], v[198:201], v[32:35]
	v_mfma_f32_16x16x32_bf16 v[24:27], v[230:233], v[198:201], v[24:27]
	v_mfma_f32_16x16x32_bf16 v[16:19], v[222:225], v[206:209], v[16:19]
	v_mfma_f32_16x16x32_bf16 v[8:11], v[230:233], v[206:209], v[8:11]
	v_mfma_f32_16x16x32_bf16 v[4:7], v[222:225], v[214:217], v[4:7]
	v_mfma_f32_16x16x32_bf16 v[0:3], v[230:233], v[214:217], v[0:3]
	s_nop 0
	s_add_i32 s78, 0, 0x18000
	v_add_u32_e32 v154, s78, v143
	s_barrier
	ds_read_b128 v[138:141], v154
	ds_read_b128 v[146:149], v154 offset:1024
	ds_read_b128 v[150:153], v154 offset:2048
	ds_read_b128 v[154:157], v154 offset:3072
	s_add_u32 s70, s70, 0x80000
	s_addc_u32 s71, s71, 0
	s_mov_b32 m0, s85
	v_lshl_add_u64 v[218:219], s[70:71], 0, v[128:129]
	ds_read_b128 v[158:161], v145 offset:32768
	ds_read_b128 v[162:165], v145 offset:33792
	ds_read_b128 v[194:197], v145 offset:34816
	ds_read_b128 v[198:201], v145 offset:35840
	ds_read_b128 v[202:205], v145 offset:36864
	ds_read_b128 v[206:209], v145 offset:37888
	ds_read_b128 v[210:213], v145 offset:38912
	ds_read_b128 v[214:217], v145 offset:39936
	global_load_lds_dwordx4 v[218:219], off
	v_lshl_add_u64 v[218:219], s[70:71], 0, v[130:131]
	s_mov_b32 m0, s86
	s_nop 0
	global_load_lds_dwordx4 v[218:219], off
	s_waitcnt lgkmcnt(8)
	s_barrier
	s_waitcnt lgkmcnt(0)
	s_nop 0
	s_waitcnt lgkmcnt(0)
	v_mfma_f32_16x16x32_bf16 v[124:127], v[138:141], v[158:161], v[124:127]
	v_mfma_f32_16x16x32_bf16 v[120:123], v[150:153], v[158:161], v[120:123]
	v_mfma_f32_16x16x32_bf16 v[116:119], v[138:141], v[194:197], v[116:119]
	v_mfma_f32_16x16x32_bf16 v[108:111], v[150:153], v[194:197], v[108:111]
	v_mfma_f32_16x16x32_bf16 v[100:103], v[138:141], v[202:205], v[100:103]
	v_mfma_f32_16x16x32_bf16 v[92:95], v[150:153], v[202:205], v[92:95]
	v_mfma_f32_16x16x32_bf16 v[84:87], v[138:141], v[210:213], v[84:87]
	v_mfma_f32_16x16x32_bf16 v[76:79], v[150:153], v[210:213], v[76:79]
	v_mfma_f32_16x16x32_bf16 v[124:127], v[146:149], v[162:165], v[124:127]
	v_mfma_f32_16x16x32_bf16 v[120:123], v[154:157], v[162:165], v[120:123]
	v_mfma_f32_16x16x32_bf16 v[116:119], v[146:149], v[198:201], v[116:119]
	v_mfma_f32_16x16x32_bf16 v[108:111], v[154:157], v[198:201], v[108:111]
	v_mfma_f32_16x16x32_bf16 v[100:103], v[146:149], v[206:209], v[100:103]
	v_mfma_f32_16x16x32_bf16 v[92:95], v[154:157], v[206:209], v[92:95]
	v_mfma_f32_16x16x32_bf16 v[84:87], v[146:149], v[214:217], v[84:87]
	v_mfma_f32_16x16x32_bf16 v[76:79], v[154:157], v[214:217], v[76:79]
	s_nop 0
	s_barrier
	s_add_i32 s70, 0, 0x1c000
	s_add_i32 s71, s78, s83
	v_add_u32_e32 v193, s70, v143
	v_lshl_add_u64 v[166:167], v[166:167], 0, s[0:1]
	s_mov_b32 m0, s71
	ds_read_b128 v[218:221], v193
	ds_read_b128 v[222:225], v193 offset:1024
	ds_read_b128 v[226:229], v193 offset:2048
	ds_read_b128 v[230:233], v193 offset:3072
	global_load_lds_dwordx4 v[166:167], off
	v_lshl_add_u64 v[166:167], v[176:177], 0, s[0:1]
	s_add_i32 m0, s71, 0x2000
	s_nop 0
	global_load_lds_dwordx4 v[166:167], off
	s_barrier
	s_waitcnt lgkmcnt(0)
	s_nop 0
	s_waitcnt lgkmcnt(0)
	v_mfma_f32_16x16x32_bf16 v[112:115], v[218:221], v[158:161], v[112:115]
	v_mfma_f32_16x16x32_bf16 v[104:107], v[226:229], v[158:161], v[104:107]
	v_mfma_f32_16x16x32_bf16 v[96:99], v[218:221], v[194:197], v[96:99]
	v_mfma_f32_16x16x32_bf16 v[88:91], v[226:229], v[194:197], v[88:91]
	v_mfma_f32_16x16x32_bf16 v[80:83], v[218:221], v[202:205], v[80:83]
	v_mfma_f32_16x16x32_bf16 v[72:75], v[226:229], v[202:205], v[72:75]
	v_mfma_f32_16x16x32_bf16 v[68:71], v[218:221], v[210:213], v[68:71]
	v_mfma_f32_16x16x32_bf16 v[64:67], v[226:229], v[210:213], v[64:67]
	v_mfma_f32_16x16x32_bf16 v[112:115], v[222:225], v[162:165], v[112:115]
	v_mfma_f32_16x16x32_bf16 v[104:107], v[230:233], v[162:165], v[104:107]
	v_mfma_f32_16x16x32_bf16 v[96:99], v[222:225], v[198:201], v[96:99]
	v_mfma_f32_16x16x32_bf16 v[88:91], v[230:233], v[198:201], v[88:91]
	v_mfma_f32_16x16x32_bf16 v[80:83], v[222:225], v[206:209], v[80:83]
	v_mfma_f32_16x16x32_bf16 v[72:75], v[230:233], v[206:209], v[72:75]
	v_mfma_f32_16x16x32_bf16 v[68:71], v[222:225], v[214:217], v[68:71]
	v_mfma_f32_16x16x32_bf16 v[64:67], v[230:233], v[214:217], v[64:67]
	s_nop 0
	s_mov_b32 m0, s87
	v_lshl_add_u64 v[166:167], v[234:235], 0, s[0:1]
	s_barrier
	ds_read_b128 v[158:161], v145 offset:49152
	ds_read_b128 v[162:165], v145 offset:50176
	ds_read_b128 v[194:197], v145 offset:51200
	ds_read_b128 v[198:201], v145 offset:52224
	ds_read_b128 v[202:205], v145 offset:53248
	ds_read_b128 v[206:209], v145 offset:54272
	ds_read_b128 v[210:213], v145 offset:55296
	ds_read_b128 v[214:217], v145 offset:56320
	global_load_lds_dwordx4 v[166:167], off
	v_lshl_add_u64 v[166:167], v[236:237], 0, s[0:1]
	s_mov_b32 m0, s88
	s_nop 0
	global_load_lds_dwordx4 v[166:167], off
	s_barrier
	s_waitcnt lgkmcnt(0)
	s_nop 0
	s_waitcnt lgkmcnt(0)
	v_mfma_f32_16x16x32_bf16 v[60:63], v[138:141], v[158:161], v[60:63]
	v_mfma_f32_16x16x32_bf16 v[56:59], v[150:153], v[158:161], v[56:59]
	v_mfma_f32_16x16x32_bf16 v[52:55], v[138:141], v[194:197], v[52:55]
	v_mfma_f32_16x16x32_bf16 v[44:47], v[150:153], v[194:197], v[44:47]
	v_mfma_f32_16x16x32_bf16 v[36:39], v[138:141], v[202:205], v[36:39]
	v_mfma_f32_16x16x32_bf16 v[28:31], v[150:153], v[202:205], v[28:31]
	v_mfma_f32_16x16x32_bf16 v[20:23], v[138:141], v[210:213], v[20:23]
	v_mfma_f32_16x16x32_bf16 v[12:15], v[150:153], v[210:213], v[12:15]
	v_mfma_f32_16x16x32_bf16 v[60:63], v[146:149], v[162:165], v[60:63]
	v_mfma_f32_16x16x32_bf16 v[56:59], v[154:157], v[162:165], v[56:59]
	v_mfma_f32_16x16x32_bf16 v[52:55], v[146:149], v[198:201], v[52:55]
	v_mfma_f32_16x16x32_bf16 v[44:47], v[154:157], v[198:201], v[44:47]
	v_mfma_f32_16x16x32_bf16 v[36:39], v[146:149], v[206:209], v[36:39]
	v_mfma_f32_16x16x32_bf16 v[28:31], v[154:157], v[206:209], v[28:31]
	v_mfma_f32_16x16x32_bf16 v[20:23], v[146:149], v[214:217], v[20:23]
	v_mfma_f32_16x16x32_bf16 v[12:15], v[154:157], v[214:217], v[12:15]
	s_nop 0
	s_barrier
	s_add_u32 s68, s68, 0x80080
	s_addc_u32 s69, s69, 0
	s_add_i32 s70, s70, s83
	v_lshl_add_u64 v[138:139], s[68:69], 0, v[168:169]
	s_mov_b32 m0, s70
	s_nop 0
	global_load_lds_dwordx4 v[138:139], off
	v_lshl_add_u64 v[138:139], s[68:69], 0, v[132:133]
	s_add_i32 m0, s70, 0x2000
	s_nop 0
	global_load_lds_dwordx4 v[138:139], off
	s_waitcnt vmcnt(6)
	s_barrier
	s_nop 0
	v_mfma_f32_16x16x32_bf16 v[48:51], v[218:221], v[158:161], v[48:51]
	v_mfma_f32_16x16x32_bf16 v[40:43], v[226:229], v[158:161], v[40:43]
	v_mfma_f32_16x16x32_bf16 v[32:35], v[218:221], v[194:197], v[32:35]
	v_mfma_f32_16x16x32_bf16 v[24:27], v[226:229], v[194:197], v[24:27]
	v_mfma_f32_16x16x32_bf16 v[16:19], v[218:221], v[202:205], v[16:19]
	v_mfma_f32_16x16x32_bf16 v[8:11], v[226:229], v[202:205], v[8:11]
	v_mfma_f32_16x16x32_bf16 v[4:7], v[218:221], v[210:213], v[4:7]
	v_mfma_f32_16x16x32_bf16 v[0:3], v[226:229], v[210:213], v[0:3]
	v_mfma_f32_16x16x32_bf16 v[48:51], v[222:225], v[162:165], v[48:51]
	v_mfma_f32_16x16x32_bf16 v[40:43], v[230:233], v[162:165], v[40:43]
	v_mfma_f32_16x16x32_bf16 v[32:35], v[222:225], v[198:201], v[32:35]
	v_mfma_f32_16x16x32_bf16 v[24:27], v[230:233], v[198:201], v[24:27]
	v_mfma_f32_16x16x32_bf16 v[16:19], v[222:225], v[206:209], v[16:19]
	v_mfma_f32_16x16x32_bf16 v[8:11], v[230:233], v[206:209], v[8:11]
	v_mfma_f32_16x16x32_bf16 v[4:7], v[222:225], v[214:217], v[4:7]
	v_mfma_f32_16x16x32_bf16 v[0:3], v[230:233], v[214:217], v[0:3]
	s_nop 0
	s_add_u32 s28, s28, 0x100
	s_addc_u32 s29, s29, 0
	s_add_u32 s96, s96, 0x100
	s_addc_u32 s97, s97, 0
	s_cmp_ge_u32 vcc_lo, s92
	s_mov_b32 s68, vcc_lo
	s_barrier
	s_cbranch_scc0 .LBB0_1189
	v_readlane_b32 s94, v239, 44
	v_lshl_or_b32 v140, s91, 8, v144
	v_readlane_b32 s95, v239, 45
	v_lshl_add_u32 v148, s2, 8, v142
	v_ashrrev_i32_e32 v141, 31, v140
	v_mov_b64_e32 v[138:139], s[94:95]
	s_movk_i32 s2, 0x5600
	v_mad_i64_i32 v[146:147], s[28:29], v148, s2, v[138:139]
	v_lshlrev_b64 v[140:141], 1, v[140:141]
	v_lshl_add_u64 v[146:147], v[146:147], 0, v[140:141]
	v_cvt_pk_bf16_f32 v124, v124, v125
	v_cvt_pk_bf16_f32 v125, v126, v127
	v_cvt_pk_bf16_f32 v126, v120, v121
	v_cvt_pk_bf16_f32 v127, v122, v123
	global_store_dwordx4 v[146:147], v[124:127], off
	v_cvt_pk_bf16_f32 v112, v112, v113
	v_cvt_pk_bf16_f32 v113, v114, v115
	v_cvt_pk_bf16_f32 v114, v104, v105
	v_or_b32_e32 v104, 16, v148
	v_mad_i64_i32 v[104:105], s[28:29], v104, s2, v[138:139]
	v_cvt_pk_bf16_f32 v115, v106, v107
	global_store_dwordx4 v[146:147], v[112:115], off offset:256
	s_and_b64 vcc, exec, s[12:13]
	s_mov_b32 s91, s6
	v_lshl_add_u64 v[112:113], v[104:105], 0, v[140:141]
	v_cvt_pk_bf16_f32 v104, v116, v117
	v_cvt_pk_bf16_f32 v105, v118, v119
	v_cvt_pk_bf16_f32 v106, v108, v109
	v_cvt_pk_bf16_f32 v107, v110, v111
	global_store_dwordx4 v[112:113], v[104:107], off
	v_cvt_pk_bf16_f32 v96, v96, v97
	v_cvt_pk_bf16_f32 v97, v98, v99
	v_cvt_pk_bf16_f32 v98, v88, v89
	v_or_b32_e32 v88, 32, v148
	v_mad_i64_i32 v[88:89], s[28:29], v88, s2, v[138:139]
	v_cvt_pk_bf16_f32 v99, v90, v91
	global_store_dwordx4 v[112:113], v[96:99], off offset:256
	s_mov_b32 s92, s90
	s_mov_b64 s[68:69], s[14:15]
	v_lshl_add_u64 v[96:97], v[88:89], 0, v[140:141]
	v_cvt_pk_bf16_f32 v88, v100, v101
	v_cvt_pk_bf16_f32 v89, v102, v103
	v_cvt_pk_bf16_f32 v90, v92, v93
	v_cvt_pk_bf16_f32 v91, v94, v95
	global_store_dwordx4 v[96:97], v[88:91], off
	v_cvt_pk_bf16_f32 v80, v80, v81
	v_cvt_pk_bf16_f32 v81, v82, v83
	v_cvt_pk_bf16_f32 v82, v72, v73
	v_or_b32_e32 v72, 48, v148
	v_mad_i64_i32 v[72:73], s[28:29], v72, s2, v[138:139]
	v_cvt_pk_bf16_f32 v83, v74, v75
	global_store_dwordx4 v[96:97], v[80:83], off offset:256
	s_mov_b32 s97, 0xac00
	s_nop 0
	v_lshl_add_u64 v[80:81], v[72:73], 0, v[140:141]
	v_cvt_pk_bf16_f32 v72, v84, v85
	v_cvt_pk_bf16_f32 v73, v86, v87
	v_cvt_pk_bf16_f32 v74, v76, v77
	v_cvt_pk_bf16_f32 v75, v78, v79
	global_store_dwordx4 v[80:81], v[72:75], off
	v_cvt_pk_bf16_f32 v68, v68, v69
	v_cvt_pk_bf16_f32 v69, v70, v71
	v_cvt_pk_bf16_f32 v70, v64, v65
	v_add_u32_e32 v64, 0x80, v148
	v_mad_i64_i32 v[64:65], s[28:29], v64, s2, v[138:139]
	v_lshl_add_u64 v[64:65], v[64:65], 0, v[140:141]
	v_cvt_pk_bf16_f32 v71, v66, v67
	global_store_dwordx4 v[80:81], v[68:71], off offset:256
	v_cvt_pk_bf16_f32 v60, v60, v61
	v_cvt_pk_bf16_f32 v61, v62, v63
	v_cvt_pk_bf16_f32 v62, v56, v57
	v_cvt_pk_bf16_f32 v63, v58, v59
	global_store_dwordx4 v[64:65], v[60:63], off
	v_cvt_pk_bf16_f32 v48, v48, v49
	v_cvt_pk_bf16_f32 v49, v50, v51
	v_cvt_pk_bf16_f32 v50, v40, v41
	v_add_u32_e32 v40, 0x90, v148
	v_mad_i64_i32 v[40:41], s[28:29], v40, s2, v[138:139]
	v_cvt_pk_bf16_f32 v51, v42, v43
	global_store_dwordx4 v[64:65], v[48:51], off offset:256
	s_nop 1
	v_lshl_add_u64 v[48:49], v[40:41], 0, v[140:141]
	v_cvt_pk_bf16_f32 v40, v52, v53
	v_cvt_pk_bf16_f32 v41, v54, v55
	v_cvt_pk_bf16_f32 v42, v44, v45
	v_cvt_pk_bf16_f32 v43, v46, v47
	global_store_dwordx4 v[48:49], v[40:43], off
	v_cvt_pk_bf16_f32 v32, v32, v33
	v_cvt_pk_bf16_f32 v33, v34, v35
	v_cvt_pk_bf16_f32 v34, v24, v25
	v_add_u32_e32 v24, 0xa0, v148
	v_mad_i64_i32 v[24:25], s[28:29], v24, s2, v[138:139]
	v_cvt_pk_bf16_f32 v35, v26, v27
	global_store_dwordx4 v[48:49], v[32:35], off offset:256
	s_nop 1
	v_lshl_add_u64 v[32:33], v[24:25], 0, v[140:141]
	v_cvt_pk_bf16_f32 v24, v36, v37
	v_cvt_pk_bf16_f32 v25, v38, v39
	v_cvt_pk_bf16_f32 v26, v28, v29
	v_cvt_pk_bf16_f32 v27, v30, v31
	global_store_dwordx4 v[32:33], v[24:27], off
	v_cvt_pk_bf16_f32 v16, v16, v17
	v_cvt_pk_bf16_f32 v17, v18, v19
	v_cvt_pk_bf16_f32 v18, v8, v9
	v_add_u32_e32 v8, 0xb0, v148
	v_mad_i64_i32 v[8:9], s[28:29], v8, s2, v[138:139]
	v_cvt_pk_bf16_f32 v19, v10, v11
	global_store_dwordx4 v[32:33], v[16:19], off offset:256
	s_mov_b32 s2, s4
	s_mov_b64 s[28:29], s[8:9]
	v_lshl_add_u64 v[16:17], v[8:9], 0, v[140:141]
	v_cvt_pk_bf16_f32 v8, v20, v21
	v_cvt_pk_bf16_f32 v9, v22, v23
	v_cvt_pk_bf16_f32 v10, v12, v13
	v_cvt_pk_bf16_f32 v11, v14, v15
	global_store_dwordx4 v[16:17], v[8:11], off
	v_cvt_pk_bf16_f32 v4, v4, v5
	v_cvt_pk_bf16_f32 v5, v6, v7
	v_cvt_pk_bf16_f32 v6, v0, v1
	v_cvt_pk_bf16_f32 v7, v2, v3
	global_store_dwordx4 v[16:17], v[4:7], off offset:256
	s_cbranch_vccz .LBB0_1179
	s_waitcnt vmcnt(0)
	s_cmpk_gt_u32 s36, 0xff
	s_cbranch_scc1 .LBB0_1193
	s_barrier

.LBB0_1345:
	s_add_u32 s56, s82, 0xfff80080
	s_addc_u32 s57, s83, -1
	s_add_i32 s30, 0, 0x10000
	v_add_u32_e32 v154, s30, v143
	ds_read_b128 v[138:141], v154
	ds_read_b128 v[146:149], v154 offset:1024
	ds_read_b128 v[150:153], v154 offset:2048
	ds_read_b128 v[154:157], v154 offset:3072
	s_cmp_eq_u32 s94, 28
	s_cselect_b32 s71, s13, s57
	s_cselect_b32 s70, s90, s56
	s_cselect_b32 s69, s7, s93
	s_cselect_b32 s68, s91, s92
	v_lshl_add_u64 v[166:167], s[82:83], 0, v[134:135]
	s_add_i32 m0, s9, 0xc000
	ds_read_b128 v[158:161], v145
	ds_read_b128 v[162:165], v145 offset:1024
	ds_read_b128 v[194:197], v145 offset:2048
	ds_read_b128 v[198:201], v145 offset:3072
	ds_read_b128 v[202:205], v145 offset:4096
	ds_read_b128 v[206:209], v145 offset:5120
	ds_read_b128 v[210:213], v145 offset:6144
	ds_read_b128 v[214:217], v145 offset:7168
	global_load_lds_dwordx4 v[166:167], off
	v_lshl_add_u64 v[166:167], s[82:83], 0, v[136:137]
	s_add_i32 m0, s9, 0xe000
	s_nop 0
	global_load_lds_dwordx4 v[166:167], off
	s_waitcnt lgkmcnt(8)
	s_barrier
	s_waitcnt lgkmcnt(0)
	s_nop 0
	s_waitcnt lgkmcnt(0)
	v_mfma_f32_16x16x32_bf16 v[124:127], v[138:141], v[158:161], v[124:127]
	v_mfma_f32_16x16x32_bf16 v[120:123], v[150:153], v[158:161], v[120:123]
	v_mfma_f32_16x16x32_bf16 v[116:119], v[138:141], v[194:197], v[116:119]
	v_mfma_f32_16x16x32_bf16 v[108:111], v[150:153], v[194:197], v[108:111]
	v_mfma_f32_16x16x32_bf16 v[100:103], v[138:141], v[202:205], v[100:103]
	v_mfma_f32_16x16x32_bf16 v[92:95], v[150:153], v[202:205], v[92:95]
	v_mfma_f32_16x16x32_bf16 v[84:87], v[138:141], v[210:213], v[84:87]
	v_mfma_f32_16x16x32_bf16 v[76:79], v[150:153], v[210:213], v[76:79]
	v_mfma_f32_16x16x32_bf16 v[124:127], v[146:149], v[162:165], v[124:127]
	v_mfma_f32_16x16x32_bf16 v[120:123], v[154:157], v[162:165], v[120:123]
	v_mfma_f32_16x16x32_bf16 v[116:119], v[146:149], v[198:201], v[116:119]
	v_mfma_f32_16x16x32_bf16 v[108:111], v[154:157], v[198:201], v[108:111]
	v_mfma_f32_16x16x32_bf16 v[100:103], v[146:149], v[206:209], v[100:103]
	v_mfma_f32_16x16x32_bf16 v[92:95], v[154:157], v[206:209], v[92:95]
	v_mfma_f32_16x16x32_bf16 v[84:87], v[146:149], v[214:217], v[84:87]
	v_mfma_f32_16x16x32_bf16 v[76:79], v[154:157], v[214:217], v[76:79]
	s_nop 0
	s_barrier
	s_add_i32 s56, 0, 0x14000
	v_add_u32_e32 v166, s56, v143
	s_add_i32 s57, s30, s84
	ds_read_b128 v[218:221], v166
	ds_read_b128 v[222:225], v166 offset:1024
	ds_read_b128 v[226:229], v166 offset:2048
	ds_read_b128 v[230:233], v166 offset:3072
	v_lshl_add_u64 v[166:167], s[68:69], 0, v[168:169]
	s_mov_b32 m0, s57
	v_lshl_add_u64 v[176:177], s[68:69], 0, v[132:133]
	global_load_lds_dwordx4 v[166:167], off
	s_add_i32 m0, s57, 0x2000
	s_nop 0
	global_load_lds_dwordx4 v[176:177], off
	s_barrier
	s_waitcnt lgkmcnt(0)
	s_nop 0
	s_waitcnt lgkmcnt(0)
	v_mfma_f32_16x16x32_bf16 v[112:115], v[218:221], v[158:161], v[112:115]
	v_mfma_f32_16x16x32_bf16 v[104:107], v[226:229], v[158:161], v[104:107]
	v_mfma_f32_16x16x32_bf16 v[96:99], v[218:221], v[194:197], v[96:99]
	v_mfma_f32_16x16x32_bf16 v[88:91], v[226:229], v[194:197], v[88:91]
	v_mfma_f32_16x16x32_bf16 v[80:83], v[218:221], v[202:205], v[80:83]
	v_mfma_f32_16x16x32_bf16 v[72:75], v[226:229], v[202:205], v[72:75]
	v_mfma_f32_16x16x32_bf16 v[68:71], v[218:221], v[210:213], v[68:71]
	v_mfma_f32_16x16x32_bf16 v[64:67], v[226:229], v[210:213], v[64:67]
	v_mfma_f32_16x16x32_bf16 v[112:115], v[222:225], v[162:165], v[112:115]
	v_mfma_f32_16x16x32_bf16 v[104:107], v[230:233], v[162:165], v[104:107]
	v_mfma_f32_16x16x32_bf16 v[96:99], v[222:225], v[198:201], v[96:99]
	v_mfma_f32_16x16x32_bf16 v[88:91], v[230:233], v[198:201], v[88:91]
	v_mfma_f32_16x16x32_bf16 v[80:83], v[222:225], v[206:209], v[80:83]
	v_mfma_f32_16x16x32_bf16 v[72:75], v[230:233], v[206:209], v[72:75]
	v_mfma_f32_16x16x32_bf16 v[68:71], v[222:225], v[214:217], v[68:71]
	v_mfma_f32_16x16x32_bf16 v[64:67], v[230:233], v[214:217], v[64:67]
	s_nop 0
	s_mov_b32 m0, s9
	v_lshl_add_u64 v[234:235], s[70:71], 0, v[128:129]
	s_barrier
	ds_read_b128 v[158:161], v145 offset:16384
	ds_read_b128 v[162:165], v145 offset:17408
	ds_read_b128 v[194:197], v145 offset:18432
	ds_read_b128 v[198:201], v145 offset:19456
	ds_read_b128 v[202:205], v145 offset:20480
	ds_read_b128 v[206:209], v145 offset:21504
	ds_read_b128 v[210:213], v145 offset:22528
	ds_read_b128 v[214:217], v145 offset:23552
	global_load_lds_dwordx4 v[234:235], off
	v_lshl_add_u64 v[236:237], s[70:71], 0, v[130:131]
	s_mov_b32 m0, s15
	s_nop 0
	global_load_lds_dwordx4 v[236:237], off
	s_barrier
	s_waitcnt lgkmcnt(0)
	s_nop 0
	s_waitcnt lgkmcnt(0)
	v_mfma_f32_16x16x32_bf16 v[60:63], v[138:141], v[158:161], v[60:63]
	v_mfma_f32_16x16x32_bf16 v[56:59], v[150:153], v[158:161], v[56:59]
	v_mfma_f32_16x16x32_bf16 v[52:55], v[138:141], v[194:197], v[52:55]
	v_mfma_f32_16x16x32_bf16 v[44:47], v[150:153], v[194:197], v[44:47]
	v_mfma_f32_16x16x32_bf16 v[36:39], v[138:141], v[202:205], v[36:39]
	v_mfma_f32_16x16x32_bf16 v[28:31], v[150:153], v[202:205], v[28:31]
	v_mfma_f32_16x16x32_bf16 v[20:23], v[138:141], v[210:213], v[20:23]
	v_mfma_f32_16x16x32_bf16 v[12:15], v[150:153], v[210:213], v[12:15]
	v_mfma_f32_16x16x32_bf16 v[60:63], v[146:149], v[162:165], v[60:63]
	v_mfma_f32_16x16x32_bf16 v[56:59], v[154:157], v[162:165], v[56:59]
	v_mfma_f32_16x16x32_bf16 v[52:55], v[146:149], v[198:201], v[52:55]
	v_mfma_f32_16x16x32_bf16 v[44:47], v[154:157], v[198:201], v[44:47]
	v_mfma_f32_16x16x32_bf16 v[36:39], v[146:149], v[206:209], v[36:39]
	v_mfma_f32_16x16x32_bf16 v[28:31], v[154:157], v[206:209], v[28:31]
	v_mfma_f32_16x16x32_bf16 v[20:23], v[146:149], v[214:217], v[20:23]
	v_mfma_f32_16x16x32_bf16 v[12:15], v[154:157], v[214:217], v[12:15]
	s_nop 0
	s_barrier
	s_add_u32 s96, s68, 0x80000
	s_addc_u32 s97, s69, 0
	s_add_i32 s57, s56, s84
	v_lshl_add_u64 v[138:139], s[96:97], 0, v[168:169]
	s_mov_b32 m0, s57
	s_nop 0
	global_load_lds_dwordx4 v[138:139], off
	v_lshl_add_u64 v[138:139], s[96:97], 0, v[132:133]
	s_add_i32 m0, s57, 0x2000
	s_nop 0
	global_load_lds_dwordx4 v[138:139], off
	s_waitcnt vmcnt(6)
	s_barrier
	s_nop 0
	v_mfma_f32_16x16x32_bf16 v[48:51], v[218:221], v[158:161], v[48:51]
	v_mfma_f32_16x16x32_bf16 v[40:43], v[226:229], v[158:161], v[40:43]
	v_mfma_f32_16x16x32_bf16 v[32:35], v[218:221], v[194:197], v[32:35]
	v_mfma_f32_16x16x32_bf16 v[24:27], v[226:229], v[194:197], v[24:27]
	v_mfma_f32_16x16x32_bf16 v[16:19], v[218:221], v[202:205], v[16:19]
	v_mfma_f32_16x16x32_bf16 v[8:11], v[226:229], v[202:205], v[8:11]
	v_mfma_f32_16x16x32_bf16 v[4:7], v[218:221], v[210:213], v[4:7]
	v_mfma_f32_16x16x32_bf16 v[0:3], v[226:229], v[210:213], v[0:3]
	v_mfma_f32_16x16x32_bf16 v[48:51], v[222:225], v[162:165], v[48:51]
	v_mfma_f32_16x16x32_bf16 v[40:43], v[230:233], v[162:165], v[40:43]
	v_mfma_f32_16x16x32_bf16 v[32:35], v[222:225], v[198:201], v[32:35]
	v_mfma_f32_16x16x32_bf16 v[24:27], v[230:233], v[198:201], v[24:27]
	v_mfma_f32_16x16x32_bf16 v[16:19], v[222:225], v[206:209], v[16:19]
	v_mfma_f32_16x16x32_bf16 v[8:11], v[230:233], v[206:209], v[8:11]
	v_mfma_f32_16x16x32_bf16 v[4:7], v[222:225], v[214:217], v[4:7]
	v_mfma_f32_16x16x32_bf16 v[0:3], v[230:233], v[214:217], v[0:3]
	s_nop 0
	s_add_i32 s57, 0, 0x18000
	v_add_u32_e32 v154, s57, v143
	s_barrier
	ds_read_b128 v[138:141], v154
	ds_read_b128 v[146:149], v154 offset:1024
	ds_read_b128 v[150:153], v154 offset:2048
	ds_read_b128 v[154:157], v154 offset:3072
	s_add_u32 s70, s70, 0x80000
	s_addc_u32 s71, s71, 0
	s_mov_b32 m0, s85
	v_lshl_add_u64 v[218:219], s[70:71], 0, v[128:129]
	ds_read_b128 v[158:161], v145 offset:32768
	ds_read_b128 v[162:165], v145 offset:33792
	ds_read_b128 v[194:197], v145 offset:34816
	ds_read_b128 v[198:201], v145 offset:35840
	ds_read_b128 v[202:205], v145 offset:36864
	ds_read_b128 v[206:209], v145 offset:37888
	ds_read_b128 v[210:213], v145 offset:38912
	ds_read_b128 v[214:217], v145 offset:39936
	global_load_lds_dwordx4 v[218:219], off
	v_lshl_add_u64 v[218:219], s[70:71], 0, v[130:131]
	s_mov_b32 m0, s86
	s_nop 0
	global_load_lds_dwordx4 v[218:219], off
	s_waitcnt lgkmcnt(8)
	s_barrier
	s_waitcnt lgkmcnt(0)
	s_nop 0
	s_waitcnt lgkmcnt(0)
	v_mfma_f32_16x16x32_bf16 v[124:127], v[138:141], v[158:161], v[124:127]
	v_mfma_f32_16x16x32_bf16 v[120:123], v[150:153], v[158:161], v[120:123]
	v_mfma_f32_16x16x32_bf16 v[116:119], v[138:141], v[194:197], v[116:119]
	v_mfma_f32_16x16x32_bf16 v[108:111], v[150:153], v[194:197], v[108:111]
	v_mfma_f32_16x16x32_bf16 v[100:103], v[138:141], v[202:205], v[100:103]
	v_mfma_f32_16x16x32_bf16 v[92:95], v[150:153], v[202:205], v[92:95]
	v_mfma_f32_16x16x32_bf16 v[84:87], v[138:141], v[210:213], v[84:87]
	v_mfma_f32_16x16x32_bf16 v[76:79], v[150:153], v[210:213], v[76:79]
	v_mfma_f32_16x16x32_bf16 v[124:127], v[146:149], v[162:165], v[124:127]
	v_mfma_f32_16x16x32_bf16 v[120:123], v[154:157], v[162:165], v[120:123]
	v_mfma_f32_16x16x32_bf16 v[116:119], v[146:149], v[198:201], v[116:119]
	v_mfma_f32_16x16x32_bf16 v[108:111], v[154:157], v[198:201], v[108:111]
	v_mfma_f32_16x16x32_bf16 v[100:103], v[146:149], v[206:209], v[100:103]
	v_mfma_f32_16x16x32_bf16 v[92:95], v[154:157], v[206:209], v[92:95]
	v_mfma_f32_16x16x32_bf16 v[84:87], v[146:149], v[214:217], v[84:87]
	v_mfma_f32_16x16x32_bf16 v[76:79], v[154:157], v[214:217], v[76:79]
	s_nop 0
	s_barrier
	s_add_i32 s58, 0, 0x1c000
	s_add_i32 s70, s57, s84
	v_add_u32_e32 v193, s58, v143
	v_lshl_add_u64 v[166:167], v[166:167], 0, s[0:1]
	s_mov_b32 m0, s70
	ds_read_b128 v[218:221], v193
	ds_read_b128 v[222:225], v193 offset:1024
	ds_read_b128 v[226:229], v193 offset:2048
	ds_read_b128 v[230:233], v193 offset:3072
	global_load_lds_dwordx4 v[166:167], off
	v_lshl_add_u64 v[166:167], v[176:177], 0, s[0:1]
	s_add_i32 m0, s70, 0x2000
	s_nop 0
	global_load_lds_dwordx4 v[166:167], off
	s_barrier
	s_waitcnt lgkmcnt(0)
	s_nop 0
	s_waitcnt lgkmcnt(0)
	v_mfma_f32_16x16x32_bf16 v[112:115], v[218:221], v[158:161], v[112:115]
	v_mfma_f32_16x16x32_bf16 v[104:107], v[226:229], v[158:161], v[104:107]
	v_mfma_f32_16x16x32_bf16 v[96:99], v[218:221], v[194:197], v[96:99]
	v_mfma_f32_16x16x32_bf16 v[88:91], v[226:229], v[194:197], v[88:91]
	v_mfma_f32_16x16x32_bf16 v[80:83], v[218:221], v[202:205], v[80:83]
	v_mfma_f32_16x16x32_bf16 v[72:75], v[226:229], v[202:205], v[72:75]
	v_mfma_f32_16x16x32_bf16 v[68:71], v[218:221], v[210:213], v[68:71]
	v_mfma_f32_16x16x32_bf16 v[64:67], v[226:229], v[210:213], v[64:67]
	v_mfma_f32_16x16x32_bf16 v[112:115], v[222:225], v[162:165], v[112:115]
	v_mfma_f32_16x16x32_bf16 v[104:107], v[230:233], v[162:165], v[104:107]
	v_mfma_f32_16x16x32_bf16 v[96:99], v[222:225], v[198:201], v[96:99]
	v_mfma_f32_16x16x32_bf16 v[88:91], v[230:233], v[198:201], v[88:91]
	v_mfma_f32_16x16x32_bf16 v[80:83], v[222:225], v[206:209], v[80:83]
	v_mfma_f32_16x16x32_bf16 v[72:75], v[230:233], v[206:209], v[72:75]
	v_mfma_f32_16x16x32_bf16 v[68:71], v[222:225], v[214:217], v[68:71]
	v_mfma_f32_16x16x32_bf16 v[64:67], v[230:233], v[214:217], v[64:67]
	s_nop 0
	s_mov_b32 m0, s87
	v_lshl_add_u64 v[166:167], v[234:235], 0, s[0:1]
	s_barrier
	ds_read_b128 v[158:161], v145 offset:49152
	ds_read_b128 v[162:165], v145 offset:50176
	ds_read_b128 v[194:197], v145 offset:51200
	ds_read_b128 v[198:201], v145 offset:52224
	ds_read_b128 v[202:205], v145 offset:53248
	ds_read_b128 v[206:209], v145 offset:54272
	ds_read_b128 v[210:213], v145 offset:55296
	ds_read_b128 v[214:217], v145 offset:56320
	global_load_lds_dwordx4 v[166:167], off
	v_lshl_add_u64 v[166:167], v[236:237], 0, s[0:1]
	s_mov_b32 m0, s88
	s_nop 0
	global_load_lds_dwordx4 v[166:167], off
	s_barrier
	s_waitcnt lgkmcnt(0)
	s_nop 0
	s_waitcnt lgkmcnt(0)
	v_mfma_f32_16x16x32_bf16 v[60:63], v[138:141], v[158:161], v[60:63]
	v_mfma_f32_16x16x32_bf16 v[56:59], v[150:153], v[158:161], v[56:59]
	v_mfma_f32_16x16x32_bf16 v[52:55], v[138:141], v[194:197], v[52:55]
	v_mfma_f32_16x16x32_bf16 v[44:47], v[150:153], v[194:197], v[44:47]
	v_mfma_f32_16x16x32_bf16 v[36:39], v[138:141], v[202:205], v[36:39]
	v_mfma_f32_16x16x32_bf16 v[28:31], v[150:153], v[202:205], v[28:31]
	v_mfma_f32_16x16x32_bf16 v[20:23], v[138:141], v[210:213], v[20:23]
	v_mfma_f32_16x16x32_bf16 v[12:15], v[150:153], v[210:213], v[12:15]
	v_mfma_f32_16x16x32_bf16 v[60:63], v[146:149], v[162:165], v[60:63]
	v_mfma_f32_16x16x32_bf16 v[56:59], v[154:157], v[162:165], v[56:59]
	v_mfma_f32_16x16x32_bf16 v[52:55], v[146:149], v[198:201], v[52:55]
	v_mfma_f32_16x16x32_bf16 v[44:47], v[154:157], v[198:201], v[44:47]
	v_mfma_f32_16x16x32_bf16 v[36:39], v[146:149], v[206:209], v[36:39]
	v_mfma_f32_16x16x32_bf16 v[28:31], v[154:157], v[206:209], v[28:31]
	v_mfma_f32_16x16x32_bf16 v[20:23], v[146:149], v[214:217], v[20:23]
	v_mfma_f32_16x16x32_bf16 v[12:15], v[154:157], v[214:217], v[12:15]
	s_nop 0
	s_barrier
	s_add_u32 s68, s68, 0x80080
	s_addc_u32 s69, s69, 0
	s_add_i32 s70, s58, s84
	v_lshl_add_u64 v[138:139], s[68:69], 0, v[168:169]
	s_mov_b32 m0, s70
	s_nop 0
	global_load_lds_dwordx4 v[138:139], off
	v_lshl_add_u64 v[138:139], s[68:69], 0, v[132:133]
	s_add_i32 m0, s70, 0x2000
	s_nop 0
	global_load_lds_dwordx4 v[138:139], off
	s_waitcnt vmcnt(6)
	s_barrier
	s_nop 0
	v_mfma_f32_16x16x32_bf16 v[48:51], v[218:221], v[158:161], v[48:51]
	v_mfma_f32_16x16x32_bf16 v[40:43], v[226:229], v[158:161], v[40:43]
	v_mfma_f32_16x16x32_bf16 v[32:35], v[218:221], v[194:197], v[32:35]
	v_mfma_f32_16x16x32_bf16 v[24:27], v[226:229], v[194:197], v[24:27]
	v_mfma_f32_16x16x32_bf16 v[16:19], v[218:221], v[202:205], v[16:19]
	v_mfma_f32_16x16x32_bf16 v[8:11], v[226:229], v[202:205], v[8:11]
	v_mfma_f32_16x16x32_bf16 v[4:7], v[218:221], v[210:213], v[4:7]
	v_mfma_f32_16x16x32_bf16 v[0:3], v[226:229], v[210:213], v[0:3]
	v_mfma_f32_16x16x32_bf16 v[48:51], v[222:225], v[162:165], v[48:51]
	v_mfma_f32_16x16x32_bf16 v[40:43], v[230:233], v[162:165], v[40:43]
	v_mfma_f32_16x16x32_bf16 v[32:35], v[222:225], v[198:201], v[32:35]
	v_mfma_f32_16x16x32_bf16 v[24:27], v[230:233], v[198:201], v[24:27]
	v_mfma_f32_16x16x32_bf16 v[16:19], v[222:225], v[206:209], v[16:19]
	v_mfma_f32_16x16x32_bf16 v[8:11], v[230:233], v[206:209], v[8:11]
	v_mfma_f32_16x16x32_bf16 v[4:7], v[222:225], v[214:217], v[4:7]
	v_mfma_f32_16x16x32_bf16 v[0:3], v[230:233], v[214:217], v[0:3]
	s_nop 0
	s_add_i32 s94, s94, 2
	s_add_u32 s82, s82, 0x100
	s_addc_u32 s83, s83, 0
	s_add_u32 s92, s92, 0x100
	s_addc_u32 s93, s93, 0
	s_cmp_gt_u32 s94, 29
	s_barrier
	s_cbranch_scc0 .LBB0_1345
	v_readlane_b32 s94, v239, 44
	v_lshl_or_b32 v140, s8, 8, v144
	v_readlane_b32 s95, v239, 45
	v_lshl_add_u32 v148, s14, 8, v142
	v_ashrrev_i32_e32 v141, 31, v140
	v_mov_b64_e32 v[138:139], s[94:95]
	s_movk_i32 s7, 0x5600
	v_mad_i64_i32 v[146:147], s[68:69], v148, s7, v[138:139]
	v_lshlrev_b64 v[140:141], 1, v[140:141]
	v_lshl_add_u64 v[146:147], v[146:147], 0, v[140:141]
	v_cvt_pk_bf16_f32 v124, v124, v125
	v_cvt_pk_bf16_f32 v125, v126, v127
	v_cvt_pk_bf16_f32 v126, v120, v121
	v_cvt_pk_bf16_f32 v127, v122, v123
	global_store_dwordx4 v[146:147], v[124:127], off
	v_cvt_pk_bf16_f32 v112, v112, v113
	v_cvt_pk_bf16_f32 v113, v114, v115
	v_cvt_pk_bf16_f32 v114, v104, v105
	v_or_b32_e32 v104, 16, v148
	v_mad_i64_i32 v[104:105], s[68:69], v104, s7, v[138:139]
	v_cvt_pk_bf16_f32 v115, v106, v107
	global_store_dwordx4 v[146:147], v[112:115], off offset:256
	s_and_b64 vcc, exec, s[4:5]
	s_mov_b32 s8, s6
	v_lshl_add_u64 v[112:113], v[104:105], 0, v[140:141]
	v_cvt_pk_bf16_f32 v104, v116, v117
	v_cvt_pk_bf16_f32 v105, v118, v119
	v_cvt_pk_bf16_f32 v106, v108, v109
	v_cvt_pk_bf16_f32 v107, v110, v111
	global_store_dwordx4 v[112:113], v[104:107], off
	v_cvt_pk_bf16_f32 v96, v96, v97
	v_cvt_pk_bf16_f32 v97, v98, v99
	v_cvt_pk_bf16_f32 v98, v88, v89
	v_or_b32_e32 v88, 32, v148
	v_mad_i64_i32 v[88:89], s[68:69], v88, s7, v[138:139]
	v_cvt_pk_bf16_f32 v99, v90, v91
	global_store_dwordx4 v[112:113], v[96:99], off offset:256
	s_mov_b32 s14, s12
	s_mov_b64 s[70:71], s[28:29]
	v_lshl_add_u64 v[96:97], v[88:89], 0, v[140:141]
	v_cvt_pk_bf16_f32 v88, v100, v101
	v_cvt_pk_bf16_f32 v89, v102, v103
	v_cvt_pk_bf16_f32 v90, v92, v93
	v_cvt_pk_bf16_f32 v91, v94, v95
	global_store_dwordx4 v[96:97], v[88:91], off
	v_cvt_pk_bf16_f32 v80, v80, v81
	v_cvt_pk_bf16_f32 v81, v82, v83
	v_cvt_pk_bf16_f32 v82, v72, v73
	v_or_b32_e32 v72, 48, v148
	v_mad_i64_i32 v[72:73], s[68:69], v72, s7, v[138:139]
	v_cvt_pk_bf16_f32 v83, v74, v75
	global_store_dwordx4 v[96:97], v[80:83], off offset:256
	s_nop 1
	v_lshl_add_u64 v[80:81], v[72:73], 0, v[140:141]
	v_cvt_pk_bf16_f32 v72, v84, v85
	v_cvt_pk_bf16_f32 v73, v86, v87
	v_cvt_pk_bf16_f32 v74, v76, v77
	v_cvt_pk_bf16_f32 v75, v78, v79
	global_store_dwordx4 v[80:81], v[72:75], off
	v_cvt_pk_bf16_f32 v68, v68, v69
	v_cvt_pk_bf16_f32 v69, v70, v71
	v_cvt_pk_bf16_f32 v70, v64, v65
	v_add_u32_e32 v64, 0x80, v148
	v_mad_i64_i32 v[64:65], s[68:69], v64, s7, v[138:139]
	v_lshl_add_u64 v[64:65], v[64:65], 0, v[140:141]
	v_cvt_pk_bf16_f32 v71, v66, v67
	global_store_dwordx4 v[80:81], v[68:71], off offset:256
	v_cvt_pk_bf16_f32 v60, v60, v61
	v_cvt_pk_bf16_f32 v61, v62, v63
	v_cvt_pk_bf16_f32 v62, v56, v57
	v_cvt_pk_bf16_f32 v63, v58, v59
	global_store_dwordx4 v[64:65], v[60:63], off
	v_cvt_pk_bf16_f32 v48, v48, v49
	v_cvt_pk_bf16_f32 v49, v50, v51
	v_cvt_pk_bf16_f32 v50, v40, v41
	v_add_u32_e32 v40, 0x90, v148
	v_mad_i64_i32 v[40:41], s[68:69], v40, s7, v[138:139]
	v_cvt_pk_bf16_f32 v51, v42, v43
	global_store_dwordx4 v[64:65], v[48:51], off offset:256
	s_nop 1
	v_lshl_add_u64 v[48:49], v[40:41], 0, v[140:141]
	v_cvt_pk_bf16_f32 v40, v52, v53
	v_cvt_pk_bf16_f32 v41, v54, v55
	v_cvt_pk_bf16_f32 v42, v44, v45
	v_cvt_pk_bf16_f32 v43, v46, v47
	global_store_dwordx4 v[48:49], v[40:43], off
	v_cvt_pk_bf16_f32 v32, v32, v33
	v_cvt_pk_bf16_f32 v33, v34, v35
	v_cvt_pk_bf16_f32 v34, v24, v25
	v_add_u32_e32 v24, 0xa0, v148
	v_mad_i64_i32 v[24:25], s[68:69], v24, s7, v[138:139]
	v_cvt_pk_bf16_f32 v35, v26, v27
	global_store_dwordx4 v[48:49], v[32:35], off offset:256
	s_nop 1
	v_lshl_add_u64 v[32:33], v[24:25], 0, v[140:141]
	v_cvt_pk_bf16_f32 v24, v36, v37
	v_cvt_pk_bf16_f32 v25, v38, v39
	v_cvt_pk_bf16_f32 v26, v28, v29
	v_cvt_pk_bf16_f32 v27, v30, v31
	global_store_dwordx4 v[32:33], v[24:27], off
	v_cvt_pk_bf16_f32 v16, v16, v17
	v_cvt_pk_bf16_f32 v17, v18, v19
	v_cvt_pk_bf16_f32 v18, v8, v9
	v_add_u32_e32 v8, 0xb0, v148
	v_mad_i64_i32 v[8:9], s[68:69], v8, s7, v[138:139]
	v_cvt_pk_bf16_f32 v19, v10, v11
	global_store_dwordx4 v[32:33], v[16:19], off offset:256
	s_mov_b64 s[68:69], s[78:79]
	s_nop 0
	v_lshl_add_u64 v[16:17], v[8:9], 0, v[140:141]
	v_cvt_pk_bf16_f32 v8, v20, v21
	v_cvt_pk_bf16_f32 v9, v22, v23
	v_cvt_pk_bf16_f32 v10, v12, v13
	v_cvt_pk_bf16_f32 v11, v14, v15
	global_store_dwordx4 v[16:17], v[8:11], off
	v_cvt_pk_bf16_f32 v4, v4, v5
	v_cvt_pk_bf16_f32 v5, v6, v7
	v_cvt_pk_bf16_f32 v6, v0, v1
	v_cvt_pk_bf16_f32 v7, v2, v3
	global_store_dwordx4 v[16:17], v[4:7], off offset:256
	s_cbranch_vccz .LBB0_1342
	s_waitcnt vmcnt(0)
	s_cmpk_gt_u32 s73, 0xff
	s_cbranch_scc1 .LBB0_1349
	s_barrier

.LBB0_1415:
	v_add_u32_e32 v154, s30, v140
	ds_read_b128 v[142:145], v154
	ds_read_b128 v[146:149], v154 offset:1024
	ds_read_b128 v[150:153], v154 offset:2048
	ds_read_b128 v[154:157], v154 offset:3072
	s_add_i32 s14, s12, 0xf3880080
	s_cmp_lg_u32 s79, 28
	s_cselect_b32 s14, s14, 0
	s_add_u32 s28, s8, s14
	s_addc_u32 s29, s9, 0
	s_add_u32 s14, s6, s14
	s_addc_u32 s15, s7, 0
	v_lshl_add_u64 v[166:167], v[134:135], 0, s[12:13]
	s_add_i32 m0, s5, 0xc000
	ds_read_b128 v[158:161], v141
	ds_read_b128 v[162:165], v141 offset:1024
	ds_read_b128 v[194:197], v141 offset:2048
	ds_read_b128 v[198:201], v141 offset:3072
	ds_read_b128 v[202:205], v141 offset:4096
	ds_read_b128 v[206:209], v141 offset:5120
	ds_read_b128 v[210:213], v141 offset:6144
	ds_read_b128 v[214:217], v141 offset:7168
	global_load_lds_dwordx4 v[166:167], off
	v_lshl_add_u64 v[166:167], v[136:137], 0, s[12:13]
	s_add_i32 m0, s5, 0xe000
	s_nop 0
	global_load_lds_dwordx4 v[166:167], off
	s_waitcnt lgkmcnt(8)
	s_barrier
	s_waitcnt lgkmcnt(0)
	s_nop 0
	s_waitcnt lgkmcnt(0)
	v_mfma_f32_16x16x32_bf16 v[124:127], v[142:145], v[158:161], v[124:127]
	v_mfma_f32_16x16x32_bf16 v[120:123], v[150:153], v[158:161], v[120:123]
	v_mfma_f32_16x16x32_bf16 v[116:119], v[142:145], v[194:197], v[116:119]
	v_mfma_f32_16x16x32_bf16 v[108:111], v[150:153], v[194:197], v[108:111]
	v_mfma_f32_16x16x32_bf16 v[100:103], v[142:145], v[202:205], v[100:103]
	v_mfma_f32_16x16x32_bf16 v[92:95], v[150:153], v[202:205], v[92:95]
	v_mfma_f32_16x16x32_bf16 v[84:87], v[142:145], v[210:213], v[84:87]
	v_mfma_f32_16x16x32_bf16 v[76:79], v[150:153], v[210:213], v[76:79]
	v_mfma_f32_16x16x32_bf16 v[124:127], v[146:149], v[162:165], v[124:127]
	v_mfma_f32_16x16x32_bf16 v[120:123], v[154:157], v[162:165], v[120:123]
	v_mfma_f32_16x16x32_bf16 v[116:119], v[146:149], v[198:201], v[116:119]
	v_mfma_f32_16x16x32_bf16 v[108:111], v[154:157], v[198:201], v[108:111]
	v_mfma_f32_16x16x32_bf16 v[100:103], v[146:149], v[206:209], v[100:103]
	v_mfma_f32_16x16x32_bf16 v[92:95], v[154:157], v[206:209], v[92:95]
	v_mfma_f32_16x16x32_bf16 v[84:87], v[146:149], v[214:217], v[84:87]
	v_mfma_f32_16x16x32_bf16 v[76:79], v[154:157], v[214:217], v[76:79]
	s_nop 0
	s_barrier
	v_add_u32_e32 v166, s56, v140
	s_add_i32 s82, s30, s68
	ds_read_b128 v[218:221], v166
	ds_read_b128 v[222:225], v166 offset:1024
	ds_read_b128 v[226:229], v166 offset:2048
	ds_read_b128 v[230:233], v166 offset:3072
	v_lshl_add_u64 v[166:167], s[14:15], 0, v[168:169]
	s_mov_b32 m0, s82
	v_lshl_add_u64 v[176:177], s[14:15], 0, v[132:133]
	global_load_lds_dwordx4 v[166:167], off
	s_add_i32 m0, s82, 0x2000
	s_nop 0
	global_load_lds_dwordx4 v[176:177], off
	s_barrier
	s_waitcnt lgkmcnt(0)
	s_nop 0
	s_waitcnt lgkmcnt(0)
	v_mfma_f32_16x16x32_bf16 v[112:115], v[218:221], v[158:161], v[112:115]
	v_mfma_f32_16x16x32_bf16 v[104:107], v[226:229], v[158:161], v[104:107]
	v_mfma_f32_16x16x32_bf16 v[96:99], v[218:221], v[194:197], v[96:99]
	v_mfma_f32_16x16x32_bf16 v[88:91], v[226:229], v[194:197], v[88:91]
	v_mfma_f32_16x16x32_bf16 v[80:83], v[218:221], v[202:205], v[80:83]
	v_mfma_f32_16x16x32_bf16 v[72:75], v[226:229], v[202:205], v[72:75]
	v_mfma_f32_16x16x32_bf16 v[68:71], v[218:221], v[210:213], v[68:71]
	v_mfma_f32_16x16x32_bf16 v[64:67], v[226:229], v[210:213], v[64:67]
	v_mfma_f32_16x16x32_bf16 v[112:115], v[222:225], v[162:165], v[112:115]
	v_mfma_f32_16x16x32_bf16 v[104:107], v[230:233], v[162:165], v[104:107]
	v_mfma_f32_16x16x32_bf16 v[96:99], v[222:225], v[198:201], v[96:99]
	v_mfma_f32_16x16x32_bf16 v[88:91], v[230:233], v[198:201], v[88:91]
	v_mfma_f32_16x16x32_bf16 v[80:83], v[222:225], v[206:209], v[80:83]
	v_mfma_f32_16x16x32_bf16 v[72:75], v[230:233], v[206:209], v[72:75]
	v_mfma_f32_16x16x32_bf16 v[68:71], v[222:225], v[214:217], v[68:71]
	v_mfma_f32_16x16x32_bf16 v[64:67], v[230:233], v[214:217], v[64:67]
	s_nop 0
	s_mov_b32 m0, s5
	v_lshl_add_u64 v[234:235], s[28:29], 0, v[128:129]
	s_barrier
	ds_read_b128 v[158:161], v141 offset:16384
	ds_read_b128 v[162:165], v141 offset:17408
	ds_read_b128 v[194:197], v141 offset:18432
	ds_read_b128 v[198:201], v141 offset:19456
	ds_read_b128 v[202:205], v141 offset:20480
	ds_read_b128 v[206:209], v141 offset:21504
	ds_read_b128 v[210:213], v141 offset:22528
	ds_read_b128 v[214:217], v141 offset:23552
	global_load_lds_dwordx4 v[234:235], off
	v_lshl_add_u64 v[236:237], s[28:29], 0, v[130:131]
	s_mov_b32 m0, s69
	s_nop 0
	global_load_lds_dwordx4 v[236:237], off
	s_barrier
	s_waitcnt lgkmcnt(0)
	s_nop 0
	s_waitcnt lgkmcnt(0)
	v_mfma_f32_16x16x32_bf16 v[60:63], v[142:145], v[158:161], v[60:63]
	v_mfma_f32_16x16x32_bf16 v[56:59], v[150:153], v[158:161], v[56:59]
	v_mfma_f32_16x16x32_bf16 v[52:55], v[142:145], v[194:197], v[52:55]
	v_mfma_f32_16x16x32_bf16 v[44:47], v[150:153], v[194:197], v[44:47]
	v_mfma_f32_16x16x32_bf16 v[36:39], v[142:145], v[202:205], v[36:39]
	v_mfma_f32_16x16x32_bf16 v[28:31], v[150:153], v[202:205], v[28:31]
	v_mfma_f32_16x16x32_bf16 v[20:23], v[142:145], v[210:213], v[20:23]
	v_mfma_f32_16x16x32_bf16 v[12:15], v[150:153], v[210:213], v[12:15]
	v_mfma_f32_16x16x32_bf16 v[60:63], v[146:149], v[162:165], v[60:63]
	v_mfma_f32_16x16x32_bf16 v[56:59], v[154:157], v[162:165], v[56:59]
	v_mfma_f32_16x16x32_bf16 v[52:55], v[146:149], v[198:201], v[52:55]
	v_mfma_f32_16x16x32_bf16 v[44:47], v[154:157], v[198:201], v[44:47]
	v_mfma_f32_16x16x32_bf16 v[36:39], v[146:149], v[206:209], v[36:39]
	v_mfma_f32_16x16x32_bf16 v[28:31], v[154:157], v[206:209], v[28:31]
	v_mfma_f32_16x16x32_bf16 v[20:23], v[146:149], v[214:217], v[20:23]
	v_mfma_f32_16x16x32_bf16 v[12:15], v[154:157], v[214:217], v[12:15]
	s_nop 0
	s_barrier
	s_add_u32 s82, s14, 0x80000
	s_addc_u32 s83, s15, 0
	s_add_i32 s84, s56, s68
	v_lshl_add_u64 v[142:143], s[82:83], 0, v[168:169]
	s_mov_b32 m0, s84
	s_nop 0
	global_load_lds_dwordx4 v[142:143], off
	v_lshl_add_u64 v[142:143], s[82:83], 0, v[132:133]
	s_add_i32 m0, s84, 0x2000
	s_nop 0
	global_load_lds_dwordx4 v[142:143], off
	s_waitcnt vmcnt(6)
	s_barrier
	s_nop 0
	v_mfma_f32_16x16x32_bf16 v[48:51], v[218:221], v[158:161], v[48:51]
	v_mfma_f32_16x16x32_bf16 v[40:43], v[226:229], v[158:161], v[40:43]
	v_mfma_f32_16x16x32_bf16 v[32:35], v[218:221], v[194:197], v[32:35]
	v_mfma_f32_16x16x32_bf16 v[24:27], v[226:229], v[194:197], v[24:27]
	v_mfma_f32_16x16x32_bf16 v[16:19], v[218:221], v[202:205], v[16:19]
	v_mfma_f32_16x16x32_bf16 v[8:11], v[226:229], v[202:205], v[8:11]
	v_mfma_f32_16x16x32_bf16 v[4:7], v[218:221], v[210:213], v[4:7]
	v_mfma_f32_16x16x32_bf16 v[0:3], v[226:229], v[210:213], v[0:3]
	v_mfma_f32_16x16x32_bf16 v[48:51], v[222:225], v[162:165], v[48:51]
	v_mfma_f32_16x16x32_bf16 v[40:43], v[230:233], v[162:165], v[40:43]
	v_mfma_f32_16x16x32_bf16 v[32:35], v[222:225], v[198:201], v[32:35]
	v_mfma_f32_16x16x32_bf16 v[24:27], v[230:233], v[198:201], v[24:27]
	v_mfma_f32_16x16x32_bf16 v[16:19], v[222:225], v[206:209], v[16:19]
	v_mfma_f32_16x16x32_bf16 v[8:11], v[230:233], v[206:209], v[8:11]
	v_mfma_f32_16x16x32_bf16 v[4:7], v[222:225], v[214:217], v[4:7]
	v_mfma_f32_16x16x32_bf16 v[0:3], v[230:233], v[214:217], v[0:3]
	s_nop 0
	v_add_u32_e32 v154, s57, v140
	s_barrier
	ds_read_b128 v[142:145], v154
	ds_read_b128 v[146:149], v154 offset:1024
	ds_read_b128 v[150:153], v154 offset:2048
	ds_read_b128 v[154:157], v154 offset:3072
	s_add_u32 s28, s28, 0x80000
	s_addc_u32 s29, s29, 0
	s_mov_b32 m0, s70
	v_lshl_add_u64 v[218:219], s[28:29], 0, v[128:129]
	ds_read_b128 v[158:161], v141 offset:32768
	ds_read_b128 v[162:165], v141 offset:33792
	ds_read_b128 v[194:197], v141 offset:34816
	ds_read_b128 v[198:201], v141 offset:35840
	ds_read_b128 v[202:205], v141 offset:36864
	ds_read_b128 v[206:209], v141 offset:37888
	ds_read_b128 v[210:213], v141 offset:38912
	ds_read_b128 v[214:217], v141 offset:39936
	global_load_lds_dwordx4 v[218:219], off
	v_lshl_add_u64 v[218:219], s[28:29], 0, v[130:131]
	s_mov_b32 m0, s71
	s_nop 0
	global_load_lds_dwordx4 v[218:219], off
	s_waitcnt lgkmcnt(8)
	s_barrier
	s_waitcnt lgkmcnt(0)
	s_nop 0
	s_waitcnt lgkmcnt(0)
	v_mfma_f32_16x16x32_bf16 v[124:127], v[142:145], v[158:161], v[124:127]
	v_mfma_f32_16x16x32_bf16 v[120:123], v[150:153], v[158:161], v[120:123]
	v_mfma_f32_16x16x32_bf16 v[116:119], v[142:145], v[194:197], v[116:119]
	v_mfma_f32_16x16x32_bf16 v[108:111], v[150:153], v[194:197], v[108:111]
	v_mfma_f32_16x16x32_bf16 v[100:103], v[142:145], v[202:205], v[100:103]
	v_mfma_f32_16x16x32_bf16 v[92:95], v[150:153], v[202:205], v[92:95]
	v_mfma_f32_16x16x32_bf16 v[84:87], v[142:145], v[210:213], v[84:87]
	v_mfma_f32_16x16x32_bf16 v[76:79], v[150:153], v[210:213], v[76:79]
	v_mfma_f32_16x16x32_bf16 v[124:127], v[146:149], v[162:165], v[124:127]
	v_mfma_f32_16x16x32_bf16 v[120:123], v[154:157], v[162:165], v[120:123]
	v_mfma_f32_16x16x32_bf16 v[116:119], v[146:149], v[198:201], v[116:119]
	v_mfma_f32_16x16x32_bf16 v[108:111], v[154:157], v[198:201], v[108:111]
	v_mfma_f32_16x16x32_bf16 v[100:103], v[146:149], v[206:209], v[100:103]
	v_mfma_f32_16x16x32_bf16 v[92:95], v[154:157], v[206:209], v[92:95]
	v_mfma_f32_16x16x32_bf16 v[84:87], v[146:149], v[214:217], v[84:87]
	v_mfma_f32_16x16x32_bf16 v[76:79], v[154:157], v[214:217], v[76:79]
	s_nop 0
	s_barrier
	s_add_i32 s28, s57, s68
	v_add_u32_e32 v193, s58, v140
	v_lshl_add_u64 v[166:167], v[166:167], 0, s[0:1]
	s_mov_b32 m0, s28
	ds_read_b128 v[218:221], v193
	ds_read_b128 v[222:225], v193 offset:1024
	ds_read_b128 v[226:229], v193 offset:2048
	ds_read_b128 v[230:233], v193 offset:3072
	global_load_lds_dwordx4 v[166:167], off
	v_lshl_add_u64 v[166:167], v[176:177], 0, s[0:1]
	s_add_i32 m0, s28, 0x2000
	s_nop 0
	global_load_lds_dwordx4 v[166:167], off
	s_barrier
	s_waitcnt lgkmcnt(0)
	s_nop 0
	s_waitcnt lgkmcnt(0)
	v_mfma_f32_16x16x32_bf16 v[112:115], v[218:221], v[158:161], v[112:115]
	v_mfma_f32_16x16x32_bf16 v[104:107], v[226:229], v[158:161], v[104:107]
	v_mfma_f32_16x16x32_bf16 v[96:99], v[218:221], v[194:197], v[96:99]
	v_mfma_f32_16x16x32_bf16 v[88:91], v[226:229], v[194:197], v[88:91]
	v_mfma_f32_16x16x32_bf16 v[80:83], v[218:221], v[202:205], v[80:83]
	v_mfma_f32_16x16x32_bf16 v[72:75], v[226:229], v[202:205], v[72:75]
	v_mfma_f32_16x16x32_bf16 v[68:71], v[218:221], v[210:213], v[68:71]
	v_mfma_f32_16x16x32_bf16 v[64:67], v[226:229], v[210:213], v[64:67]
	v_mfma_f32_16x16x32_bf16 v[112:115], v[222:225], v[162:165], v[112:115]
	v_mfma_f32_16x16x32_bf16 v[104:107], v[230:233], v[162:165], v[104:107]
	v_mfma_f32_16x16x32_bf16 v[96:99], v[222:225], v[198:201], v[96:99]
	v_mfma_f32_16x16x32_bf16 v[88:91], v[230:233], v[198:201], v[88:91]
	v_mfma_f32_16x16x32_bf16 v[80:83], v[222:225], v[206:209], v[80:83]
	v_mfma_f32_16x16x32_bf16 v[72:75], v[230:233], v[206:209], v[72:75]
	v_mfma_f32_16x16x32_bf16 v[68:71], v[222:225], v[214:217], v[68:71]
	v_mfma_f32_16x16x32_bf16 v[64:67], v[230:233], v[214:217], v[64:67]
	s_nop 0
	s_mov_b32 m0, s73
	v_lshl_add_u64 v[166:167], v[234:235], 0, s[0:1]
	s_barrier
	ds_read_b128 v[158:161], v141 offset:49152
	ds_read_b128 v[162:165], v141 offset:50176
	ds_read_b128 v[194:197], v141 offset:51200
	ds_read_b128 v[198:201], v141 offset:52224
	ds_read_b128 v[202:205], v141 offset:53248
	ds_read_b128 v[206:209], v141 offset:54272
	ds_read_b128 v[210:213], v141 offset:55296
	ds_read_b128 v[214:217], v141 offset:56320
	global_load_lds_dwordx4 v[166:167], off
	v_lshl_add_u64 v[166:167], v[236:237], 0, s[0:1]
	s_mov_b32 m0, s78
	s_nop 0
	global_load_lds_dwordx4 v[166:167], off
	s_barrier
	s_waitcnt lgkmcnt(0)
	s_nop 0
	s_waitcnt lgkmcnt(0)
	v_mfma_f32_16x16x32_bf16 v[60:63], v[142:145], v[158:161], v[60:63]
	v_mfma_f32_16x16x32_bf16 v[56:59], v[150:153], v[158:161], v[56:59]
	v_mfma_f32_16x16x32_bf16 v[52:55], v[142:145], v[194:197], v[52:55]
	v_mfma_f32_16x16x32_bf16 v[44:47], v[150:153], v[194:197], v[44:47]
	v_mfma_f32_16x16x32_bf16 v[36:39], v[142:145], v[202:205], v[36:39]
	v_mfma_f32_16x16x32_bf16 v[28:31], v[150:153], v[202:205], v[28:31]
	v_mfma_f32_16x16x32_bf16 v[20:23], v[142:145], v[210:213], v[20:23]
	v_mfma_f32_16x16x32_bf16 v[12:15], v[150:153], v[210:213], v[12:15]
	v_mfma_f32_16x16x32_bf16 v[60:63], v[146:149], v[162:165], v[60:63]
	v_mfma_f32_16x16x32_bf16 v[56:59], v[154:157], v[162:165], v[56:59]
	v_mfma_f32_16x16x32_bf16 v[52:55], v[146:149], v[198:201], v[52:55]
	v_mfma_f32_16x16x32_bf16 v[44:47], v[154:157], v[198:201], v[44:47]
	v_mfma_f32_16x16x32_bf16 v[36:39], v[146:149], v[206:209], v[36:39]
	v_mfma_f32_16x16x32_bf16 v[28:31], v[154:157], v[206:209], v[28:31]
	v_mfma_f32_16x16x32_bf16 v[20:23], v[146:149], v[214:217], v[20:23]
	v_mfma_f32_16x16x32_bf16 v[12:15], v[154:157], v[214:217], v[12:15]
	s_nop 0
	s_barrier
	s_add_u32 s14, s14, 0x80080
	s_addc_u32 s15, s15, 0
	s_add_i32 s28, s58, s68
	v_lshl_add_u64 v[142:143], s[14:15], 0, v[168:169]
	s_mov_b32 m0, s28
	s_nop 0
	global_load_lds_dwordx4 v[142:143], off
	v_lshl_add_u64 v[142:143], s[14:15], 0, v[132:133]
	s_add_i32 m0, s28, 0x2000
	s_nop 0
	global_load_lds_dwordx4 v[142:143], off
	s_waitcnt vmcnt(6)
	s_barrier
	s_nop 0
	v_mfma_f32_16x16x32_bf16 v[48:51], v[218:221], v[158:161], v[48:51]
	v_mfma_f32_16x16x32_bf16 v[40:43], v[226:229], v[158:161], v[40:43]
	v_mfma_f32_16x16x32_bf16 v[32:35], v[218:221], v[194:197], v[32:35]
	v_mfma_f32_16x16x32_bf16 v[24:27], v[226:229], v[194:197], v[24:27]
	v_mfma_f32_16x16x32_bf16 v[16:19], v[218:221], v[202:205], v[16:19]
	v_mfma_f32_16x16x32_bf16 v[8:11], v[226:229], v[202:205], v[8:11]
	v_mfma_f32_16x16x32_bf16 v[4:7], v[218:221], v[210:213], v[4:7]
	v_mfma_f32_16x16x32_bf16 v[0:3], v[226:229], v[210:213], v[0:3]
	v_mfma_f32_16x16x32_bf16 v[48:51], v[222:225], v[162:165], v[48:51]
	v_mfma_f32_16x16x32_bf16 v[40:43], v[230:233], v[162:165], v[40:43]
	v_mfma_f32_16x16x32_bf16 v[32:35], v[222:225], v[198:201], v[32:35]
	v_mfma_f32_16x16x32_bf16 v[24:27], v[230:233], v[198:201], v[24:27]
	v_mfma_f32_16x16x32_bf16 v[16:19], v[222:225], v[206:209], v[16:19]
	v_mfma_f32_16x16x32_bf16 v[8:11], v[230:233], v[206:209], v[8:11]
	v_mfma_f32_16x16x32_bf16 v[4:7], v[222:225], v[214:217], v[4:7]
	v_mfma_f32_16x16x32_bf16 v[0:3], v[230:233], v[214:217], v[0:3]
	s_nop 0
	s_add_i32 s79, s79, 2
	s_add_u32 s12, s12, 0x100
	s_addc_u32 s13, s13, 0
	s_cmp_gt_u32 s79, 29
	s_barrier
	s_cbranch_scc0 .LBB0_1415
	s_sext_i32_i16 s2, s2
	s_lshl_b32 s2, s2, 8
	s_or_b32 s2, s2, s72
	v_or_b32_e32 v130, s2, v138
	v_lshl_add_u32 v134, s4, 8, v139
	v_ashrrev_i32_e32 v131, 31, v130
	v_mov_b64_e32 v[128:129], s[94:95]
	s_movk_i32 s40, 0x5600
	v_mad_i64_i32 v[132:133], s[4:5], v134, s40, v[128:129]
	v_lshlrev_b64 v[130:131], 1, v[130:131]
	v_lshl_add_u64 v[132:133], v[132:133], 0, v[130:131]
	v_cvt_pk_bf16_f32 v124, v124, v125
	v_cvt_pk_bf16_f32 v125, v126, v127
	v_cvt_pk_bf16_f32 v126, v120, v121
	v_cvt_pk_bf16_f32 v127, v122, v123
	global_store_dwordx4 v[132:133], v[124:127], off
	v_cvt_pk_bf16_f32 v112, v112, v113
	v_cvt_pk_bf16_f32 v113, v114, v115
	v_cvt_pk_bf16_f32 v114, v104, v105
	v_or_b32_e32 v104, 16, v134
	v_mad_i64_i32 v[104:105], s[4:5], v104, s40, v[128:129]
	v_cvt_pk_bf16_f32 v115, v106, v107
	global_store_dwordx4 v[132:133], v[112:115], off offset:256
	s_cmpk_lt_u32 s3, 0x100
	s_mov_b32 s39, 0x2fa0be83
	v_lshl_add_u64 v[112:113], v[104:105], 0, v[130:131]
	v_cvt_pk_bf16_f32 v104, v116, v117
	v_cvt_pk_bf16_f32 v105, v118, v119
	v_cvt_pk_bf16_f32 v106, v108, v109
	v_cvt_pk_bf16_f32 v107, v110, v111
	global_store_dwordx4 v[112:113], v[104:107], off
	v_cvt_pk_bf16_f32 v96, v96, v97
	v_cvt_pk_bf16_f32 v97, v98, v99
	v_cvt_pk_bf16_f32 v98, v88, v89
	v_or_b32_e32 v88, 32, v134
	v_mad_i64_i32 v[88:89], s[4:5], v88, s40, v[128:129]
	v_cvt_pk_bf16_f32 v99, v90, v91
	global_store_dwordx4 v[112:113], v[96:99], off offset:256
	s_nop 1
	v_lshl_add_u64 v[96:97], v[88:89], 0, v[130:131]
	v_cvt_pk_bf16_f32 v88, v100, v101
	v_cvt_pk_bf16_f32 v89, v102, v103
	v_cvt_pk_bf16_f32 v90, v92, v93
	v_cvt_pk_bf16_f32 v91, v94, v95
	global_store_dwordx4 v[96:97], v[88:91], off
	v_cvt_pk_bf16_f32 v80, v80, v81
	v_cvt_pk_bf16_f32 v81, v82, v83
	v_cvt_pk_bf16_f32 v82, v72, v73
	v_or_b32_e32 v72, 48, v134
	v_mad_i64_i32 v[72:73], s[4:5], v72, s40, v[128:129]
	v_cvt_pk_bf16_f32 v83, v74, v75
	global_store_dwordx4 v[96:97], v[80:83], off offset:256
	s_nop 1
	v_lshl_add_u64 v[80:81], v[72:73], 0, v[130:131]
	v_cvt_pk_bf16_f32 v72, v84, v85
	v_cvt_pk_bf16_f32 v73, v86, v87
	v_cvt_pk_bf16_f32 v74, v76, v77
	v_cvt_pk_bf16_f32 v75, v78, v79
	global_store_dwordx4 v[80:81], v[72:75], off
	v_cvt_pk_bf16_f32 v68, v68, v69
	v_cvt_pk_bf16_f32 v69, v70, v71
	v_cvt_pk_bf16_f32 v70, v64, v65
	v_add_u32_e32 v64, 0x80, v134
	v_mad_i64_i32 v[64:65], s[4:5], v64, s40, v[128:129]
	v_lshl_add_u64 v[64:65], v[64:65], 0, v[130:131]
	v_cvt_pk_bf16_f32 v71, v66, v67
	global_store_dwordx4 v[80:81], v[68:71], off offset:256
	v_cvt_pk_bf16_f32 v60, v60, v61
	v_cvt_pk_bf16_f32 v61, v62, v63
	v_cvt_pk_bf16_f32 v62, v56, v57
	v_cvt_pk_bf16_f32 v63, v58, v59
	global_store_dwordx4 v[64:65], v[60:63], off
	v_cvt_pk_bf16_f32 v48, v48, v49
	v_cvt_pk_bf16_f32 v49, v50, v51
	v_cvt_pk_bf16_f32 v50, v40, v41
	v_add_u32_e32 v40, 0x90, v134
	v_mad_i64_i32 v[40:41], s[4:5], v40, s40, v[128:129]
	v_cvt_pk_bf16_f32 v51, v42, v43
	global_store_dwordx4 v[64:65], v[48:51], off offset:256
	s_nop 1
	v_lshl_add_u64 v[48:49], v[40:41], 0, v[130:131]
	v_cvt_pk_bf16_f32 v40, v52, v53
	v_cvt_pk_bf16_f32 v41, v54, v55
	v_cvt_pk_bf16_f32 v42, v44, v45
	v_cvt_pk_bf16_f32 v43, v46, v47
	global_store_dwordx4 v[48:49], v[40:43], off
	v_cvt_pk_bf16_f32 v32, v32, v33
	v_cvt_pk_bf16_f32 v33, v34, v35
	v_cvt_pk_bf16_f32 v34, v24, v25
	v_add_u32_e32 v24, 0xa0, v134
	v_mad_i64_i32 v[24:25], s[4:5], v24, s40, v[128:129]
	v_cvt_pk_bf16_f32 v35, v26, v27
	global_store_dwordx4 v[48:49], v[32:35], off offset:256
	s_nop 1
	v_lshl_add_u64 v[32:33], v[24:25], 0, v[130:131]
	v_cvt_pk_bf16_f32 v24, v36, v37
	v_cvt_pk_bf16_f32 v25, v38, v39
	v_cvt_pk_bf16_f32 v26, v28, v29
	v_cvt_pk_bf16_f32 v27, v30, v31
	global_store_dwordx4 v[32:33], v[24:27], off
	v_cvt_pk_bf16_f32 v16, v16, v17
	v_cvt_pk_bf16_f32 v17, v18, v19
	v_cvt_pk_bf16_f32 v18, v8, v9
	v_add_u32_e32 v8, 0xb0, v134
	v_mad_i64_i32 v[8:9], s[4:5], v8, s40, v[128:129]
	v_cvt_pk_bf16_f32 v19, v10, v11
	global_store_dwordx4 v[32:33], v[16:19], off offset:256
	s_nop 1
	v_lshl_add_u64 v[16:17], v[8:9], 0, v[130:131]
	v_cvt_pk_bf16_f32 v8, v20, v21
	v_cvt_pk_bf16_f32 v9, v22, v23
	v_cvt_pk_bf16_f32 v10, v12, v13
	v_cvt_pk_bf16_f32 v11, v14, v15
	global_store_dwordx4 v[16:17], v[8:11], off
	v_cvt_pk_bf16_f32 v4, v4, v5
	v_cvt_pk_bf16_f32 v5, v6, v7
	v_cvt_pk_bf16_f32 v6, v0, v1
	v_cvt_pk_bf16_f32 v7, v2, v3
	global_store_dwordx4 v[16:17], v[4:7], off offset:256
	s_waitcnt vmcnt(0)
	s_cbranch_scc0 .LBB0_1418
	s_barrier

.LBB0_1553:
	s_add_i32 s94, s14, 2
	s_add_u32 s12, s8, 0x100
	s_addc_u32 s13, s9, 0
	s_add_i32 s95, 0, 0x10000
	v_add_u32_e32 v138, s95, v141
	ds_read_b128 v[144:147], v138
	ds_read_b128 v[148:151], v138 offset:1024
	ds_read_b128 v[152:155], v138 offset:2048
	ds_read_b128 v[156:159], v138 offset:3072
	s_cmp_eq_u32 s91, s14
	s_cselect_b32 s14, s6, s92
	s_cselect_b32 s29, s5, s13
	s_cselect_b32 s28, s4, s12
	s_cselect_b32 s15, s7, s93
	v_lshl_add_u64 v[138:139], s[8:9], 0, v[134:135]
	s_add_i32 m0, s71, 0xc000
	ds_read_b128 v[160:163], v143
	ds_read_b128 v[164:167], v143 offset:1024
	ds_read_b128 v[194:197], v143 offset:2048
	ds_read_b128 v[198:201], v143 offset:3072
	ds_read_b128 v[202:205], v143 offset:4096
	ds_read_b128 v[206:209], v143 offset:5120
	ds_read_b128 v[210:213], v143 offset:6144
	ds_read_b128 v[214:217], v143 offset:7168
	global_load_lds_dwordx4 v[138:139], off
	v_lshl_add_u64 v[138:139], s[8:9], 0, v[136:137]
	s_add_i32 m0, s71, 0xe000
	s_nop 0
	global_load_lds_dwordx4 v[138:139], off
	s_waitcnt lgkmcnt(8)
	s_barrier
	s_waitcnt lgkmcnt(0)
	s_nop 0
	s_waitcnt lgkmcnt(0)
	v_mfma_f32_16x16x32_bf16 v[124:127], v[144:147], v[160:163], v[124:127]
	v_mfma_f32_16x16x32_bf16 v[120:123], v[152:155], v[160:163], v[120:123]
	v_mfma_f32_16x16x32_bf16 v[116:119], v[144:147], v[194:197], v[116:119]
	v_mfma_f32_16x16x32_bf16 v[108:111], v[152:155], v[194:197], v[108:111]
	v_mfma_f32_16x16x32_bf16 v[100:103], v[144:147], v[202:205], v[100:103]
	v_mfma_f32_16x16x32_bf16 v[92:95], v[152:155], v[202:205], v[92:95]
	v_mfma_f32_16x16x32_bf16 v[80:83], v[144:147], v[210:213], v[80:83]
	v_mfma_f32_16x16x32_bf16 v[72:75], v[152:155], v[210:213], v[72:75]
	v_mfma_f32_16x16x32_bf16 v[124:127], v[148:151], v[164:167], v[124:127]
	v_mfma_f32_16x16x32_bf16 v[120:123], v[156:159], v[164:167], v[120:123]
	v_mfma_f32_16x16x32_bf16 v[116:119], v[148:151], v[198:201], v[116:119]
	v_mfma_f32_16x16x32_bf16 v[108:111], v[156:159], v[198:201], v[108:111]
	v_mfma_f32_16x16x32_bf16 v[100:103], v[148:151], v[206:209], v[100:103]
	v_mfma_f32_16x16x32_bf16 v[92:95], v[156:159], v[206:209], v[92:95]
	v_mfma_f32_16x16x32_bf16 v[80:83], v[148:151], v[214:217], v[80:83]
	v_mfma_f32_16x16x32_bf16 v[72:75], v[156:159], v[214:217], v[72:75]
	s_nop 0
	s_barrier
	s_add_i32 s96, 0, 0x14000
	v_add_u32_e32 v138, s96, v141
	s_add_i32 s8, s95, s69
	ds_read_b128 v[218:221], v138
	ds_read_b128 v[222:225], v138 offset:1024
	ds_read_b128 v[226:229], v138 offset:2048
	ds_read_b128 v[230:233], v138 offset:3072
	v_lshl_add_u64 v[138:139], s[14:15], 0, v[168:169]
	s_mov_b32 m0, s8
	v_lshl_add_u64 v[176:177], s[14:15], 0, v[128:129]
	global_load_lds_dwordx4 v[138:139], off
	s_add_i32 m0, s8, 0x2000
	s_nop 0
	global_load_lds_dwordx4 v[176:177], off
	s_barrier
	s_waitcnt lgkmcnt(0)
	s_nop 0
	s_waitcnt lgkmcnt(0)
	v_mfma_f32_16x16x32_bf16 v[112:115], v[218:221], v[160:163], v[112:115]
	v_mfma_f32_16x16x32_bf16 v[104:107], v[226:229], v[160:163], v[104:107]
	v_mfma_f32_16x16x32_bf16 v[96:99], v[218:221], v[194:197], v[96:99]
	v_mfma_f32_16x16x32_bf16 v[88:91], v[226:229], v[194:197], v[88:91]
	v_mfma_f32_16x16x32_bf16 v[84:87], v[218:221], v[202:205], v[84:87]
	v_mfma_f32_16x16x32_bf16 v[76:79], v[226:229], v[202:205], v[76:79]
	v_mfma_f32_16x16x32_bf16 v[68:71], v[218:221], v[210:213], v[68:71]
	v_mfma_f32_16x16x32_bf16 v[64:67], v[226:229], v[210:213], v[64:67]
	v_mfma_f32_16x16x32_bf16 v[112:115], v[222:225], v[164:167], v[112:115]
	v_mfma_f32_16x16x32_bf16 v[104:107], v[230:233], v[164:167], v[104:107]
	v_mfma_f32_16x16x32_bf16 v[96:99], v[222:225], v[198:201], v[96:99]
	v_mfma_f32_16x16x32_bf16 v[88:91], v[230:233], v[198:201], v[88:91]
	v_mfma_f32_16x16x32_bf16 v[84:87], v[222:225], v[206:209], v[84:87]
	v_mfma_f32_16x16x32_bf16 v[76:79], v[230:233], v[206:209], v[76:79]
	v_mfma_f32_16x16x32_bf16 v[68:71], v[222:225], v[214:217], v[68:71]
	v_mfma_f32_16x16x32_bf16 v[64:67], v[230:233], v[214:217], v[64:67]
	s_nop 0
	s_mov_b32 m0, s71
	v_lshl_add_u64 v[234:235], s[28:29], 0, v[132:133]
	s_barrier
	ds_read_b128 v[160:163], v143 offset:16384
	ds_read_b128 v[164:167], v143 offset:17408
	ds_read_b128 v[194:197], v143 offset:18432
	ds_read_b128 v[198:201], v143 offset:19456
	ds_read_b128 v[202:205], v143 offset:20480
	ds_read_b128 v[206:209], v143 offset:21504
	ds_read_b128 v[210:213], v143 offset:22528
	ds_read_b128 v[214:217], v143 offset:23552
	global_load_lds_dwordx4 v[234:235], off
	v_lshl_add_u64 v[236:237], s[28:29], 0, v[130:131]
	s_mov_b32 m0, s72
	s_nop 0
	global_load_lds_dwordx4 v[236:237], off
	s_barrier
	s_waitcnt lgkmcnt(0)
	s_nop 0
	s_waitcnt lgkmcnt(0)
	v_mfma_f32_16x16x32_bf16 v[60:63], v[144:147], v[160:163], v[60:63]
	v_mfma_f32_16x16x32_bf16 v[56:59], v[152:155], v[160:163], v[56:59]
	v_mfma_f32_16x16x32_bf16 v[52:55], v[144:147], v[194:197], v[52:55]
	v_mfma_f32_16x16x32_bf16 v[44:47], v[152:155], v[194:197], v[44:47]
	v_mfma_f32_16x16x32_bf16 v[36:39], v[144:147], v[202:205], v[36:39]
	v_mfma_f32_16x16x32_bf16 v[28:31], v[152:155], v[202:205], v[28:31]
	v_mfma_f32_16x16x32_bf16 v[20:23], v[144:147], v[210:213], v[20:23]
	v_mfma_f32_16x16x32_bf16 v[12:15], v[152:155], v[210:213], v[12:15]
	v_mfma_f32_16x16x32_bf16 v[60:63], v[148:151], v[164:167], v[60:63]
	v_mfma_f32_16x16x32_bf16 v[56:59], v[156:159], v[164:167], v[56:59]
	v_mfma_f32_16x16x32_bf16 v[52:55], v[148:151], v[198:201], v[52:55]
	v_mfma_f32_16x16x32_bf16 v[44:47], v[156:159], v[198:201], v[44:47]
	v_mfma_f32_16x16x32_bf16 v[36:39], v[148:151], v[206:209], v[36:39]
	v_mfma_f32_16x16x32_bf16 v[28:31], v[156:159], v[206:209], v[28:31]
	v_mfma_f32_16x16x32_bf16 v[20:23], v[148:151], v[214:217], v[20:23]
	v_mfma_f32_16x16x32_bf16 v[12:15], v[156:159], v[214:217], v[12:15]
	s_nop 0
	s_barrier
	s_add_u32 s8, s14, 0x158000
	s_addc_u32 s9, s15, 0
	s_add_i32 s95, s96, s69
	v_lshl_add_u64 v[144:145], s[8:9], 0, v[168:169]
	s_mov_b32 m0, s95
	s_nop 0
	global_load_lds_dwordx4 v[144:145], off
	v_lshl_add_u64 v[144:145], s[8:9], 0, v[128:129]
	s_add_i32 m0, s95, 0x2000
	s_nop 0
	global_load_lds_dwordx4 v[144:145], off
	s_waitcnt vmcnt(6)
	s_barrier
	s_nop 0
	v_mfma_f32_16x16x32_bf16 v[48:51], v[218:221], v[160:163], v[48:51]
	v_mfma_f32_16x16x32_bf16 v[40:43], v[226:229], v[160:163], v[40:43]
	v_mfma_f32_16x16x32_bf16 v[32:35], v[218:221], v[194:197], v[32:35]
	v_mfma_f32_16x16x32_bf16 v[24:27], v[226:229], v[194:197], v[24:27]
	v_mfma_f32_16x16x32_bf16 v[16:19], v[218:221], v[202:205], v[16:19]
	v_mfma_f32_16x16x32_bf16 v[8:11], v[226:229], v[202:205], v[8:11]
	v_mfma_f32_16x16x32_bf16 v[4:7], v[218:221], v[210:213], v[4:7]
	v_mfma_f32_16x16x32_bf16 v[0:3], v[226:229], v[210:213], v[0:3]
	v_mfma_f32_16x16x32_bf16 v[48:51], v[222:225], v[164:167], v[48:51]
	v_mfma_f32_16x16x32_bf16 v[40:43], v[230:233], v[164:167], v[40:43]
	v_mfma_f32_16x16x32_bf16 v[32:35], v[222:225], v[198:201], v[32:35]
	v_mfma_f32_16x16x32_bf16 v[24:27], v[230:233], v[198:201], v[24:27]
	v_mfma_f32_16x16x32_bf16 v[16:19], v[222:225], v[206:209], v[16:19]
	v_mfma_f32_16x16x32_bf16 v[8:11], v[230:233], v[206:209], v[8:11]
	v_mfma_f32_16x16x32_bf16 v[4:7], v[222:225], v[214:217], v[4:7]
	v_mfma_f32_16x16x32_bf16 v[0:3], v[230:233], v[214:217], v[0:3]
	s_nop 0
	s_add_i32 s95, 0, 0x18000
	v_add_u32_e32 v156, s95, v141
	s_barrier
	ds_read_b128 v[144:147], v156
	ds_read_b128 v[148:151], v156 offset:1024
	ds_read_b128 v[152:155], v156 offset:2048
	ds_read_b128 v[156:159], v156 offset:3072
	s_add_u32 s8, s28, 0x158000
	s_addc_u32 s9, s29, 0
	s_mov_b32 m0, s73
	v_lshl_add_u64 v[218:219], s[8:9], 0, v[132:133]
	ds_read_b128 v[160:163], v143 offset:32768
	ds_read_b128 v[164:167], v143 offset:33792
	ds_read_b128 v[194:197], v143 offset:34816
	ds_read_b128 v[198:201], v143 offset:35840
	ds_read_b128 v[202:205], v143 offset:36864
	ds_read_b128 v[206:209], v143 offset:37888
	ds_read_b128 v[210:213], v143 offset:38912
	ds_read_b128 v[214:217], v143 offset:39936
	global_load_lds_dwordx4 v[218:219], off
	v_lshl_add_u64 v[218:219], s[8:9], 0, v[130:131]
	s_mov_b32 m0, s78
	s_nop 0
	global_load_lds_dwordx4 v[218:219], off
	s_waitcnt lgkmcnt(8)
	s_barrier
	s_waitcnt lgkmcnt(0)
	s_nop 0
	s_waitcnt lgkmcnt(0)
	v_mfma_f32_16x16x32_bf16 v[124:127], v[144:147], v[160:163], v[124:127]
	v_mfma_f32_16x16x32_bf16 v[120:123], v[152:155], v[160:163], v[120:123]
	v_mfma_f32_16x16x32_bf16 v[116:119], v[144:147], v[194:197], v[116:119]
	v_mfma_f32_16x16x32_bf16 v[108:111], v[152:155], v[194:197], v[108:111]
	v_mfma_f32_16x16x32_bf16 v[100:103], v[144:147], v[202:205], v[100:103]
	v_mfma_f32_16x16x32_bf16 v[92:95], v[152:155], v[202:205], v[92:95]
	v_mfma_f32_16x16x32_bf16 v[80:83], v[144:147], v[210:213], v[80:83]
	v_mfma_f32_16x16x32_bf16 v[72:75], v[152:155], v[210:213], v[72:75]
	v_mfma_f32_16x16x32_bf16 v[124:127], v[148:151], v[164:167], v[124:127]
	v_mfma_f32_16x16x32_bf16 v[120:123], v[156:159], v[164:167], v[120:123]
	v_mfma_f32_16x16x32_bf16 v[116:119], v[148:151], v[198:201], v[116:119]
	v_mfma_f32_16x16x32_bf16 v[108:111], v[156:159], v[198:201], v[108:111]
	v_mfma_f32_16x16x32_bf16 v[100:103], v[148:151], v[206:209], v[100:103]
	v_mfma_f32_16x16x32_bf16 v[92:95], v[156:159], v[206:209], v[92:95]
	v_mfma_f32_16x16x32_bf16 v[80:83], v[148:151], v[214:217], v[80:83]
	v_mfma_f32_16x16x32_bf16 v[72:75], v[156:159], v[214:217], v[72:75]
	s_nop 0
	s_barrier
	s_add_i32 s28, 0, 0x1c000
	s_add_i32 s8, s95, s69
	v_add_u32_e32 v193, s28, v141
	v_lshl_add_u64 v[138:139], v[138:139], 0, s[0:1]
	s_mov_b32 m0, s8
	ds_read_b128 v[218:221], v193
	ds_read_b128 v[222:225], v193 offset:1024
	ds_read_b128 v[226:229], v193 offset:2048
	ds_read_b128 v[230:233], v193 offset:3072
	global_load_lds_dwordx4 v[138:139], off
	v_lshl_add_u64 v[138:139], v[176:177], 0, s[0:1]
	s_add_i32 m0, s8, 0x2000
	s_nop 0
	global_load_lds_dwordx4 v[138:139], off
	s_barrier
	s_waitcnt lgkmcnt(0)
	s_nop 0
	s_waitcnt lgkmcnt(0)
	v_mfma_f32_16x16x32_bf16 v[112:115], v[218:221], v[160:163], v[112:115]
	v_mfma_f32_16x16x32_bf16 v[104:107], v[226:229], v[160:163], v[104:107]
	v_mfma_f32_16x16x32_bf16 v[96:99], v[218:221], v[194:197], v[96:99]
	v_mfma_f32_16x16x32_bf16 v[88:91], v[226:229], v[194:197], v[88:91]
	v_mfma_f32_16x16x32_bf16 v[84:87], v[218:221], v[202:205], v[84:87]
	v_mfma_f32_16x16x32_bf16 v[76:79], v[226:229], v[202:205], v[76:79]
	v_mfma_f32_16x16x32_bf16 v[68:71], v[218:221], v[210:213], v[68:71]
	v_mfma_f32_16x16x32_bf16 v[64:67], v[226:229], v[210:213], v[64:67]
	v_mfma_f32_16x16x32_bf16 v[112:115], v[222:225], v[164:167], v[112:115]
	v_mfma_f32_16x16x32_bf16 v[104:107], v[230:233], v[164:167], v[104:107]
	v_mfma_f32_16x16x32_bf16 v[96:99], v[222:225], v[198:201], v[96:99]
	v_mfma_f32_16x16x32_bf16 v[88:91], v[230:233], v[198:201], v[88:91]
	v_mfma_f32_16x16x32_bf16 v[84:87], v[222:225], v[206:209], v[84:87]
	v_mfma_f32_16x16x32_bf16 v[76:79], v[230:233], v[206:209], v[76:79]
	v_mfma_f32_16x16x32_bf16 v[68:71], v[222:225], v[214:217], v[68:71]
	v_mfma_f32_16x16x32_bf16 v[64:67], v[230:233], v[214:217], v[64:67]
	s_nop 0
	s_mov_b32 m0, s82
	v_lshl_add_u64 v[138:139], v[234:235], 0, s[0:1]
	s_barrier
	ds_read_b128 v[160:163], v143 offset:49152
	ds_read_b128 v[164:167], v143 offset:50176
	ds_read_b128 v[194:197], v143 offset:51200
	ds_read_b128 v[198:201], v143 offset:52224
	ds_read_b128 v[202:205], v143 offset:53248
	ds_read_b128 v[206:209], v143 offset:54272
	ds_read_b128 v[210:213], v143 offset:55296
	ds_read_b128 v[214:217], v143 offset:56320
	global_load_lds_dwordx4 v[138:139], off
	v_lshl_add_u64 v[138:139], v[236:237], 0, s[0:1]
	s_mov_b32 m0, s83
	s_nop 0
	global_load_lds_dwordx4 v[138:139], off
	s_barrier
	s_waitcnt lgkmcnt(0)
	s_nop 0
	s_waitcnt lgkmcnt(0)
	v_mfma_f32_16x16x32_bf16 v[60:63], v[144:147], v[160:163], v[60:63]
	v_mfma_f32_16x16x32_bf16 v[56:59], v[152:155], v[160:163], v[56:59]
	v_mfma_f32_16x16x32_bf16 v[52:55], v[144:147], v[194:197], v[52:55]
	v_mfma_f32_16x16x32_bf16 v[44:47], v[152:155], v[194:197], v[44:47]
	v_mfma_f32_16x16x32_bf16 v[36:39], v[144:147], v[202:205], v[36:39]
	v_mfma_f32_16x16x32_bf16 v[28:31], v[152:155], v[202:205], v[28:31]
	v_mfma_f32_16x16x32_bf16 v[20:23], v[144:147], v[210:213], v[20:23]
	v_mfma_f32_16x16x32_bf16 v[12:15], v[152:155], v[210:213], v[12:15]
	v_mfma_f32_16x16x32_bf16 v[60:63], v[148:151], v[164:167], v[60:63]
	v_mfma_f32_16x16x32_bf16 v[56:59], v[156:159], v[164:167], v[56:59]
	v_mfma_f32_16x16x32_bf16 v[52:55], v[148:151], v[198:201], v[52:55]
	v_mfma_f32_16x16x32_bf16 v[44:47], v[156:159], v[198:201], v[44:47]
	v_mfma_f32_16x16x32_bf16 v[36:39], v[148:151], v[206:209], v[36:39]
	v_mfma_f32_16x16x32_bf16 v[28:31], v[156:159], v[206:209], v[28:31]
	v_mfma_f32_16x16x32_bf16 v[20:23], v[148:151], v[214:217], v[20:23]
	v_mfma_f32_16x16x32_bf16 v[12:15], v[156:159], v[214:217], v[12:15]
	s_nop 0
	s_barrier
	s_add_u32 s8, s14, 0x158080
	s_addc_u32 s9, s15, 0
	s_add_i32 s14, s28, s69
	v_lshl_add_u64 v[138:139], s[8:9], 0, v[168:169]
	s_mov_b32 m0, s14
	s_nop 0
	global_load_lds_dwordx4 v[138:139], off
	v_lshl_add_u64 v[138:139], s[8:9], 0, v[128:129]
	s_add_i32 m0, s14, 0x2000
	s_nop 0
	global_load_lds_dwordx4 v[138:139], off
	s_waitcnt vmcnt(6)
	s_barrier
	s_nop 0
	v_mfma_f32_16x16x32_bf16 v[48:51], v[218:221], v[160:163], v[48:51]
	v_mfma_f32_16x16x32_bf16 v[40:43], v[226:229], v[160:163], v[40:43]
	v_mfma_f32_16x16x32_bf16 v[32:35], v[218:221], v[194:197], v[32:35]
	v_mfma_f32_16x16x32_bf16 v[24:27], v[226:229], v[194:197], v[24:27]
	v_mfma_f32_16x16x32_bf16 v[16:19], v[218:221], v[202:205], v[16:19]
	v_mfma_f32_16x16x32_bf16 v[8:11], v[226:229], v[202:205], v[8:11]
	v_mfma_f32_16x16x32_bf16 v[4:7], v[218:221], v[210:213], v[4:7]
	v_mfma_f32_16x16x32_bf16 v[0:3], v[226:229], v[210:213], v[0:3]
	v_mfma_f32_16x16x32_bf16 v[48:51], v[222:225], v[164:167], v[48:51]
	v_mfma_f32_16x16x32_bf16 v[40:43], v[230:233], v[164:167], v[40:43]
	v_mfma_f32_16x16x32_bf16 v[32:35], v[222:225], v[198:201], v[32:35]
	v_mfma_f32_16x16x32_bf16 v[24:27], v[230:233], v[198:201], v[24:27]
	v_mfma_f32_16x16x32_bf16 v[16:19], v[222:225], v[206:209], v[16:19]
	v_mfma_f32_16x16x32_bf16 v[8:11], v[230:233], v[206:209], v[8:11]
	v_mfma_f32_16x16x32_bf16 v[4:7], v[222:225], v[214:217], v[4:7]
	v_mfma_f32_16x16x32_bf16 v[0:3], v[230:233], v[214:217], v[0:3]
	s_nop 0
	s_add_u32 s92, s92, 0x100
	s_addc_u32 s93, s93, 0
	s_cmp_ge_u32 s94, s90
	s_mov_b64 s[8:9], s[12:13]
	s_mov_b32 s14, s94
	s_barrier
	s_cbranch_scc0 .LBB0_1553
	v_lshl_add_u32 v144, s85, 8, v140
	v_lshl_or_b32 v138, s89, 8, v142
	v_ashrrev_i32_e32 v145, 31, v144
	v_readlane_b32 s8, v240, 62
	v_ashrrev_i32_e32 v139, 31, v138
	v_lshlrev_b64 v[146:147], 12, v[144:145]
	v_readlane_b32 s9, v240, 63
	v_lshlrev_b64 v[148:149], 1, v[138:139]
	v_cvt_pk_bf16_f32 v124, v124, v125
	v_cvt_pk_bf16_f32 v125, v126, v127
	v_cvt_pk_bf16_f32 v126, v120, v121
	v_cvt_pk_bf16_f32 v127, v122, v123
	s_nop 0
	v_lshl_add_u64 v[146:147], s[8:9], 0, v[146:147]
	v_lshl_add_u64 v[138:139], v[146:147], 0, v[148:149]
	global_store_dwordx4 v[138:139], v[124:127], off
	v_cvt_pk_bf16_f32 v112, v112, v113
	v_cvt_pk_bf16_f32 v113, v114, v115
	v_cvt_pk_bf16_f32 v114, v104, v105
	v_or_b32_e32 v104, 16, v144
	v_ashrrev_i32_e32 v105, 31, v104
	v_lshlrev_b64 v[104:105], 12, v[104:105]
	v_lshl_add_u64 v[104:105], s[8:9], 0, v[104:105]
	v_cvt_pk_bf16_f32 v115, v106, v107
	global_store_dwordx4 v[138:139], v[112:115], off offset:256
	v_readlane_b32 s92, v239, 42
	v_readlane_b32 s94, v239, 44
	v_lshl_add_u64 v[112:113], v[104:105], 0, v[148:149]
	v_cvt_pk_bf16_f32 v104, v116, v117
	v_cvt_pk_bf16_f32 v105, v118, v119
	v_cvt_pk_bf16_f32 v106, v108, v109
	v_cvt_pk_bf16_f32 v107, v110, v111
	global_store_dwordx4 v[112:113], v[104:107], off
	v_cvt_pk_bf16_f32 v96, v96, v97
	v_cvt_pk_bf16_f32 v97, v98, v99
	v_cvt_pk_bf16_f32 v98, v88, v89
	v_or_b32_e32 v88, 32, v144
	v_ashrrev_i32_e32 v89, 31, v88
	v_lshlrev_b64 v[88:89], 12, v[88:89]
	v_lshl_add_u64 v[88:89], s[8:9], 0, v[88:89]
	v_cvt_pk_bf16_f32 v99, v90, v91
	global_store_dwordx4 v[112:113], v[96:99], off offset:256
	s_mov_b32 s89, s88
	s_mov_b32 s85, s87
	v_lshl_add_u64 v[96:97], v[88:89], 0, v[148:149]
	v_cvt_pk_bf16_f32 v88, v100, v101
	v_cvt_pk_bf16_f32 v89, v102, v103
	v_cvt_pk_bf16_f32 v90, v92, v93
	v_cvt_pk_bf16_f32 v91, v94, v95
	global_store_dwordx4 v[96:97], v[88:91], off
	v_cvt_pk_bf16_f32 v84, v84, v85
	v_cvt_pk_bf16_f32 v85, v86, v87
	v_cvt_pk_bf16_f32 v86, v76, v77
	v_or_b32_e32 v76, 48, v144
	v_ashrrev_i32_e32 v77, 31, v76
	v_lshlrev_b64 v[76:77], 12, v[76:77]
	v_lshl_add_u64 v[76:77], s[8:9], 0, v[76:77]
	v_cvt_pk_bf16_f32 v87, v78, v79
	global_store_dwordx4 v[96:97], v[84:87], off offset:256
	s_mov_b64 s[8:9], 0x80000
	s_mov_b32 s90, s86
	v_lshl_add_u64 v[84:85], v[76:77], 0, v[148:149]
	v_cvt_pk_bf16_f32 v76, v80, v81
	v_cvt_pk_bf16_f32 v77, v82, v83
	v_cvt_pk_bf16_f32 v78, v72, v73
	v_cvt_pk_bf16_f32 v79, v74, v75
	global_store_dwordx4 v[84:85], v[76:79], off
	v_cvt_pk_bf16_f32 v68, v68, v69
	v_cvt_pk_bf16_f32 v69, v70, v71
	v_cvt_pk_bf16_f32 v70, v64, v65
	v_lshl_add_u64 v[64:65], v[138:139], 0, s[8:9]
	s_mov_b32 s8, 0x80000
	v_cvt_pk_bf16_f32 v71, v66, v67
	global_store_dwordx4 v[84:85], v[68:71], off offset:256
	v_cvt_pk_bf16_f32 v60, v60, v61
	v_cvt_pk_bf16_f32 v61, v62, v63
	v_cvt_pk_bf16_f32 v62, v56, v57
	v_add_co_u32_e32 v56, vcc, s8, v138
	v_cvt_pk_bf16_f32 v63, v58, v59
	s_mov_b64 s[8:9], 0x90000
	s_nop 0
	v_addc_co_u32_e32 v57, vcc, 0, v139, vcc
	global_store_dwordx4 v[56:57], v[60:63], off
	v_cvt_pk_bf16_f32 v48, v48, v49
	v_cvt_pk_bf16_f32 v49, v50, v51
	v_cvt_pk_bf16_f32 v50, v40, v41
	v_cvt_pk_bf16_f32 v51, v42, v43
	global_store_dwordx4 v[64:65], v[48:51], off offset:256
	v_cvt_pk_bf16_f32 v40, v52, v53
	v_cvt_pk_bf16_f32 v41, v54, v55
	v_cvt_pk_bf16_f32 v42, v44, v45
	v_cvt_pk_bf16_f32 v43, v46, v47
	s_mov_b64 s[12:13], s[6:7]
	s_nop 0
	v_lshl_add_u64 v[48:49], v[138:139], 0, s[8:9]
	s_mov_b32 s8, 0x90000
	v_add_co_u32_e32 v44, vcc, s8, v138
	s_mov_b64 s[8:9], 0xa0000
	s_nop 0
	v_addc_co_u32_e32 v45, vcc, 0, v139, vcc
	global_store_dwordx4 v[44:45], v[40:43], off
	v_cvt_pk_bf16_f32 v32, v32, v33
	v_cvt_pk_bf16_f32 v33, v34, v35
	v_cvt_pk_bf16_f32 v34, v24, v25
	v_cvt_pk_bf16_f32 v35, v26, v27
	global_store_dwordx4 v[48:49], v[32:35], off offset:256
	v_cvt_pk_bf16_f32 v24, v36, v37
	v_cvt_pk_bf16_f32 v25, v38, v39
	v_cvt_pk_bf16_f32 v26, v28, v29
	v_cvt_pk_bf16_f32 v27, v30, v31
	v_readlane_b32 s93, v239, 43
	s_nop 0
	v_lshl_add_u64 v[32:33], v[138:139], 0, s[8:9]
	s_mov_b32 s8, 0xa0000
	v_add_co_u32_e32 v28, vcc, s8, v138
	s_mov_b64 s[8:9], 0xb0000
	s_nop 0
	v_addc_co_u32_e32 v29, vcc, 0, v139, vcc
	global_store_dwordx4 v[28:29], v[24:27], off
	v_cvt_pk_bf16_f32 v16, v16, v17
	v_cvt_pk_bf16_f32 v17, v18, v19
	v_cvt_pk_bf16_f32 v18, v8, v9
	v_cvt_pk_bf16_f32 v19, v10, v11
	global_store_dwordx4 v[32:33], v[16:19], off offset:256
	v_cvt_pk_bf16_f32 v8, v20, v21
	v_cvt_pk_bf16_f32 v9, v22, v23
	v_cvt_pk_bf16_f32 v10, v12, v13
	v_readlane_b32 s95, v239, 45
	v_cvt_pk_bf16_f32 v11, v14, v15
	s_nop 0
	v_lshl_add_u64 v[16:17], v[138:139], 0, s[8:9]
	s_mov_b32 s8, 0xb0000
	v_add_co_u32_e32 v12, vcc, s8, v138
	s_mov_b64 s[8:9], s[4:5]
	s_nop 0
	v_addc_co_u32_e32 v13, vcc, 0, v139, vcc
	s_and_b64 vcc, exec, s[2:3]
	global_store_dwordx4 v[12:13], v[8:11], off
	v_cvt_pk_bf16_f32 v4, v4, v5
	v_cvt_pk_bf16_f32 v5, v6, v7
	v_cvt_pk_bf16_f32 v6, v0, v1
	v_cvt_pk_bf16_f32 v7, v2, v3
	global_store_dwordx4 v[16:17], v[4:7], off offset:256
	s_cbranch_vccz .LBB0_1545
	s_branch .LBB0_1556

.LBB0_1575:
	s_add_i32 vcc_hi, s28, 2
	s_add_u32 s14, s12, 0x100
	s_addc_u32 s15, s13, 0
	s_add_i32 s70, 0, 0x10000
	v_add_u32_e32 v146, s70, v149
	ds_read_b128 v[128:131], v146
	ds_read_b128 v[142:145], v146 offset:1024
	ds_read_b128 v[152:155], v146 offset:2048
	ds_read_b128 v[156:159], v146 offset:3072
	s_cmp_eq_u32 s96, s28
	s_cselect_b32 s28, s95, s97
	s_cselect_b32 s69, s7, s15
	s_cselect_b32 s68, s6, s14
	s_cselect_b32 s29, s94, vcc_lo
	v_lshl_add_u64 v[146:147], s[12:13], 0, v[138:139]
	s_add_i32 m0, s72, 0xc000
	ds_read_b128 v[160:163], v151
	ds_read_b128 v[164:167], v151 offset:1024
	ds_read_b128 v[194:197], v151 offset:2048
	ds_read_b128 v[198:201], v151 offset:3072
	ds_read_b128 v[202:205], v151 offset:4096
	ds_read_b128 v[206:209], v151 offset:5120
	ds_read_b128 v[210:213], v151 offset:6144
	ds_read_b128 v[214:217], v151 offset:7168
	global_load_lds_dwordx4 v[146:147], off
	v_lshl_add_u64 v[146:147], s[12:13], 0, v[140:141]
	s_add_i32 m0, s72, 0xe000
	s_nop 0
	global_load_lds_dwordx4 v[146:147], off
	s_waitcnt lgkmcnt(8)
	s_barrier
	s_waitcnt lgkmcnt(0)
	s_nop 0
	s_waitcnt lgkmcnt(0)
	v_mfma_f32_16x16x32_bf16 v[124:127], v[128:131], v[160:163], v[124:127]
	v_mfma_f32_16x16x32_bf16 v[120:123], v[152:155], v[160:163], v[120:123]
	v_mfma_f32_16x16x32_bf16 v[116:119], v[128:131], v[194:197], v[116:119]
	v_mfma_f32_16x16x32_bf16 v[108:111], v[152:155], v[194:197], v[108:111]
	v_mfma_f32_16x16x32_bf16 v[100:103], v[128:131], v[202:205], v[100:103]
	v_mfma_f32_16x16x32_bf16 v[92:95], v[152:155], v[202:205], v[92:95]
	v_mfma_f32_16x16x32_bf16 v[84:87], v[128:131], v[210:213], v[84:87]
	v_mfma_f32_16x16x32_bf16 v[76:79], v[152:155], v[210:213], v[76:79]
	v_mfma_f32_16x16x32_bf16 v[124:127], v[142:145], v[164:167], v[124:127]
	v_mfma_f32_16x16x32_bf16 v[120:123], v[156:159], v[164:167], v[120:123]
	v_mfma_f32_16x16x32_bf16 v[116:119], v[142:145], v[198:201], v[116:119]
	v_mfma_f32_16x16x32_bf16 v[108:111], v[156:159], v[198:201], v[108:111]
	v_mfma_f32_16x16x32_bf16 v[100:103], v[142:145], v[206:209], v[100:103]
	v_mfma_f32_16x16x32_bf16 v[92:95], v[156:159], v[206:209], v[92:95]
	v_mfma_f32_16x16x32_bf16 v[84:87], v[142:145], v[214:217], v[84:87]
	v_mfma_f32_16x16x32_bf16 v[76:79], v[156:159], v[214:217], v[76:79]
	s_nop 0
	s_barrier
	s_add_i32 s85, 0, 0x14000
	v_add_u32_e32 v146, s85, v149
	s_add_i32 s12, s70, s71
	ds_read_b128 v[218:221], v146
	ds_read_b128 v[222:225], v146 offset:1024
	ds_read_b128 v[226:229], v146 offset:2048
	ds_read_b128 v[230:233], v146 offset:3072
	v_lshl_add_u64 v[146:147], s[28:29], 0, v[168:169]
	s_mov_b32 m0, s12
	v_lshl_add_u64 v[176:177], s[28:29], 0, v[136:137]
	global_load_lds_dwordx4 v[146:147], off
	s_add_i32 m0, s12, 0x2000
	s_nop 0
	global_load_lds_dwordx4 v[176:177], off
	s_barrier
	s_waitcnt lgkmcnt(0)
	s_nop 0
	s_waitcnt lgkmcnt(0)
	v_mfma_f32_16x16x32_bf16 v[112:115], v[218:221], v[160:163], v[112:115]
	v_mfma_f32_16x16x32_bf16 v[104:107], v[226:229], v[160:163], v[104:107]
	v_mfma_f32_16x16x32_bf16 v[96:99], v[218:221], v[194:197], v[96:99]
	v_mfma_f32_16x16x32_bf16 v[88:91], v[226:229], v[194:197], v[88:91]
	v_mfma_f32_16x16x32_bf16 v[80:83], v[218:221], v[202:205], v[80:83]
	v_mfma_f32_16x16x32_bf16 v[72:75], v[226:229], v[202:205], v[72:75]
	v_mfma_f32_16x16x32_bf16 v[68:71], v[218:221], v[210:213], v[68:71]
	v_mfma_f32_16x16x32_bf16 v[64:67], v[226:229], v[210:213], v[64:67]
	v_mfma_f32_16x16x32_bf16 v[112:115], v[222:225], v[164:167], v[112:115]
	v_mfma_f32_16x16x32_bf16 v[104:107], v[230:233], v[164:167], v[104:107]
	v_mfma_f32_16x16x32_bf16 v[96:99], v[222:225], v[198:201], v[96:99]
	v_mfma_f32_16x16x32_bf16 v[88:91], v[230:233], v[198:201], v[88:91]
	v_mfma_f32_16x16x32_bf16 v[80:83], v[222:225], v[206:209], v[80:83]
	v_mfma_f32_16x16x32_bf16 v[72:75], v[230:233], v[206:209], v[72:75]
	v_mfma_f32_16x16x32_bf16 v[68:71], v[222:225], v[214:217], v[68:71]
	v_mfma_f32_16x16x32_bf16 v[64:67], v[230:233], v[214:217], v[64:67]
	s_nop 0
	s_mov_b32 m0, s72
	v_lshl_add_u64 v[234:235], s[68:69], 0, v[132:133]
	s_barrier
	ds_read_b128 v[160:163], v151 offset:16384
	ds_read_b128 v[164:167], v151 offset:17408
	ds_read_b128 v[194:197], v151 offset:18432
	ds_read_b128 v[198:201], v151 offset:19456
	ds_read_b128 v[202:205], v151 offset:20480
	ds_read_b128 v[206:209], v151 offset:21504
	ds_read_b128 v[210:213], v151 offset:22528
	ds_read_b128 v[214:217], v151 offset:23552
	global_load_lds_dwordx4 v[234:235], off
	v_lshl_add_u64 v[236:237], s[68:69], 0, v[134:135]
	s_mov_b32 m0, s73
	s_nop 0
	global_load_lds_dwordx4 v[236:237], off
	s_barrier
	s_waitcnt lgkmcnt(0)
	s_nop 0
	s_waitcnt lgkmcnt(0)
	v_mfma_f32_16x16x32_bf16 v[60:63], v[128:131], v[160:163], v[60:63]
	v_mfma_f32_16x16x32_bf16 v[56:59], v[152:155], v[160:163], v[56:59]
	v_mfma_f32_16x16x32_bf16 v[52:55], v[128:131], v[194:197], v[52:55]
	v_mfma_f32_16x16x32_bf16 v[44:47], v[152:155], v[194:197], v[44:47]
	v_mfma_f32_16x16x32_bf16 v[36:39], v[128:131], v[202:205], v[36:39]
	v_mfma_f32_16x16x32_bf16 v[28:31], v[152:155], v[202:205], v[28:31]
	v_mfma_f32_16x16x32_bf16 v[20:23], v[128:131], v[210:213], v[20:23]
	v_mfma_f32_16x16x32_bf16 v[12:15], v[152:155], v[210:213], v[12:15]
	v_mfma_f32_16x16x32_bf16 v[60:63], v[142:145], v[164:167], v[60:63]
	v_mfma_f32_16x16x32_bf16 v[56:59], v[156:159], v[164:167], v[56:59]
	v_mfma_f32_16x16x32_bf16 v[52:55], v[142:145], v[198:201], v[52:55]
	v_mfma_f32_16x16x32_bf16 v[44:47], v[156:159], v[198:201], v[44:47]
	v_mfma_f32_16x16x32_bf16 v[36:39], v[142:145], v[206:209], v[36:39]
	v_mfma_f32_16x16x32_bf16 v[28:31], v[156:159], v[206:209], v[28:31]
	v_mfma_f32_16x16x32_bf16 v[20:23], v[142:145], v[214:217], v[20:23]
	v_mfma_f32_16x16x32_bf16 v[12:15], v[156:159], v[214:217], v[12:15]
	s_nop 0
	s_barrier
	s_add_u32 s12, s28, 0x158000
	s_addc_u32 s13, s29, 0
	s_add_i32 s70, s85, s71
	v_lshl_add_u64 v[128:129], s[12:13], 0, v[168:169]
	s_mov_b32 m0, s70
	s_nop 0
	global_load_lds_dwordx4 v[128:129], off
	v_lshl_add_u64 v[128:129], s[12:13], 0, v[136:137]
	s_add_i32 m0, s70, 0x2000
	s_nop 0
	global_load_lds_dwordx4 v[128:129], off
	s_waitcnt vmcnt(6)
	s_barrier
	s_nop 0
	v_mfma_f32_16x16x32_bf16 v[48:51], v[218:221], v[160:163], v[48:51]
	v_mfma_f32_16x16x32_bf16 v[40:43], v[226:229], v[160:163], v[40:43]
	v_mfma_f32_16x16x32_bf16 v[32:35], v[218:221], v[194:197], v[32:35]
	v_mfma_f32_16x16x32_bf16 v[24:27], v[226:229], v[194:197], v[24:27]
	v_mfma_f32_16x16x32_bf16 v[16:19], v[218:221], v[202:205], v[16:19]
	v_mfma_f32_16x16x32_bf16 v[8:11], v[226:229], v[202:205], v[8:11]
	v_mfma_f32_16x16x32_bf16 v[4:7], v[218:221], v[210:213], v[4:7]
	v_mfma_f32_16x16x32_bf16 v[0:3], v[226:229], v[210:213], v[0:3]
	v_mfma_f32_16x16x32_bf16 v[48:51], v[222:225], v[164:167], v[48:51]
	v_mfma_f32_16x16x32_bf16 v[40:43], v[230:233], v[164:167], v[40:43]
	v_mfma_f32_16x16x32_bf16 v[32:35], v[222:225], v[198:201], v[32:35]
	v_mfma_f32_16x16x32_bf16 v[24:27], v[230:233], v[198:201], v[24:27]
	v_mfma_f32_16x16x32_bf16 v[16:19], v[222:225], v[206:209], v[16:19]
	v_mfma_f32_16x16x32_bf16 v[8:11], v[230:233], v[206:209], v[8:11]
	v_mfma_f32_16x16x32_bf16 v[4:7], v[222:225], v[214:217], v[4:7]
	v_mfma_f32_16x16x32_bf16 v[0:3], v[230:233], v[214:217], v[0:3]
	s_nop 0
	s_add_i32 s70, 0, 0x18000
	v_add_u32_e32 v156, s70, v149
	s_barrier
	ds_read_b128 v[128:131], v156
	ds_read_b128 v[142:145], v156 offset:1024
	ds_read_b128 v[152:155], v156 offset:2048
	ds_read_b128 v[156:159], v156 offset:3072
	s_add_u32 s12, s68, 0x158000
	s_addc_u32 s13, s69, 0
	s_mov_b32 m0, s78
	v_lshl_add_u64 v[218:219], s[12:13], 0, v[132:133]
	ds_read_b128 v[160:163], v151 offset:32768
	ds_read_b128 v[164:167], v151 offset:33792
	ds_read_b128 v[194:197], v151 offset:34816
	ds_read_b128 v[198:201], v151 offset:35840
	ds_read_b128 v[202:205], v151 offset:36864
	ds_read_b128 v[206:209], v151 offset:37888
	ds_read_b128 v[210:213], v151 offset:38912
	ds_read_b128 v[214:217], v151 offset:39936
	global_load_lds_dwordx4 v[218:219], off
	v_lshl_add_u64 v[218:219], s[12:13], 0, v[134:135]
	s_mov_b32 m0, s79
	s_nop 0
	global_load_lds_dwordx4 v[218:219], off
	s_waitcnt lgkmcnt(8)
	s_barrier
	s_waitcnt lgkmcnt(0)
	s_nop 0
	s_waitcnt lgkmcnt(0)
	v_mfma_f32_16x16x32_bf16 v[124:127], v[128:131], v[160:163], v[124:127]
	v_mfma_f32_16x16x32_bf16 v[120:123], v[152:155], v[160:163], v[120:123]
	v_mfma_f32_16x16x32_bf16 v[116:119], v[128:131], v[194:197], v[116:119]
	v_mfma_f32_16x16x32_bf16 v[108:111], v[152:155], v[194:197], v[108:111]
	v_mfma_f32_16x16x32_bf16 v[100:103], v[128:131], v[202:205], v[100:103]
	v_mfma_f32_16x16x32_bf16 v[92:95], v[152:155], v[202:205], v[92:95]
	v_mfma_f32_16x16x32_bf16 v[84:87], v[128:131], v[210:213], v[84:87]
	v_mfma_f32_16x16x32_bf16 v[76:79], v[152:155], v[210:213], v[76:79]
	v_mfma_f32_16x16x32_bf16 v[124:127], v[142:145], v[164:167], v[124:127]
	v_mfma_f32_16x16x32_bf16 v[120:123], v[156:159], v[164:167], v[120:123]
	v_mfma_f32_16x16x32_bf16 v[116:119], v[142:145], v[198:201], v[116:119]
	v_mfma_f32_16x16x32_bf16 v[108:111], v[156:159], v[198:201], v[108:111]
	v_mfma_f32_16x16x32_bf16 v[100:103], v[142:145], v[206:209], v[100:103]
	v_mfma_f32_16x16x32_bf16 v[92:95], v[156:159], v[206:209], v[92:95]
	v_mfma_f32_16x16x32_bf16 v[84:87], v[142:145], v[214:217], v[84:87]
	v_mfma_f32_16x16x32_bf16 v[76:79], v[156:159], v[214:217], v[76:79]
	s_nop 0
	s_barrier
	s_add_i32 s68, 0, 0x1c000
	s_add_i32 s12, s70, s71
	v_add_u32_e32 v193, s68, v149
	v_lshl_add_u64 v[146:147], v[146:147], 0, s[0:1]
	s_mov_b32 m0, s12
	ds_read_b128 v[218:221], v193
	ds_read_b128 v[222:225], v193 offset:1024
	ds_read_b128 v[226:229], v193 offset:2048
	ds_read_b128 v[230:233], v193 offset:3072
	global_load_lds_dwordx4 v[146:147], off
	v_lshl_add_u64 v[146:147], v[176:177], 0, s[0:1]
	s_add_i32 m0, s12, 0x2000
	s_nop 0
	global_load_lds_dwordx4 v[146:147], off
	s_barrier
	s_waitcnt lgkmcnt(0)
	s_nop 0
	s_waitcnt lgkmcnt(0)
	v_mfma_f32_16x16x32_bf16 v[112:115], v[218:221], v[160:163], v[112:115]
	v_mfma_f32_16x16x32_bf16 v[104:107], v[226:229], v[160:163], v[104:107]
	v_mfma_f32_16x16x32_bf16 v[96:99], v[218:221], v[194:197], v[96:99]
	v_mfma_f32_16x16x32_bf16 v[88:91], v[226:229], v[194:197], v[88:91]
	v_mfma_f32_16x16x32_bf16 v[80:83], v[218:221], v[202:205], v[80:83]
	v_mfma_f32_16x16x32_bf16 v[72:75], v[226:229], v[202:205], v[72:75]
	v_mfma_f32_16x16x32_bf16 v[68:71], v[218:221], v[210:213], v[68:71]
	v_mfma_f32_16x16x32_bf16 v[64:67], v[226:229], v[210:213], v[64:67]
	v_mfma_f32_16x16x32_bf16 v[112:115], v[222:225], v[164:167], v[112:115]
	v_mfma_f32_16x16x32_bf16 v[104:107], v[230:233], v[164:167], v[104:107]
	v_mfma_f32_16x16x32_bf16 v[96:99], v[222:225], v[198:201], v[96:99]
	v_mfma_f32_16x16x32_bf16 v[88:91], v[230:233], v[198:201], v[88:91]
	v_mfma_f32_16x16x32_bf16 v[80:83], v[222:225], v[206:209], v[80:83]
	v_mfma_f32_16x16x32_bf16 v[72:75], v[230:233], v[206:209], v[72:75]
	v_mfma_f32_16x16x32_bf16 v[68:71], v[222:225], v[214:217], v[68:71]
	v_mfma_f32_16x16x32_bf16 v[64:67], v[230:233], v[214:217], v[64:67]
	s_nop 0
	s_mov_b32 m0, s82
	v_lshl_add_u64 v[146:147], v[234:235], 0, s[0:1]
	s_barrier
	ds_read_b128 v[160:163], v151 offset:49152
	ds_read_b128 v[164:167], v151 offset:50176
	ds_read_b128 v[194:197], v151 offset:51200
	ds_read_b128 v[198:201], v151 offset:52224
	ds_read_b128 v[202:205], v151 offset:53248
	ds_read_b128 v[206:209], v151 offset:54272
	ds_read_b128 v[210:213], v151 offset:55296
	ds_read_b128 v[214:217], v151 offset:56320
	global_load_lds_dwordx4 v[146:147], off
	v_lshl_add_u64 v[146:147], v[236:237], 0, s[0:1]
	s_mov_b32 m0, s83
	s_nop 0
	global_load_lds_dwordx4 v[146:147], off
	s_barrier
	s_waitcnt lgkmcnt(0)
	s_nop 0
	s_waitcnt lgkmcnt(0)
	v_mfma_f32_16x16x32_bf16 v[60:63], v[128:131], v[160:163], v[60:63]
	v_mfma_f32_16x16x32_bf16 v[56:59], v[152:155], v[160:163], v[56:59]
	v_mfma_f32_16x16x32_bf16 v[52:55], v[128:131], v[194:197], v[52:55]
	v_mfma_f32_16x16x32_bf16 v[44:47], v[152:155], v[194:197], v[44:47]
	v_mfma_f32_16x16x32_bf16 v[36:39], v[128:131], v[202:205], v[36:39]
	v_mfma_f32_16x16x32_bf16 v[28:31], v[152:155], v[202:205], v[28:31]
	v_mfma_f32_16x16x32_bf16 v[20:23], v[128:131], v[210:213], v[20:23]
	v_mfma_f32_16x16x32_bf16 v[12:15], v[152:155], v[210:213], v[12:15]
	v_mfma_f32_16x16x32_bf16 v[60:63], v[142:145], v[164:167], v[60:63]
	v_mfma_f32_16x16x32_bf16 v[56:59], v[156:159], v[164:167], v[56:59]
	v_mfma_f32_16x16x32_bf16 v[52:55], v[142:145], v[198:201], v[52:55]
	v_mfma_f32_16x16x32_bf16 v[44:47], v[156:159], v[198:201], v[44:47]
	v_mfma_f32_16x16x32_bf16 v[36:39], v[142:145], v[206:209], v[36:39]
	v_mfma_f32_16x16x32_bf16 v[28:31], v[156:159], v[206:209], v[28:31]
	v_mfma_f32_16x16x32_bf16 v[20:23], v[142:145], v[214:217], v[20:23]
	v_mfma_f32_16x16x32_bf16 v[12:15], v[156:159], v[214:217], v[12:15]
	s_nop 0
	s_barrier
	s_add_u32 s12, s28, 0x158080
	s_addc_u32 s13, s29, 0
	s_add_i32 s28, s68, s71
	v_lshl_add_u64 v[128:129], s[12:13], 0, v[168:169]
	s_mov_b32 m0, s28
	s_nop 0
	global_load_lds_dwordx4 v[128:129], off
	v_lshl_add_u64 v[128:129], s[12:13], 0, v[136:137]
	s_add_i32 m0, s28, 0x2000
	s_nop 0
	global_load_lds_dwordx4 v[128:129], off
	s_waitcnt vmcnt(6)
	s_barrier
	s_nop 0
	v_mfma_f32_16x16x32_bf16 v[48:51], v[218:221], v[160:163], v[48:51]
	v_mfma_f32_16x16x32_bf16 v[40:43], v[226:229], v[160:163], v[40:43]
	v_mfma_f32_16x16x32_bf16 v[32:35], v[218:221], v[194:197], v[32:35]
	v_mfma_f32_16x16x32_bf16 v[24:27], v[226:229], v[194:197], v[24:27]
	v_mfma_f32_16x16x32_bf16 v[16:19], v[218:221], v[202:205], v[16:19]
	v_mfma_f32_16x16x32_bf16 v[8:11], v[226:229], v[202:205], v[8:11]
	v_mfma_f32_16x16x32_bf16 v[4:7], v[218:221], v[210:213], v[4:7]
	v_mfma_f32_16x16x32_bf16 v[0:3], v[226:229], v[210:213], v[0:3]
	v_mfma_f32_16x16x32_bf16 v[48:51], v[222:225], v[164:167], v[48:51]
	v_mfma_f32_16x16x32_bf16 v[40:43], v[230:233], v[164:167], v[40:43]
	v_mfma_f32_16x16x32_bf16 v[32:35], v[222:225], v[198:201], v[32:35]
	v_mfma_f32_16x16x32_bf16 v[24:27], v[230:233], v[198:201], v[24:27]
	v_mfma_f32_16x16x32_bf16 v[16:19], v[222:225], v[206:209], v[16:19]
	v_mfma_f32_16x16x32_bf16 v[8:11], v[230:233], v[206:209], v[8:11]
	v_mfma_f32_16x16x32_bf16 v[4:7], v[222:225], v[214:217], v[4:7]
	v_mfma_f32_16x16x32_bf16 v[0:3], v[230:233], v[214:217], v[0:3]
	s_nop 0
	s_add_u32 s97, s97, 0x100
	s_addc_u32 vcc_lo, vcc_lo, 0
	s_cmp_ge_u32 vcc_hi, s93
	s_mov_b64 s[12:13], s[14:15]
	s_mov_b32 s28, vcc_hi
	s_barrier
	s_cbranch_scc0 .LBB0_1575
	v_lshl_add_u32 v144, s92, 8, v148
	v_lshl_or_b32 v142, s91, 8, v150
	s_mov_b64 s[12:13], -1
	s_cmp_gt_i32 s30, -1
	v_ashrrev_i32_e32 v143, 31, v142
	v_ashrrev_i32_e32 v145, 31, v144
	s_cbranch_scc1 .LBB0_1578
	v_readlane_b32 s12, v240, 62
	v_lshlrev_b64 v[128:129], 12, v[144:145]
	v_readlane_b32 s13, v240, 63
	v_or_b32_e32 v146, 16, v144
	v_lshlrev_b64 v[130:131], 1, v[142:143]
	v_lshl_add_u64 v[128:129], s[12:13], 0, v[128:129]
	v_ashrrev_i32_e32 v147, 31, v146
	v_lshl_add_u64 v[128:129], v[128:129], 0, v[130:131]
	v_cvt_pk_bf16_f32 v152, v124, v125
	v_cvt_pk_bf16_f32 v153, v126, v127
	v_cvt_pk_bf16_f32 v154, v120, v121
	v_cvt_pk_bf16_f32 v155, v122, v123
	v_lshlrev_b64 v[146:147], 12, v[146:147]
	global_store_dwordx4 v[128:129], v[152:155], off
	v_lshl_add_u64 v[146:147], s[12:13], 0, v[146:147]
	v_lshl_add_u64 v[146:147], v[146:147], 0, v[130:131]
	v_cvt_pk_bf16_f32 v152, v112, v113
	v_cvt_pk_bf16_f32 v153, v114, v115
	v_cvt_pk_bf16_f32 v154, v104, v105
	v_cvt_pk_bf16_f32 v155, v106, v107
	global_store_dwordx4 v[128:129], v[152:155], off offset:256
	s_nop 1
	v_cvt_pk_bf16_f32 v152, v116, v117
	v_cvt_pk_bf16_f32 v153, v118, v119
	v_cvt_pk_bf16_f32 v154, v108, v109
	v_cvt_pk_bf16_f32 v155, v110, v111
	global_store_dwordx4 v[146:147], v[152:155], off
	s_nop 1
	v_cvt_pk_bf16_f32 v152, v96, v97
	v_cvt_pk_bf16_f32 v153, v98, v99
	v_cvt_pk_bf16_f32 v154, v88, v89
	v_cvt_pk_bf16_f32 v155, v90, v91
	global_store_dwordx4 v[146:147], v[152:155], off offset:256
	v_or_b32_e32 v146, 32, v144
	v_ashrrev_i32_e32 v147, 31, v146
	v_lshlrev_b64 v[146:147], 12, v[146:147]
	v_lshl_add_u64 v[146:147], s[12:13], 0, v[146:147]
	v_lshl_add_u64 v[146:147], v[146:147], 0, v[130:131]
	v_cvt_pk_bf16_f32 v152, v100, v101
	v_cvt_pk_bf16_f32 v153, v102, v103
	v_cvt_pk_bf16_f32 v154, v92, v93
	v_cvt_pk_bf16_f32 v155, v94, v95
	global_store_dwordx4 v[146:147], v[152:155], off
	s_nop 1
	v_cvt_pk_bf16_f32 v152, v80, v81
	v_cvt_pk_bf16_f32 v153, v82, v83
	v_cvt_pk_bf16_f32 v154, v72, v73
	v_cvt_pk_bf16_f32 v155, v74, v75
	global_store_dwordx4 v[146:147], v[152:155], off offset:256
	v_or_b32_e32 v146, 48, v144
	v_ashrrev_i32_e32 v147, 31, v146
	v_lshlrev_b64 v[146:147], 12, v[146:147]
	v_lshl_add_u64 v[146:147], s[12:13], 0, v[146:147]
	v_lshl_add_u64 v[130:131], v[146:147], 0, v[130:131]
	v_cvt_pk_bf16_f32 v152, v84, v85
	v_cvt_pk_bf16_f32 v153, v86, v87
	v_cvt_pk_bf16_f32 v154, v76, v77
	v_cvt_pk_bf16_f32 v155, v78, v79
	s_mov_b64 s[12:13], 0x80000
	global_store_dwordx4 v[130:131], v[152:155], off
	s_nop 1
	v_cvt_pk_bf16_f32 v152, v68, v69
	v_cvt_pk_bf16_f32 v153, v70, v71
	v_cvt_pk_bf16_f32 v154, v64, v65
	v_cvt_pk_bf16_f32 v155, v66, v67
	global_store_dwordx4 v[130:131], v[152:155], off offset:256
	v_lshl_add_u64 v[130:131], v[128:129], 0, s[12:13]
	s_mov_b32 s12, 0x80000
	v_add_co_u32_e32 v146, vcc, s12, v128
	v_cvt_pk_bf16_f32 v152, v60, v61
	v_cvt_pk_bf16_f32 v153, v62, v63
	v_cvt_pk_bf16_f32 v154, v56, v57
	v_cvt_pk_bf16_f32 v155, v58, v59
	s_nop 1
	v_addc_co_u32_e32 v147, vcc, 0, v129, vcc
	s_mov_b64 s[12:13], 0x90000
	global_store_dwordx4 v[146:147], v[152:155], off
	s_nop 1
	v_cvt_pk_bf16_f32 v152, v48, v49
	v_cvt_pk_bf16_f32 v153, v50, v51
	v_cvt_pk_bf16_f32 v154, v40, v41
	v_cvt_pk_bf16_f32 v155, v42, v43
	global_store_dwordx4 v[130:131], v[152:155], off offset:256
	v_lshl_add_u64 v[130:131], v[128:129], 0, s[12:13]
	s_mov_b32 s12, 0x90000
	v_add_co_u32_e32 v146, vcc, s12, v128
	v_cvt_pk_bf16_f32 v152, v52, v53
	v_cvt_pk_bf16_f32 v153, v54, v55
	v_cvt_pk_bf16_f32 v154, v44, v45
	v_cvt_pk_bf16_f32 v155, v46, v47
	s_nop 1
	v_addc_co_u32_e32 v147, vcc, 0, v129, vcc
	s_mov_b64 s[12:13], 0xa0000
	global_store_dwordx4 v[146:147], v[152:155], off
	s_nop 1
	v_cvt_pk_bf16_f32 v152, v32, v33
	v_cvt_pk_bf16_f32 v153, v34, v35
	v_cvt_pk_bf16_f32 v154, v24, v25
	v_cvt_pk_bf16_f32 v155, v26, v27
	global_store_dwordx4 v[130:131], v[152:155], off offset:256
	v_lshl_add_u64 v[130:131], v[128:129], 0, s[12:13]
	s_mov_b32 s12, 0xa0000
	v_add_co_u32_e32 v146, vcc, s12, v128
	s_mov_b64 s[12:13], 0xb0000
	s_nop 0
	v_addc_co_u32_e32 v147, vcc, 0, v129, vcc
	v_cvt_pk_bf16_f32 v152, v36, v37
	v_cvt_pk_bf16_f32 v153, v38, v39
	v_cvt_pk_bf16_f32 v154, v28, v29
	v_cvt_pk_bf16_f32 v155, v30, v31
	global_store_dwordx4 v[146:147], v[152:155], off
	v_lshl_add_u64 v[146:147], v[128:129], 0, s[12:13]
	s_mov_b32 s12, 0xb0000
	v_add_co_u32_e32 v128, vcc, s12, v128
	v_cvt_pk_bf16_f32 v152, v16, v17
	v_cvt_pk_bf16_f32 v153, v18, v19
	v_cvt_pk_bf16_f32 v154, v8, v9
	v_cvt_pk_bf16_f32 v155, v10, v11
	s_nop 1
	v_addc_co_u32_e32 v129, vcc, 0, v129, vcc
	s_mov_b64 s[12:13], 0
	global_store_dwordx4 v[130:131], v[152:155], off offset:256
	s_nop 1
	v_cvt_pk_bf16_f32 v152, v20, v21
	v_cvt_pk_bf16_f32 v153, v22, v23
	v_cvt_pk_bf16_f32 v154, v12, v13
	v_cvt_pk_bf16_f32 v155, v14, v15
	global_store_dwordx4 v[128:129], v[152:155], off
	v_cvt_pk_bf16_f32 v128, v4, v5
	v_cvt_pk_bf16_f32 v129, v6, v7
	v_cvt_pk_bf16_f32 v130, v0, v1
	v_cvt_pk_bf16_f32 v131, v2, v3
